# remaining 38 bf16 RNE bit-trick packs elsewhere in the file -> v_cvt_pk_bf16_f32
# speedup vs baseline: 1.0023x; 1.0023x over previous
.LBB0_642:
	v_add_co_u32_e32 v88, vcc, s11, v72
	global_load_dwordx4 v[56:59], v[74:75], off offset:-3584
	global_load_dwordx4 v[60:63], v[74:75], off offset:-3600
	global_load_dwordx4 v[64:67], v[72:73], off
	v_addc_co_u32_e32 v89, vcc, 0, v73, vcc
	v_add_co_u32_e32 v86, vcc, s3, v72
	global_load_dwordx4 v[48:51], v[74:75], off offset:-3072
	global_load_dwordx4 v[52:55], v[74:75], off offset:-3088
	v_addc_co_u32_e32 v87, vcc, 0, v73, vcc
	v_add_co_u32_e32 v84, vcc, s16, v72
	global_load_dwordx4 v[40:43], v[74:75], off offset:-2560
	global_load_dwordx4 v[44:47], v[74:75], off offset:-2576
	v_addc_co_u32_e32 v85, vcc, 0, v73, vcc
	v_add_co_u32_e32 v82, vcc, s17, v72
	global_load_dwordx4 v[32:35], v[74:75], off offset:-2048
	global_load_dwordx4 v[36:39], v[74:75], off offset:-2064
	v_addc_co_u32_e32 v83, vcc, 0, v73, vcc
	global_load_dwordx4 v[24:27], v[74:75], off offset:-1536
	global_load_dwordx4 v[28:31], v[74:75], off offset:-1552
	global_load_dwordx4 v[16:19], v[74:75], off offset:-1024
	global_load_dwordx4 v[20:23], v[74:75], off offset:-1040
	global_load_dwordx4 v[8:11], v[74:75], off offset:-512
	global_load_dwordx4 v[12:15], v[74:75], off offset:-528
	v_add_co_u32_e32 v80, vcc, s18, v72
	global_load_dwordx4 v[0:3], v[74:75], off
	global_load_dwordx4 v[4:7], v[74:75], off offset:-16
	v_addc_co_u32_e32 v81, vcc, 0, v73, vcc
	v_add_co_u32_e32 v76, vcc, s19, v72
	s_nop 0
	v_addc_co_u32_e32 v77, vcc, 0, v73, vcc
	v_add_co_u32_e32 v78, vcc, s20, v72
	s_nop 0
	v_addc_co_u32_e32 v79, vcc, 0, v73, vcc
	global_load_dwordx4 v[98:101], v[88:89], off
	global_load_dwordx4 v[102:105], v[86:87], off
	global_load_dwordx4 v[106:109], v[84:85], off
	global_load_dwordx4 v[110:113], v[82:83], off
	global_load_dwordx4 v[114:117], v[80:81], off
	global_load_dwordx4 v[118:121], v[76:77], off
	global_load_dwordx4 v[122:125], v[78:79], off
	v_cvt_pk_bf16_f32 v126, v90, v92
	v_cvt_pk_bf16_f32 v127, v91, v93
	v_cvt_pk_bf16_f32 v128, v94, v96
	v_cvt_pk_bf16_f32 v129, v95, v97
	global_store_dwordx4 v[72:73], v[126:129], off
	s_add_i32 s10, s10, 8
	v_lshl_add_u64 v[74:75], v[74:75], 0, s[8:9]
	s_cmp_lt_u32 s10, 24
	v_lshl_add_u64 v[72:73], v[72:73], 0, s[6:7]
	s_waitcnt vmcnt(23)
	v_mov_b32_e32 v126, v60
	v_mov_b32_e32 v127, v62
	s_waitcnt vmcnt(22)
	v_lshlrev_b32_e32 v129, 16, v65
	v_lshlrev_b32_e32 v128, 16, v64
	v_mov_b32_e32 v62, v61
	v_and_b32_e32 v61, 0xffff0000, v65
	v_and_b32_e32 v60, 0xffff0000, v64
	v_mov_b32_e32 v64, v56
	v_mov_b32_e32 v65, v58
	v_lshlrev_b32_e32 v131, 16, v67
	v_lshlrev_b32_e32 v130, 16, v66
	v_mov_b32_e32 v58, v57
	v_and_b32_e32 v57, 0xffff0000, v67
	v_and_b32_e32 v56, 0xffff0000, v66
	s_waitcnt vmcnt(20)
	v_mov_b32_e32 v66, v52
	v_mov_b32_e32 v67, v54
	v_mov_b32_e32 v54, v53
	v_mov_b32_e32 v52, v48
	v_mov_b32_e32 v53, v50
	v_mov_b32_e32 v50, v49
	s_waitcnt vmcnt(18)
	v_mov_b32_e32 v48, v44
	v_mov_b32_e32 v49, v46
	v_mov_b32_e32 v46, v45
	v_mov_b32_e32 v44, v40
	v_mov_b32_e32 v45, v42
	v_mov_b32_e32 v42, v41
	s_waitcnt vmcnt(16)
	v_mov_b32_e32 v40, v36
	v_mov_b32_e32 v41, v38
	v_mov_b32_e32 v38, v37
	v_mov_b32_e32 v36, v32
	v_mov_b32_e32 v37, v34
	v_mov_b32_e32 v34, v33
	s_waitcnt vmcnt(14)
	v_mov_b32_e32 v132, v28
	v_mov_b32_e32 v133, v30
	v_mov_b32_e32 v30, v29
	v_mov_b32_e32 v28, v24
	v_mov_b32_e32 v29, v26
	v_mov_b32_e32 v26, v25
	s_waitcnt vmcnt(12)
	v_mov_b32_e32 v134, v20
	v_mov_b32_e32 v135, v22
	v_mov_b32_e32 v22, v21
	v_mov_b32_e32 v20, v16
	v_mov_b32_e32 v21, v18
	v_mov_b32_e32 v18, v17
	s_waitcnt vmcnt(10)
	v_mov_b32_e32 v136, v12
	v_mov_b32_e32 v137, v14
	v_mov_b32_e32 v14, v13
	v_mov_b32_e32 v12, v8
	v_mov_b32_e32 v13, v10
	v_mov_b32_e32 v10, v9
	v_pk_fma_f32 v[8:9], v[90:91], v[126:127], v[128:129]
	v_pk_fma_f32 v[16:17], v[92:93], v[62:63], v[60:61]
	v_pk_fma_f32 v[24:25], v[94:95], v[64:65], v[130:131]
	v_pk_fma_f32 v[32:33], v[96:97], v[58:59], v[56:57]
	s_waitcnt vmcnt(7)
	v_lshlrev_b32_e32 v57, 16, v99
	v_lshlrev_b32_e32 v56, 16, v98
	v_and_b32_e32 v59, 0xffff0000, v99
	v_and_b32_e32 v58, 0xffff0000, v98
	v_lshlrev_b32_e32 v61, 16, v101
	v_lshlrev_b32_e32 v60, 16, v100
	v_and_b32_e32 v63, 0xffff0000, v101
	v_and_b32_e32 v62, 0xffff0000, v100
	s_waitcnt vmcnt(6)
	v_lshlrev_b32_e32 v65, 16, v103
	v_lshlrev_b32_e32 v64, 16, v102
	v_and_b32_e32 v91, 0xffff0000, v103
	v_and_b32_e32 v90, 0xffff0000, v102
	v_lshlrev_b32_e32 v93, 16, v105
	v_lshlrev_b32_e32 v92, 16, v104
	v_and_b32_e32 v95, 0xffff0000, v105
	v_and_b32_e32 v94, 0xffff0000, v104
	v_bfe_u32 v144, v17, 16, 1
	v_bfe_u32 v145, v16, 16, 1
	v_bfe_u32 v146, v8, 16, 1
	v_bfe_u32 v147, v9, 16, 1
	v_bfe_u32 v148, v24, 16, 1
	v_bfe_u32 v149, v25, 16, 1
	v_pk_fma_f32 v[56:57], v[8:9], v[66:67], v[56:57]
	v_pk_fma_f32 v[54:55], v[16:17], v[54:55], v[58:59]
	v_pk_fma_f32 v[52:53], v[24:25], v[52:53], v[60:61]
	v_pk_fma_f32 v[50:51], v[32:33], v[50:51], v[62:63]
	s_waitcnt vmcnt(5)
	v_lshlrev_b32_e32 v97, 16, v107
	v_lshlrev_b32_e32 v96, 16, v106
	v_and_b32_e32 v99, 0xffff0000, v107
	v_and_b32_e32 v98, 0xffff0000, v106
	v_lshlrev_b32_e32 v101, 16, v109
	v_lshlrev_b32_e32 v100, 16, v108
	v_and_b32_e32 v103, 0xffff0000, v109
	v_and_b32_e32 v102, 0xffff0000, v108
	v_bfe_u32 v142, v33, 16, 1
	v_bfe_u32 v143, v32, 16, 1
	v_add3_u32 v58, v16, v145, s21
	v_add3_u32 v59, v17, v144, s21
	v_add3_u32 v60, v25, v149, s21
	v_add3_u32 v61, v24, v148, s21
	v_add3_u32 v62, v9, v147, s21
	v_add3_u32 v63, v8, v146, s21
	v_bfe_u32 v66, v51, 16, 1
	v_bfe_u32 v67, v50, 16, 1
	v_bfe_u32 v144, v56, 16, 1
	v_bfe_u32 v145, v57, 16, 1
	v_bfe_u32 v146, v52, 16, 1
	v_bfe_u32 v147, v53, 16, 1
	v_pk_fma_f32 v[8:9], v[56:57], v[48:49], v[64:65]
	v_pk_fma_f32 v[16:17], v[54:55], v[46:47], v[90:91]
	v_pk_fma_f32 v[24:25], v[52:53], v[44:45], v[92:93]
	v_pk_fma_f32 v[42:43], v[50:51], v[42:43], v[94:95]
	s_waitcnt vmcnt(4)
	v_lshlrev_b32_e32 v105, 16, v111
	v_lshlrev_b32_e32 v104, 16, v110
	v_and_b32_e32 v107, 0xffff0000, v111
	v_and_b32_e32 v106, 0xffff0000, v110
	v_lshlrev_b32_e32 v109, 16, v113
	v_lshlrev_b32_e32 v108, 16, v112
	v_and_b32_e32 v111, 0xffff0000, v113
	v_and_b32_e32 v110, 0xffff0000, v112
	v_add3_u32 v32, v32, v143, s21
	v_add3_u32 v33, v33, v142, s21
	v_bfe_u32 v142, v55, 16, 1
	v_bfe_u32 v143, v54, 16, 1
	v_lshrrev_b32_e32 v46, 16, v63
	v_lshrrev_b32_e32 v47, 16, v62
	v_lshrrev_b32_e32 v48, 16, v61
	v_lshrrev_b32_e32 v49, 16, v60
	v_add3_u32 v50, v50, v67, s21
	v_add3_u32 v51, v51, v66, s21
	v_add3_u32 v53, v53, v147, s21
	v_add3_u32 v52, v52, v146, s21
	v_add3_u32 v57, v57, v145, s21
	v_add3_u32 v56, v56, v144, s21
	v_bfe_u32 v60, v43, 16, 1
	v_bfe_u32 v61, v42, 16, 1
	v_bfe_u32 v64, v8, 16, 1
	v_bfe_u32 v65, v9, 16, 1
	v_bfe_u32 v66, v24, 16, 1
	v_bfe_u32 v67, v25, 16, 1
	v_pk_fma_f32 v[40:41], v[8:9], v[40:41], v[96:97]
	v_pk_fma_f32 v[38:39], v[16:17], v[38:39], v[98:99]
	v_pk_fma_f32 v[36:37], v[24:25], v[36:37], v[100:101]
	v_pk_fma_f32 v[44:45], v[42:43], v[34:35], v[102:103]
	s_waitcnt vmcnt(3)
	v_lshlrev_b32_e32 v113, 16, v115
	v_lshlrev_b32_e32 v112, 16, v114
	v_and_b32_e32 v115, 0xffff0000, v115
	v_and_b32_e32 v114, 0xffff0000, v114
	v_lshlrev_b32_e32 v127, 16, v117
	v_lshlrev_b32_e32 v126, 16, v116
	v_and_b32_e32 v117, 0xffff0000, v117
	v_and_b32_e32 v116, 0xffff0000, v116
	v_add3_u32 v54, v54, v143, s21
	v_add3_u32 v55, v55, v142, s21
	v_bfe_u32 v62, v17, 16, 1
	v_bfe_u32 v63, v16, 16, 1
	v_and_or_b32 v35, v33, s22, v49
	v_and_or_b32 v34, v32, s22, v48
	v_and_or_b32 v33, v59, s22, v47
	v_and_or_b32 v32, v58, s22, v46
	v_lshrrev_b32_e32 v46, 16, v56
	v_lshrrev_b32_e32 v47, 16, v57
	v_lshrrev_b32_e32 v48, 16, v52
	v_lshrrev_b32_e32 v49, 16, v53
	v_add3_u32 v52, v42, v61, s21
	v_add3_u32 v53, v43, v60, s21
	v_add3_u32 v56, v25, v67, s21
	v_add3_u32 v57, v24, v66, s21
	v_add3_u32 v58, v9, v65, s21
	v_add3_u32 v59, v8, v64, s21
	v_bfe_u32 v64, v40, 16, 1
	v_bfe_u32 v65, v41, 16, 1
	v_bfe_u32 v66, v36, 16, 1
	v_bfe_u32 v67, v37, 16, 1
	v_pk_fma_f32 v[8:9], v[40:41], v[132:133], v[104:105]
	v_pk_fma_f32 v[30:31], v[38:39], v[30:31], v[106:107]
	v_pk_fma_f32 v[28:29], v[36:37], v[28:29], v[108:109]
	v_pk_fma_f32 v[42:43], v[44:45], v[26:27], v[110:111]
	s_waitcnt vmcnt(2)
	v_lshlrev_b32_e32 v129, 16, v119
	v_lshlrev_b32_e32 v128, 16, v118
	v_and_b32_e32 v119, 0xffff0000, v119
	v_and_b32_e32 v118, 0xffff0000, v118
	v_lshlrev_b32_e32 v131, 16, v121
	v_lshlrev_b32_e32 v130, 16, v120
	v_and_b32_e32 v121, 0xffff0000, v121
	v_and_b32_e32 v120, 0xffff0000, v120
	v_add3_u32 v16, v16, v63, s21
	v_add3_u32 v17, v17, v62, s21
	v_bfe_u32 v60, v45, 16, 1
	v_bfe_u32 v61, v44, 16, 1
	v_bfe_u32 v62, v39, 16, 1
	v_bfe_u32 v63, v38, 16, 1
	global_store_dwordx4 v[88:89], v[32:35], off
	v_and_or_b32 v27, v51, s22, v49
	v_and_or_b32 v26, v50, s22, v48
	v_and_or_b32 v25, v55, s22, v47
	v_and_or_b32 v24, v54, s22, v46
	v_lshrrev_b32_e32 v46, 16, v59
	v_lshrrev_b32_e32 v47, 16, v58
	v_lshrrev_b32_e32 v48, 16, v57
	v_lshrrev_b32_e32 v49, 16, v56
	v_add3_u32 v37, v37, v67, s21
	v_add3_u32 v36, v36, v66, s21
	v_add3_u32 v41, v41, v65, s21
	v_add3_u32 v40, v40, v64, s21
	v_bfe_u32 v54, v31, 16, 1
	v_bfe_u32 v55, v30, 16, 1
	v_bfe_u32 v56, v8, 16, 1
	v_bfe_u32 v57, v9, 16, 1
	v_bfe_u32 v58, v28, 16, 1
	v_bfe_u32 v59, v29, 16, 1
	v_pk_fma_f32 v[32:33], v[8:9], v[134:135], v[112:113]
	v_pk_fma_f32 v[22:23], v[30:31], v[22:23], v[114:115]
	v_pk_fma_f32 v[20:21], v[28:29], v[20:21], v[126:127]
	v_pk_fma_f32 v[34:35], v[42:43], v[18:19], v[116:117]
	v_add3_u32 v38, v38, v63, s21
	v_add3_u32 v39, v39, v62, s21
	v_add3_u32 v44, v44, v61, s21
	v_add3_u32 v45, v45, v60, s21
	v_bfe_u32 v50, v43, 16, 1
	v_bfe_u32 v51, v42, 16, 1
	global_store_dwordx4 v[86:87], v[24:27], off
	v_and_or_b32 v19, v53, s22, v49
	v_and_or_b32 v18, v52, s22, v48
	v_and_or_b32 v17, v17, s22, v47
	v_and_or_b32 v16, v16, s22, v46
	v_lshrrev_b32_e32 v40, 16, v40
	v_lshrrev_b32_e32 v41, 16, v41
	v_lshrrev_b32_e32 v36, 16, v36
	v_lshrrev_b32_e32 v37, 16, v37
	v_add3_u32 v30, v30, v55, s21
	v_add3_u32 v31, v31, v54, s21
	v_add3_u32 v29, v29, v59, s21
	v_add3_u32 v28, v28, v58, s21
	v_add3_u32 v46, v9, v57, s21
	v_add3_u32 v47, v8, v56, s21
	v_bfe_u32 v52, v32, 16, 1
	v_bfe_u32 v53, v33, 16, 1
	v_bfe_u32 v54, v20, 16, 1
	v_bfe_u32 v55, v21, 16, 1
	v_pk_fma_f32 v[24:25], v[32:33], v[136:137], v[128:129]
	v_pk_fma_f32 v[14:15], v[22:23], v[14:15], v[118:119]
	v_pk_fma_f32 v[12:13], v[20:21], v[12:13], v[130:131]
	v_pk_fma_f32 v[26:27], v[34:35], v[10:11], v[120:121]
	v_add3_u32 v42, v42, v51, s21
	v_add3_u32 v43, v43, v50, s21
	v_bfe_u32 v48, v35, 16, 1
	v_bfe_u32 v49, v34, 16, 1
	v_bfe_u32 v50, v23, 16, 1
	v_bfe_u32 v51, v22, 16, 1
	v_and_or_b32 v11, v45, s22, v37
	v_and_or_b32 v10, v44, s22, v36
	v_and_or_b32 v9, v39, s22, v41
	v_and_or_b32 v8, v38, s22, v40
	v_lshrrev_b32_e32 v36, 16, v47
	v_lshrrev_b32_e32 v37, 16, v46
	v_lshrrev_b32_e32 v28, 16, v28
	v_lshrrev_b32_e32 v29, 16, v29
	v_add3_u32 v21, v21, v55, s21
	v_add3_u32 v20, v20, v54, s21
	v_add3_u32 v33, v33, v53, s21
	v_add3_u32 v32, v32, v52, s21
	v_bfe_u32 v39, v26, 16, 1
	v_bfe_u32 v41, v14, 16, 1
	v_bfe_u32 v44, v24, 16, 1
	v_bfe_u32 v45, v25, 16, 1
	v_bfe_u32 v46, v12, 16, 1
	v_bfe_u32 v47, v13, 16, 1
	s_waitcnt vmcnt(3)
	v_lshlrev_b32_e32 v138, 16, v122
	v_and_b32_e32 v139, 0xffff0000, v122
	v_lshlrev_b32_e32 v122, 16, v123
	v_and_b32_e32 v123, 0xffff0000, v123
	v_lshlrev_b32_e32 v140, 16, v124
	v_and_b32_e32 v141, 0xffff0000, v124
	v_lshlrev_b32_e32 v124, 16, v125
	v_and_b32_e32 v125, 0xffff0000, v125
	global_store_dwordx4 v[84:85], v[16:19], off
	v_add3_u32 v22, v22, v51, s21
	v_add3_u32 v23, v23, v50, s21
	v_add3_u32 v34, v34, v49, s21
	v_add3_u32 v35, v35, v48, s21
	v_bfe_u32 v38, v27, 16, 1
	v_bfe_u32 v40, v15, 16, 1
	v_mov_b32_e32 v16, v24
	v_mov_b32_e32 v17, v14
	v_mov_b32_e32 v18, v12
	v_mov_b32_e32 v19, v26
	global_store_dwordx4 v[82:83], v[8:11], off
	v_lshrrev_b32_e32 v20, 16, v20
	v_lshrrev_b32_e32 v21, 16, v21
	v_and_or_b32 v11, v43, s22, v29
	v_and_or_b32 v10, v42, s22, v28
	v_and_or_b32 v9, v31, s22, v37
	v_and_or_b32 v8, v30, s22, v36
	v_lshrrev_b32_e32 v28, 16, v32
	v_lshrrev_b32_e32 v29, 16, v33
	v_add3_u32 v30, v14, v41, s21
	v_add3_u32 v32, v26, v39, s21
	v_add3_u32 v36, v13, v47, s21
	v_add3_u32 v12, v12, v46, s21
	v_add3_u32 v37, v25, v45, s21
	v_add3_u32 v24, v24, v44, s21
	v_mov_b32_e32 v14, v25
	v_mov_b32_e32 v26, v13
	v_add3_u32 v31, v15, v40, s21
	v_add3_u32 v33, v27, v38, s21
	v_pk_fma_f32 v[4:5], v[16:17], v[4:5], v[138:139]
	v_pk_fma_f32 v[0:1], v[18:19], v[0:1], v[140:141]
	global_store_dwordx4 v[80:81], v[8:11], off
	v_lshrrev_b32_e32 v13, 16, v24
	v_lshrrev_b32_e32 v16, 16, v37
	v_and_or_b32 v11, v35, s22, v21
	v_and_or_b32 v10, v34, s22, v20
	v_and_or_b32 v9, v23, s22, v29
	v_and_or_b32 v8, v22, s22, v28
	v_lshrrev_b32_e32 v12, 16, v12
	v_lshrrev_b32_e32 v17, 16, v36
	v_pk_fma_f32 v[6:7], v[14:15], v[6:7], v[122:123]
	v_pk_fma_f32 v[2:3], v[26:27], v[2:3], v[124:125]
	v_mov_b32_e32 v90, v4
	v_mov_b32_e32 v92, v5
	v_mov_b32_e32 v94, v0
	v_mov_b32_e32 v96, v1
	global_store_dwordx4 v[76:77], v[8:11], off
	v_mov_b32_e32 v91, v6
	v_mov_b32_e32 v93, v7
	v_and_or_b32 v11, v33, s22, v17
	v_and_or_b32 v10, v32, s22, v12
	v_and_or_b32 v9, v31, s22, v16
	v_and_or_b32 v8, v30, s22, v13
	v_mov_b32_e32 v95, v2
	v_mov_b32_e32 v97, v3
	global_store_dwordx4 v[78:79], v[8:11], off
	s_cbranch_scc1 .LBB0_642
	s_nop 0
	v_lshlrev_b32_e32 v8, 2, v70
	v_mov_b32_e32 v9, 0
	v_and_b32_e32 v14, 0x78, v71
	v_lshl_add_u64 v[10:11], s[12:13], 0, v[8:9]
	v_lshlrev_b64 v[12:13], 16, v[68:69]
	v_lshlrev_b32_e32 v8, 9, v14
	v_lshl_add_u64 v[10:11], v[10:11], 0, v[12:13]
	v_lshl_add_u64 v[8:9], v[10:11], 0, v[8:9]
	s_mov_b64 s[6:7], 0x4a00000
	v_lshl_add_u64 v[10:11], v[8:9], 0, s[6:7]
	v_add_co_u32_e32 v8, vcc, 0x4a00000, v8
	s_nop 1
	v_addc_co_u32_e32 v9, vcc, 0, v9, vcc
	global_store_dword v[8:9], v4, off
	global_store_dword v[10:11], v5, off offset:512
	global_store_dword v[10:11], v6, off offset:1024
	global_store_dword v[10:11], v7, off offset:1536
	global_store_dword v[10:11], v0, off offset:2048
	global_store_dword v[10:11], v1, off offset:2560
	global_store_dword v[10:11], v2, off offset:3072
	global_store_dword v[10:11], v3, off offset:3584

.LBB0_648:
	s_add_i32 s6, s55, 0x400
	s_cmpk_gt_i32 s6, 0xff
	s_mov_b64 s[4:5], -1
	s_cbranch_scc0 .LBB0_701
	s_cmpk_gt_u32 s6, 0x1ff
	s_cbranch_scc0 .LBB0_658
	s_cmpk_gt_u32 s6, 0x3ff
	s_cbranch_scc0 .LBB0_652
	v_mov_b32_e32 v79, v156
	s_lshr_b32 s7, s55, 6
	s_and_b32 s4, s43, 0x180
	s_lshl_b32 s48, s7, 8
	s_lshl_b32 s4, s4, 1
	v_lshlrev_b32_e32 v0, 3, v79
	s_add_u32 s8, s3, s4
	v_and_b32_e32 v40, 0x78, v0
	s_addc_u32 s9, s10, 0
	v_lshlrev_b32_e32 v64, 1, v40
	v_ashrrev_i32_e32 v48, 4, v79
	v_lshl_add_u64 v[56:57], s[8:9], 0, v[64:65]
	s_add_u32 s8, s11, s4
	v_ashrrev_i32_e32 v49, 31, v48
	s_addc_u32 s9, s27, 0
	v_lshl_add_u64 v[0:1], v[48:49], 0, s[48:49]
	v_lshl_add_u64 v[58:59], s[8:9], 0, v[64:65]
	v_lshlrev_b64 v[0:1], 10, v[0:1]
	v_lshl_add_u64 v[2:3], v[56:57], 0, v[0:1]
	v_lshl_add_u64 v[4:5], v[58:59], 0, v[0:1]
	global_load_dwordx4 v[0:3], v[2:3], off
	s_nop 0
	global_load_dwordx4 v[4:7], v[4:5], off
	v_add_u32_e32 v8, 0x200, v79
	v_add_u32_e32 v16, 0x400, v79
	s_waitcnt vmcnt(9)
	v_add_u32_e32 v24, 0x600, v79
	v_add_u32_e32 v32, 0x800, v79
	v_add_u32_e32 v42, 0xa00, v79
	v_add_u32_e32 v43, 0xc00, v79
	v_ashrrev_i32_e32 v60, 4, v8
	v_ashrrev_i32_e32 v62, 4, v16
	v_ashrrev_i32_e32 v68, 4, v24
	v_ashrrev_i32_e32 v80, 4, v32
	v_ashrrev_i32_e32 v82, 4, v42
	v_ashrrev_i32_e32 v84, 4, v43
	v_ashrrev_i32_e32 v61, 31, v60
	v_ashrrev_i32_e32 v63, 31, v62
	v_ashrrev_i32_e32 v69, 31, v68
	v_mov_b32_e32 v41, s68
	v_ashrrev_i32_e32 v81, 31, v80
	v_ashrrev_i32_e32 v83, 31, v82
	v_ashrrev_i32_e32 v85, 31, v84
	v_lshl_add_u64 v[8:9], v[60:61], 0, s[48:49]
	v_lshl_add_u64 v[16:17], v[62:63], 0, s[48:49]
	s_waitcnt vmcnt(8)
	v_lshl_add_u64 v[24:25], v[68:69], 0, s[48:49]
	v_lshl_add_u64 v[32:33], v[80:81], 0, s[48:49]
	v_mad_u32_u24 v61, v40, s69, v41
	v_add_u32_e32 v61, v61, v40
	v_add_u32_e32 v64, 0, v64
	v_lshl_add_u64 v[40:41], v[82:83], 0, s[48:49]
	v_lshl_add_u64 v[50:51], v[84:85], 0, s[48:49]
	v_lshlrev_b64 v[12:13], 10, v[8:9]
	v_lshlrev_b64 v[20:21], 10, v[16:17]
	s_waitcnt vmcnt(4)
	v_lshlrev_b64 v[28:29], 10, v[24:25]
	v_lshlrev_b64 v[36:37], 10, v[32:33]
	v_lshlrev_b64 v[44:45], 10, v[40:41]
	v_lshl_add_u32 v63, v48, 1, v61
	v_mad_u64_u32 v[86:87], s[8:9], v48, s70, v[64:65]
	v_lshlrev_b64 v[48:49], 10, v[50:51]
	v_lshl_add_u64 v[8:9], v[56:57], 0, v[12:13]
	v_lshl_add_u64 v[12:13], v[58:59], 0, v[12:13]
	v_lshl_add_u64 v[16:17], v[56:57], 0, v[20:21]
	v_lshl_add_u64 v[20:21], v[58:59], 0, v[20:21]
	v_lshl_add_u64 v[24:25], v[56:57], 0, v[28:29]
	v_lshl_add_u64 v[28:29], v[58:59], 0, v[28:29]
	v_lshl_add_u64 v[32:33], v[56:57], 0, v[36:37]
	v_lshl_add_u64 v[36:37], v[58:59], 0, v[36:37]
	v_lshl_add_u64 v[40:41], v[56:57], 0, v[44:45]
	v_lshl_add_u64 v[44:45], v[58:59], 0, v[44:45]
	v_lshl_add_u64 v[50:51], v[56:57], 0, v[48:49]
	v_lshl_add_u64 v[52:53], v[58:59], 0, v[48:49]
	global_load_dwordx4 v[8:11], v[8:9], off
	s_lshl_b32 s7, s7, 11
	global_load_dwordx4 v[12:15], v[12:13], off
	v_and_b32_e32 v67, 15, v79
	global_load_dwordx4 v[16:19], v[16:17], off
	s_mov_b32 s5, s49
	global_load_dwordx4 v[20:23], v[20:21], off
	s_nop 0
	global_load_dwordx4 v[24:27], v[24:25], off
	s_nop 0
	global_load_dwordx4 v[28:31], v[28:29], off
	s_nop 0
	global_load_dwordx4 v[32:35], v[32:33], off
	s_nop 0
	global_load_dwordx4 v[36:39], v[36:37], off
	s_nop 0
	global_load_dwordx4 v[40:43], v[40:41], off
	s_nop 0
	global_load_dwordx4 v[44:47], v[44:45], off
	s_nop 0
	global_load_dwordx4 v[48:51], v[50:51], off
	s_nop 0
	global_load_dwordx4 v[52:55], v[52:53], off
	s_waitcnt vmcnt(13)
	ds_write_b128 v86, v[0:3]
	s_waitcnt vmcnt(12)
	ds_write_b16 v63, v4
	ds_write_b16_d16_hi v63, v4 offset:528
	ds_write_b16 v63, v5 offset:1056
	ds_write_b16_d16_hi v63, v5 offset:1584
	ds_write_b16 v63, v6 offset:2112
	v_add_u32_e32 v0, 0xe00, v79
	v_ashrrev_i32_e32 v4, 4, v0
	v_ashrrev_i32_e32 v5, 31, v4
	v_lshl_add_u64 v[0:1], v[4:5], 0, s[48:49]
	v_lshlrev_b64 v[86:87], 10, v[0:1]
	v_lshl_add_u64 v[0:1], v[56:57], 0, v[86:87]
	global_load_dwordx4 v[0:3], v[0:1], off
	v_lshl_add_u64 v[56:57], v[58:59], 0, v[86:87]
	global_load_dwordx4 v[56:59], v[56:57], off
	ds_write_b16_d16_hi v63, v6 offset:2640
	ds_write_b16 v63, v7 offset:3168
	ds_write_b16_d16_hi v63, v7 offset:3696
	v_mad_u64_u32 v[6:7], s[8:9], v60, s70, v[64:65]
	v_lshl_add_u32 v5, v60, 1, v61
	s_waitcnt vmcnt(13)
	ds_write_b128 v6, v[8:11]
	v_mad_u64_u32 v[6:7], s[8:9], v62, s70, v[64:65]
	s_waitcnt vmcnt(12)
	ds_write_b16 v5, v12
	ds_write_b16_d16_hi v5, v12 offset:528
	ds_write_b16 v5, v13 offset:1056
	ds_write_b16_d16_hi v5, v13 offset:1584
	ds_write_b16 v5, v14 offset:2112
	ds_write_b16_d16_hi v5, v14 offset:2640
	ds_write_b16 v5, v15 offset:3168
	ds_write_b16_d16_hi v5, v15 offset:3696
	s_waitcnt vmcnt(11)
	ds_write_b128 v6, v[16:19]
	v_lshl_add_u32 v5, v62, 1, v61
	v_mad_u64_u32 v[6:7], s[8:9], v68, s70, v[64:65]
	s_waitcnt vmcnt(10)
	ds_write_b16 v5, v20
	ds_write_b16_d16_hi v5, v20 offset:528
	ds_write_b16 v5, v21 offset:1056
	ds_write_b16_d16_hi v5, v21 offset:1584
	ds_write_b16 v5, v22 offset:2112
	ds_write_b16_d16_hi v5, v22 offset:2640
	ds_write_b16 v5, v23 offset:3168
	ds_write_b16_d16_hi v5, v23 offset:3696
	s_waitcnt vmcnt(9)
	ds_write_b128 v6, v[24:27]
	v_lshl_add_u32 v5, v68, 1, v61
	v_mad_u64_u32 v[6:7], s[8:9], v80, s70, v[64:65]
	s_waitcnt vmcnt(8)
	ds_write_b16 v5, v28
	ds_write_b16_d16_hi v5, v28 offset:528
	ds_write_b16 v5, v29 offset:1056
	ds_write_b16_d16_hi v5, v29 offset:1584
	ds_write_b16 v5, v30 offset:2112
	ds_write_b16_d16_hi v5, v30 offset:2640
	ds_write_b16 v5, v31 offset:3168
	ds_write_b16_d16_hi v5, v31 offset:3696
	s_waitcnt vmcnt(7)
	ds_write_b128 v6, v[32:35]
	v_lshl_add_u32 v5, v80, 1, v61
	v_mad_u64_u32 v[6:7], s[8:9], v82, s70, v[64:65]
	s_waitcnt vmcnt(6)
	ds_write_b16 v5, v36
	ds_write_b16_d16_hi v5, v36 offset:528
	ds_write_b16 v5, v37 offset:1056
	ds_write_b16_d16_hi v5, v37 offset:1584
	ds_write_b16 v5, v38 offset:2112
	ds_write_b16_d16_hi v5, v38 offset:2640
	ds_write_b16 v5, v39 offset:3168
	ds_write_b16_d16_hi v5, v39 offset:3696
	s_waitcnt vmcnt(5)
	ds_write_b128 v6, v[40:43]
	v_lshl_add_u32 v5, v82, 1, v61
	v_mad_u64_u32 v[6:7], s[8:9], v84, s70, v[64:65]
	s_waitcnt vmcnt(4)
	ds_write_b16 v5, v44
	ds_write_b16_d16_hi v5, v44 offset:528
	ds_write_b16 v5, v45 offset:1056
	ds_write_b16_d16_hi v5, v45 offset:1584
	ds_write_b16 v5, v46 offset:2112
	ds_write_b16_d16_hi v5, v46 offset:2640
	ds_write_b16 v5, v47 offset:3168
	ds_write_b16_d16_hi v5, v47 offset:3696
	s_waitcnt vmcnt(3)
	ds_write_b128 v6, v[48:51]
	v_lshl_add_u32 v5, v84, 1, v61
	v_mad_u64_u32 v[6:7], s[8:9], v4, s70, v[64:65]
	s_waitcnt vmcnt(2)
	ds_write_b16 v5, v52
	ds_write_b16_d16_hi v5, v52 offset:528
	ds_write_b16 v5, v53 offset:1056
	ds_write_b16_d16_hi v5, v53 offset:1584
	ds_write_b16 v5, v54 offset:2112
	ds_write_b16_d16_hi v5, v54 offset:2640
	ds_write_b16 v5, v55 offset:3168
	ds_write_b16_d16_hi v5, v55 offset:3696
	s_and_b32 s8, s33, 0x780
	s_or_b32 s48, s7, s8
	v_bfe_u32 v16, v79, 4, 2
	v_mov_b32_e32 v5, v65
	v_lshlrev_b32_e32 v64, 3, v16
	s_waitcnt vmcnt(1)
	ds_write_b128 v6, v[0:3]
	v_lshl_add_u32 v0, v4, 1, v61
	s_waitcnt vmcnt(0)
	ds_write_b16 v0, v56
	ds_write_b16_d16_hi v0, v56 offset:528
	ds_write_b16 v0, v57 offset:1056
	ds_write_b16_d16_hi v0, v57 offset:1584
	ds_write_b16 v0, v58 offset:2112
	ds_write_b16_d16_hi v0, v58 offset:2640
	ds_write_b16 v0, v59 offset:3168
	ds_write_b16_d16_hi v0, v59 offset:3696
	v_ashrrev_i32_e32 v0, 2, v79
	v_and_b32_e32 v0, -16, v0
	v_ashrrev_i32_e32 v1, 31, v0
	v_lshl_add_u64 v[0:1], v[0:1], 0, s[48:49]
	v_or_b32_e32 v0, v0, v67
	v_mov_b64_e32 v[2:3], s[30:31]
	v_mad_u64_u32 v[2:3], s[8:9], v0, s71, v[2:3]
	v_mad_i32_i24 v3, v1, s71, v3
	v_lshl_add_u64 v[0:1], v[2:3], 0, s[4:5]
	s_mov_b64 s[4:5], 0x2000
	v_lshl_add_u64 v[68:69], v[0:1], 0, s[4:5]
	v_lshlrev_b32_e32 v4, 4, v16
	v_lshl_add_u64 v[6:7], v[68:69], 0, v[4:5]
	s_waitcnt lgkmcnt(0)
	s_barrier
	global_load_dwordx4 v[0:3], v[6:7], off
	global_load_dwordx4 v[80:83], v[6:7], off offset:64
	global_load_dwordx4 v[84:87], v[6:7], off offset:128
	global_load_dwordx4 v[88:91], v[6:7], off offset:192
	v_mul_u32_u24_e32 v5, 0x110, v67
	v_add3_u32 v79, 0, v4, v5
	ds_read_b128 v[4:7], v79
	ds_read_b128 v[8:11], v79 offset:64
	ds_read_b128 v[12:15], v79 offset:128
	s_waitcnt vmcnt(3) lgkmcnt(2)
	v_mfma_f32_16x16x32_bf16 v[4:7], v[4:7], v[0:3], 0
	s_waitcnt vmcnt(2) lgkmcnt(1)
	v_mfma_f32_16x16x32_bf16 v[4:7], v[8:11], v[80:83], v[4:7]
	ds_read_b128 v[8:11], v79 offset:192
	s_waitcnt vmcnt(1) lgkmcnt(1)
	v_mfma_f32_16x16x32_bf16 v[4:7], v[12:15], v[84:87], v[4:7]
	s_waitcnt vmcnt(0) lgkmcnt(0)
	v_mfma_f32_16x16x32_bf16 v[60:63], v[8:11], v[88:91], v[4:7]
	s_nop 5
	ds_read_b128 v[4:7], v79 offset:4352
	ds_read_b128 v[8:11], v79 offset:4416
	ds_read_b128 v[12:15], v79 offset:4480
	s_waitcnt lgkmcnt(2)
	v_mfma_f32_16x16x32_bf16 v[4:7], v[4:7], v[0:3], 0
	s_waitcnt lgkmcnt(1)
	v_mfma_f32_16x16x32_bf16 v[4:7], v[8:11], v[80:83], v[4:7]
	ds_read_b128 v[8:11], v79 offset:4544
	s_waitcnt lgkmcnt(1)
	v_mfma_f32_16x16x32_bf16 v[4:7], v[12:15], v[84:87], v[4:7]
	s_waitcnt lgkmcnt(0)
	v_mfma_f32_16x16x32_bf16 v[56:59], v[8:11], v[88:91], v[4:7]
	s_nop 5
	ds_read_b128 v[4:7], v79 offset:8704
	ds_read_b128 v[8:11], v79 offset:8768
	ds_read_b128 v[12:15], v79 offset:8832
	s_waitcnt lgkmcnt(2)
	v_mfma_f32_16x16x32_bf16 v[4:7], v[4:7], v[0:3], 0
	s_waitcnt lgkmcnt(1)
	v_mfma_f32_16x16x32_bf16 v[4:7], v[8:11], v[80:83], v[4:7]
	ds_read_b128 v[8:11], v79 offset:8896
	s_waitcnt lgkmcnt(1)
	v_mfma_f32_16x16x32_bf16 v[4:7], v[12:15], v[84:87], v[4:7]
	s_waitcnt lgkmcnt(0)
	v_mfma_f32_16x16x32_bf16 v[52:55], v[8:11], v[88:91], v[4:7]
	s_nop 5
	ds_read_b128 v[4:7], v79 offset:13056
	ds_read_b128 v[8:11], v79 offset:13120
	ds_read_b128 v[12:15], v79 offset:13184
	s_waitcnt lgkmcnt(2)
	v_mfma_f32_16x16x32_bf16 v[4:7], v[4:7], v[0:3], 0
	s_waitcnt lgkmcnt(1)
	v_mfma_f32_16x16x32_bf16 v[4:7], v[8:11], v[80:83], v[4:7]
	ds_read_b128 v[8:11], v79 offset:13248
	s_waitcnt lgkmcnt(1)
	v_mfma_f32_16x16x32_bf16 v[4:7], v[12:15], v[84:87], v[4:7]
	s_waitcnt lgkmcnt(0)
	v_mfma_f32_16x16x32_bf16 v[48:51], v[8:11], v[88:91], v[4:7]
	s_nop 5
	ds_read_b128 v[4:7], v79 offset:17408
	ds_read_b128 v[8:11], v79 offset:17472
	ds_read_b128 v[12:15], v79 offset:17536
	s_waitcnt lgkmcnt(2)
	v_mfma_f32_16x16x32_bf16 v[4:7], v[4:7], v[0:3], 0
	s_waitcnt lgkmcnt(1)
	v_mfma_f32_16x16x32_bf16 v[4:7], v[8:11], v[80:83], v[4:7]
	ds_read_b128 v[8:11], v79 offset:17600
	s_waitcnt lgkmcnt(1)
	v_mfma_f32_16x16x32_bf16 v[4:7], v[12:15], v[84:87], v[4:7]
	s_waitcnt lgkmcnt(0)
	v_mfma_f32_16x16x32_bf16 v[44:47], v[8:11], v[88:91], v[4:7]
	s_nop 5
	ds_read_b128 v[4:7], v79 offset:21760
	ds_read_b128 v[8:11], v79 offset:21824
	ds_read_b128 v[12:15], v79 offset:21888
	s_waitcnt lgkmcnt(2)
	v_mfma_f32_16x16x32_bf16 v[4:7], v[4:7], v[0:3], 0
	s_waitcnt lgkmcnt(1)
	v_mfma_f32_16x16x32_bf16 v[4:7], v[8:11], v[80:83], v[4:7]
	ds_read_b128 v[8:11], v79 offset:21952
	s_waitcnt lgkmcnt(1)
	v_mfma_f32_16x16x32_bf16 v[4:7], v[12:15], v[84:87], v[4:7]
	s_waitcnt lgkmcnt(0)
	v_mfma_f32_16x16x32_bf16 v[40:43], v[8:11], v[88:91], v[4:7]
	s_nop 5
	ds_read_b128 v[4:7], v79 offset:26112
	ds_read_b128 v[8:11], v79 offset:26176
	ds_read_b128 v[12:15], v79 offset:26240
	s_waitcnt lgkmcnt(2)
	v_mfma_f32_16x16x32_bf16 v[4:7], v[4:7], v[0:3], 0
	s_waitcnt lgkmcnt(1)
	v_mfma_f32_16x16x32_bf16 v[4:7], v[8:11], v[80:83], v[4:7]
	ds_read_b128 v[8:11], v79 offset:26304
	s_waitcnt lgkmcnt(1)
	v_mfma_f32_16x16x32_bf16 v[4:7], v[12:15], v[84:87], v[4:7]
	s_waitcnt lgkmcnt(0)
	v_mfma_f32_16x16x32_bf16 v[36:39], v[8:11], v[88:91], v[4:7]
	s_nop 5
	ds_read_b128 v[4:7], v79 offset:30464
	ds_read_b128 v[8:11], v79 offset:30528
	ds_read_b128 v[12:15], v79 offset:30592
	s_waitcnt lgkmcnt(2)
	v_mfma_f32_16x16x32_bf16 v[4:7], v[4:7], v[0:3], 0
	s_waitcnt lgkmcnt(1)
	v_mfma_f32_16x16x32_bf16 v[4:7], v[8:11], v[80:83], v[4:7]
	ds_read_b128 v[8:11], v79 offset:30656
	s_waitcnt lgkmcnt(1)
	v_mfma_f32_16x16x32_bf16 v[4:7], v[12:15], v[84:87], v[4:7]
	s_waitcnt lgkmcnt(0)
	v_mfma_f32_16x16x32_bf16 v[32:35], v[8:11], v[88:91], v[4:7]
	s_nop 5
	ds_read_b128 v[4:7], v79 offset:34816
	ds_read_b128 v[8:11], v79 offset:34880
	ds_read_b128 v[12:15], v79 offset:34944
	s_waitcnt lgkmcnt(2)
	v_mfma_f32_16x16x32_bf16 v[4:7], v[4:7], v[0:3], 0
	s_waitcnt lgkmcnt(1)
	v_mfma_f32_16x16x32_bf16 v[4:7], v[8:11], v[80:83], v[4:7]
	ds_read_b128 v[8:11], v79 offset:35008
	s_waitcnt lgkmcnt(1)
	v_mfma_f32_16x16x32_bf16 v[4:7], v[12:15], v[84:87], v[4:7]
	s_waitcnt lgkmcnt(0)
	v_mfma_f32_16x16x32_bf16 v[28:31], v[8:11], v[88:91], v[4:7]
	s_nop 5
	ds_read_b128 v[4:7], v79 offset:39168
	ds_read_b128 v[8:11], v79 offset:39232
	ds_read_b128 v[12:15], v79 offset:39296
	s_waitcnt lgkmcnt(2)
	v_mfma_f32_16x16x32_bf16 v[4:7], v[4:7], v[0:3], 0
	s_waitcnt lgkmcnt(1)
	v_mfma_f32_16x16x32_bf16 v[4:7], v[8:11], v[80:83], v[4:7]
	ds_read_b128 v[8:11], v79 offset:39360
	s_waitcnt lgkmcnt(1)
	v_mfma_f32_16x16x32_bf16 v[4:7], v[12:15], v[84:87], v[4:7]
	s_waitcnt lgkmcnt(0)
	v_mfma_f32_16x16x32_bf16 v[24:27], v[8:11], v[88:91], v[4:7]
	s_nop 5
	ds_read_b128 v[4:7], v79 offset:43520
	ds_read_b128 v[8:11], v79 offset:43584
	ds_read_b128 v[12:15], v79 offset:43648
	s_waitcnt lgkmcnt(2)
	v_mfma_f32_16x16x32_bf16 v[4:7], v[4:7], v[0:3], 0
	s_waitcnt lgkmcnt(1)
	v_mfma_f32_16x16x32_bf16 v[4:7], v[8:11], v[80:83], v[4:7]
	ds_read_b128 v[8:11], v79 offset:43712
	s_waitcnt lgkmcnt(1)
	v_mfma_f32_16x16x32_bf16 v[4:7], v[12:15], v[84:87], v[4:7]
	s_waitcnt lgkmcnt(0)
	v_mfma_f32_16x16x32_bf16 v[20:23], v[8:11], v[88:91], v[4:7]
	s_nop 5
	ds_read_b128 v[4:7], v79 offset:47872
	ds_read_b128 v[8:11], v79 offset:47936
	ds_read_b128 v[12:15], v79 offset:48000
	s_waitcnt lgkmcnt(2)
	v_mfma_f32_16x16x32_bf16 v[4:7], v[4:7], v[0:3], 0
	s_waitcnt lgkmcnt(1)
	v_mfma_f32_16x16x32_bf16 v[4:7], v[8:11], v[80:83], v[4:7]
	ds_read_b128 v[8:11], v79 offset:48064
	s_waitcnt lgkmcnt(1)
	v_mfma_f32_16x16x32_bf16 v[4:7], v[12:15], v[84:87], v[4:7]
	s_waitcnt lgkmcnt(0)
	v_mfma_f32_16x16x32_bf16 v[16:19], v[8:11], v[88:91], v[4:7]
	s_nop 5
	ds_read_b128 v[4:7], v79 offset:52224
	ds_read_b128 v[8:11], v79 offset:52288
	ds_read_b128 v[12:15], v79 offset:52352
	s_waitcnt lgkmcnt(2)
	v_mfma_f32_16x16x32_bf16 v[4:7], v[4:7], v[0:3], 0
	s_waitcnt lgkmcnt(1)
	v_mfma_f32_16x16x32_bf16 v[4:7], v[8:11], v[80:83], v[4:7]
	ds_read_b128 v[8:11], v79 offset:52416
	s_waitcnt lgkmcnt(1)
	v_mfma_f32_16x16x32_bf16 v[4:7], v[12:15], v[84:87], v[4:7]
	s_waitcnt lgkmcnt(0)
	v_mfma_f32_16x16x32_bf16 v[12:15], v[8:11], v[88:91], v[4:7]
	s_nop 5
	ds_read_b128 v[4:7], v79 offset:56576
	ds_read_b128 v[8:11], v79 offset:56640
	ds_read_b128 v[92:95], v79 offset:56704
	s_waitcnt lgkmcnt(2)
	v_mfma_f32_16x16x32_bf16 v[4:7], v[4:7], v[0:3], 0
	s_waitcnt lgkmcnt(1)
	v_mfma_f32_16x16x32_bf16 v[4:7], v[8:11], v[80:83], v[4:7]
	ds_read_b128 v[8:11], v79 offset:56768
	s_waitcnt lgkmcnt(1)
	v_mfma_f32_16x16x32_bf16 v[4:7], v[92:95], v[84:87], v[4:7]
	s_waitcnt lgkmcnt(0)
	v_mfma_f32_16x16x32_bf16 v[8:11], v[8:11], v[88:91], v[4:7]
	s_nop 5
	ds_read_b128 v[4:7], v79 offset:60928
	ds_read_b128 v[92:95], v79 offset:60992
	ds_read_b128 v[96:99], v79 offset:61056
	s_waitcnt lgkmcnt(2)
	v_mfma_f32_16x16x32_bf16 v[4:7], v[4:7], v[0:3], 0
	s_waitcnt lgkmcnt(1)
	v_mfma_f32_16x16x32_bf16 v[4:7], v[92:95], v[80:83], v[4:7]
	ds_read_b128 v[92:95], v79 offset:61120
	s_waitcnt lgkmcnt(1)
	v_mfma_f32_16x16x32_bf16 v[4:7], v[96:99], v[84:87], v[4:7]
	s_waitcnt lgkmcnt(0)
	v_mfma_f32_16x16x32_bf16 v[4:7], v[92:95], v[88:91], v[4:7]
	ds_read_b128 v[92:95], v79 offset:65280
	ds_read_b128 v[96:99], v79 offset:65344
	s_waitcnt lgkmcnt(1)
	v_mfma_f32_16x16x32_bf16 v[0:3], v[92:95], v[0:3], 0
	ds_read_b128 v[92:95], v79 offset:65408
	s_waitcnt lgkmcnt(1)
	v_mfma_f32_16x16x32_bf16 v[0:3], v[96:99], v[80:83], v[0:3]
	ds_read_b128 v[80:83], v79 offset:65472
	s_waitcnt lgkmcnt(1)
	v_mfma_f32_16x16x32_bf16 v[0:3], v[92:95], v[84:87], v[0:3]
	s_waitcnt lgkmcnt(0)
	v_mfma_f32_16x16x32_bf16 v[0:3], v[80:83], v[88:91], v[0:3]
	v_max_f32_e32 v79, v63, v63
	v_max_f32_e32 v80, v62, v62
	v_max_f32_e32 v79, v80, v79
	v_max_f32_e32 v80, v59, v59
	v_max_f32_e32 v81, v58, v58
	v_max_f32_e32 v80, v81, v80
	v_max3_f32 v79, v60, v61, v79
	v_max3_f32 v80, v56, v57, v80
	s_mov_b32 s4, 0xf149f2ca
	v_max3_f32 v79, v79, s4, v80
	v_max_f32_e32 v80, v55, v55
	v_max_f32_e32 v81, v54, v54
	v_max_f32_e32 v80, v81, v80
	v_max_f32_e32 v81, v51, v51
	v_max_f32_e32 v82, v50, v50
	v_max_f32_e32 v81, v82, v81
	v_max3_f32 v80, v52, v53, v80
	v_max3_f32 v81, v48, v49, v81
	v_max3_f32 v79, v79, v80, v81
	v_max_f32_e32 v80, v47, v47
	v_max_f32_e32 v81, v46, v46
	v_max_f32_e32 v80, v81, v80
	v_max_f32_e32 v81, v43, v43
	v_max_f32_e32 v82, v42, v42
	v_max_f32_e32 v81, v82, v81
	v_max3_f32 v80, v44, v45, v80
	v_max3_f32 v81, v40, v41, v81
	v_max3_f32 v79, v79, v80, v81
	v_max_f32_e32 v80, v39, v39
	v_max_f32_e32 v81, v38, v38
	v_max_f32_e32 v80, v81, v80
	v_max_f32_e32 v81, v35, v35
	v_max_f32_e32 v82, v34, v34
	v_max_f32_e32 v81, v82, v81
	v_max3_f32 v80, v36, v37, v80
	v_max3_f32 v81, v32, v33, v81
	v_max3_f32 v79, v79, v80, v81
	v_max_f32_e32 v80, v31, v31
	v_max_f32_e32 v81, v30, v30
	v_max_f32_e32 v80, v81, v80
	v_max_f32_e32 v81, v27, v27
	v_max_f32_e32 v82, v26, v26
	v_max_f32_e32 v81, v82, v81
	v_max3_f32 v80, v28, v29, v80
	v_max3_f32 v81, v24, v25, v81
	v_max3_f32 v79, v79, v80, v81
	v_max_f32_e32 v80, v23, v23
	v_max_f32_e32 v81, v22, v22
	v_max_f32_e32 v80, v81, v80
	v_max_f32_e32 v81, v19, v19
	v_max_f32_e32 v82, v18, v18
	v_max_f32_e32 v81, v82, v81
	v_max3_f32 v80, v20, v21, v80
	v_max3_f32 v81, v16, v17, v81
	v_max3_f32 v79, v79, v80, v81
	v_max_f32_e32 v80, v15, v15
	v_max_f32_e32 v81, v14, v14
	v_max_f32_e32 v80, v81, v80
	v_max_f32_e32 v81, v11, v11
	v_max_f32_e32 v82, v10, v10
	v_max_f32_e32 v81, v82, v81
	v_max3_f32 v80, v12, v13, v80
	v_max3_f32 v81, v8, v9, v81
	v_max3_f32 v79, v79, v80, v81
	v_max_f32_e32 v80, v7, v7
	v_max_f32_e32 v81, v6, v6
	v_max_f32_e32 v80, v81, v80
	v_max_f32_e32 v81, v3, v3
	v_max_f32_e32 v82, v2, v2
	v_max_f32_e32 v81, v82, v81
	v_max3_f32 v80, v4, v5, v80
	v_max3_f32 v81, v0, v1, v81
	v_cmp_lt_i32_e32 vcc, v72, v73
	v_max3_f32 v79, v79, v80, v81
	s_nop 0
	v_cndmask_b32_e32 v80, v71, v72, vcc
	v_lshlrev_b32_e32 v104, 2, v80
	ds_bpermute_b32 v80, v104, v79
	v_cmp_lt_i32_e32 vcc, v74, v73
	s_waitcnt lgkmcnt(0)
	v_max_f32_e32 v80, v80, v80
	v_max_f32_e32 v79, v79, v80
	v_cndmask_b32_e32 v80, v71, v74, vcc
	v_lshlrev_b32_e32 v105, 2, v80
	ds_bpermute_b32 v80, v105, v79
	s_waitcnt lgkmcnt(0)
	v_max_f32_e32 v80, v80, v80
	v_max_f32_e32 v79, v79, v80
	v_sub_f32_e32 v60, v60, v79
	v_mul_f32_e32 v60, 0x3db504f3, v60
	v_sub_f32_e32 v61, v61, v79
	v_mul_f32_e32 v60, 0x3fb8aa3b, v60
	v_mul_f32_e32 v61, 0x3db504f3, v61
	v_sub_f32_e32 v62, v62, v79
	v_exp_f32_e32 v60, v60
	v_mul_f32_e32 v61, 0x3fb8aa3b, v61
	v_mul_f32_e32 v62, 0x3db504f3, v62
	v_sub_f32_e32 v63, v63, v79
	v_exp_f32_e32 v61, v61
	v_mul_f32_e32 v62, 0x3fb8aa3b, v62
	v_mul_f32_e32 v63, 0x3db504f3, v63
	v_sub_f32_e32 v56, v56, v79
	v_exp_f32_e32 v62, v62
	v_mul_f32_e32 v63, 0x3fb8aa3b, v63
	v_mul_f32_e32 v56, 0x3db504f3, v56
	v_sub_f32_e32 v57, v57, v79
	v_sub_f32_e32 v53, v53, v79
	v_exp_f32_e32 v63, v63
	v_mul_f32_e32 v56, 0x3fb8aa3b, v56
	v_mul_f32_e32 v57, 0x3db504f3, v57
	v_sub_f32_e32 v58, v58, v79
	v_mul_f32_e32 v53, 0x3db504f3, v53
	v_add_f32_e32 v80, 0, v60
	v_exp_f32_e32 v56, v56
	v_mul_f32_e32 v57, 0x3fb8aa3b, v57
	v_mul_f32_e32 v58, 0x3db504f3, v58
	v_sub_f32_e32 v59, v59, v79
	v_mul_f32_e32 v53, 0x3fb8aa3b, v53
	v_add_f32_e32 v80, v61, v80
	v_exp_f32_e32 v57, v57
	v_mul_f32_e32 v58, 0x3fb8aa3b, v58
	v_mul_f32_e32 v59, 0x3db504f3, v59
	v_sub_f32_e32 v52, v52, v79
	v_exp_f32_e32 v107, v53
	v_sub_f32_e32 v53, v54, v79
	v_add_f32_e32 v80, v62, v80
	v_exp_f32_e32 v58, v58
	v_mul_f32_e32 v59, 0x3fb8aa3b, v59
	v_mul_f32_e32 v52, 0x3db504f3, v52
	v_mul_f32_e32 v53, 0x3db504f3, v53
	v_sub_f32_e32 v49, v49, v79
	v_add_f32_e32 v80, v63, v80
	v_exp_f32_e32 v59, v59
	v_mul_f32_e32 v52, 0x3fb8aa3b, v52
	v_mul_f32_e32 v53, 0x3fb8aa3b, v53
	v_mul_f32_e32 v49, 0x3db504f3, v49
	v_add_f32_e32 v80, v56, v80
	v_exp_f32_e32 v106, v52
	v_exp_f32_e32 v108, v53
	v_sub_f32_e32 v53, v55, v79
	v_mul_f32_e32 v49, 0x3fb8aa3b, v49
	v_add_f32_e32 v52, v57, v80
	v_mul_f32_e32 v53, 0x3db504f3, v53
	v_sub_f32_e32 v48, v48, v79
	v_exp_f32_e32 v111, v49
	v_sub_f32_e32 v49, v50, v79
	v_add_f32_e32 v52, v58, v52
	v_mul_f32_e32 v53, 0x3fb8aa3b, v53
	v_mul_f32_e32 v48, 0x3db504f3, v48
	v_mul_f32_e32 v49, 0x3db504f3, v49
	v_sub_f32_e32 v45, v45, v79
	v_add_f32_e32 v52, v59, v52
	v_exp_f32_e32 v109, v53
	v_mul_f32_e32 v48, 0x3fb8aa3b, v48
	v_mul_f32_e32 v49, 0x3fb8aa3b, v49
	v_mul_f32_e32 v45, 0x3db504f3, v45
	v_add_f32_e32 v52, v106, v52
	v_exp_f32_e32 v110, v48
	v_exp_f32_e32 v112, v49
	v_sub_f32_e32 v49, v51, v79
	v_mul_f32_e32 v45, 0x3fb8aa3b, v45
	v_add_f32_e32 v48, v107, v52
	v_mul_f32_e32 v49, 0x3db504f3, v49
	v_sub_f32_e32 v44, v44, v79
	v_exp_f32_e32 v51, v45
	v_sub_f32_e32 v45, v46, v79
	v_add_f32_e32 v48, v108, v48
	v_mul_f32_e32 v49, 0x3fb8aa3b, v49
	v_mul_f32_e32 v44, 0x3db504f3, v44
	v_mul_f32_e32 v45, 0x3db504f3, v45
	v_sub_f32_e32 v41, v41, v79
	v_add_f32_e32 v48, v109, v48
	v_exp_f32_e32 v113, v49
	v_mul_f32_e32 v44, 0x3fb8aa3b, v44
	v_mul_f32_e32 v45, 0x3fb8aa3b, v45
	v_mul_f32_e32 v41, 0x3db504f3, v41
	v_add_f32_e32 v48, v110, v48
	v_exp_f32_e32 v49, v44
	v_exp_f32_e32 v50, v45
	v_sub_f32_e32 v45, v47, v79
	v_mul_f32_e32 v41, 0x3fb8aa3b, v41
	v_add_f32_e32 v44, v111, v48
	v_mul_f32_e32 v45, 0x3db504f3, v45
	v_sub_f32_e32 v40, v40, v79
	v_exp_f32_e32 v116, v41
	v_sub_f32_e32 v41, v42, v79
	v_add_f32_e32 v44, v112, v44
	v_mul_f32_e32 v45, 0x3fb8aa3b, v45
	v_mul_f32_e32 v40, 0x3db504f3, v40
	v_mul_f32_e32 v41, 0x3db504f3, v41
	v_sub_f32_e32 v37, v37, v79
	v_add_f32_e32 v44, v113, v44
	v_exp_f32_e32 v114, v45
	v_mul_f32_e32 v40, 0x3fb8aa3b, v40
	v_mul_f32_e32 v41, 0x3fb8aa3b, v41
	v_mul_f32_e32 v37, 0x3db504f3, v37
	v_add_f32_e32 v44, v49, v44
	v_exp_f32_e32 v115, v40
	v_exp_f32_e32 v117, v41
	v_sub_f32_e32 v41, v43, v79
	v_mul_f32_e32 v37, 0x3fb8aa3b, v37
	v_add_f32_e32 v40, v51, v44
	v_mul_f32_e32 v41, 0x3db504f3, v41
	v_sub_f32_e32 v36, v36, v79
	v_exp_f32_e32 v43, v37
	v_sub_f32_e32 v37, v38, v79
	v_add_f32_e32 v40, v50, v40
	v_mul_f32_e32 v41, 0x3fb8aa3b, v41
	v_mul_f32_e32 v36, 0x3db504f3, v36
	v_mul_f32_e32 v37, 0x3db504f3, v37
	v_sub_f32_e32 v33, v33, v79
	v_add_f32_e32 v40, v114, v40
	v_exp_f32_e32 v118, v41
	v_mul_f32_e32 v36, 0x3fb8aa3b, v36
	v_mul_f32_e32 v37, 0x3fb8aa3b, v37
	v_mul_f32_e32 v33, 0x3db504f3, v33
	v_add_f32_e32 v40, v115, v40
	v_exp_f32_e32 v41, v36
	v_exp_f32_e32 v42, v37
	v_sub_f32_e32 v37, v39, v79
	v_mul_f32_e32 v33, 0x3fb8aa3b, v33
	v_add_f32_e32 v36, v116, v40
	v_mul_f32_e32 v37, 0x3db504f3, v37
	v_sub_f32_e32 v32, v32, v79
	v_exp_f32_e32 v47, v33
	v_sub_f32_e32 v33, v34, v79
	v_add_f32_e32 v36, v117, v36
	v_mul_f32_e32 v37, 0x3fb8aa3b, v37
	v_mul_f32_e32 v32, 0x3db504f3, v32
	v_mul_f32_e32 v33, 0x3db504f3, v33
	v_sub_f32_e32 v29, v29, v79
	v_add_f32_e32 v36, v118, v36
	v_exp_f32_e32 v45, v37
	v_mul_f32_e32 v32, 0x3fb8aa3b, v32
	v_mul_f32_e32 v33, 0x3fb8aa3b, v33
	v_mul_f32_e32 v29, 0x3db504f3, v29
	v_add_f32_e32 v36, v41, v36
	v_exp_f32_e32 v44, v32
	v_exp_f32_e32 v46, v33
	v_sub_f32_e32 v33, v35, v79
	v_mul_f32_e32 v29, 0x3fb8aa3b, v29
	v_add_f32_e32 v32, v43, v36
	v_mul_f32_e32 v33, 0x3db504f3, v33
	v_sub_f32_e32 v28, v28, v79
	v_exp_f32_e32 v35, v29
	v_sub_f32_e32 v29, v30, v79
	v_add_f32_e32 v32, v42, v32
	v_mul_f32_e32 v33, 0x3fb8aa3b, v33
	v_mul_f32_e32 v28, 0x3db504f3, v28
	v_mul_f32_e32 v29, 0x3db504f3, v29
	v_add_f32_e32 v32, v45, v32
	v_exp_f32_e32 v48, v33
	v_mul_f32_e32 v28, 0x3fb8aa3b, v28
	v_mul_f32_e32 v29, 0x3fb8aa3b, v29
	v_add_f32_e32 v32, v44, v32
	v_exp_f32_e32 v33, v28
	v_exp_f32_e32 v34, v29
	v_sub_f32_e32 v29, v31, v79
	v_add_f32_e32 v28, v47, v32
	v_mul_f32_e32 v29, 0x3db504f3, v29
	v_sub_f32_e32 v24, v24, v79
	v_add_f32_e32 v28, v46, v28
	v_mul_f32_e32 v29, 0x3fb8aa3b, v29
	v_mul_f32_e32 v24, 0x3db504f3, v24
	v_add_f32_e32 v28, v48, v28
	v_exp_f32_e32 v37, v29
	v_mul_f32_e32 v24, 0x3fb8aa3b, v24
	v_add_f32_e32 v28, v33, v28
	v_exp_f32_e32 v36, v24
	v_add_f32_e32 v24, v35, v28
	v_add_f32_e32 v24, v34, v24
	v_add_f32_e32 v24, v37, v24
	v_add_f32_e32 v28, v36, v24
	v_sub_f32_e32 v24, v25, v79
	v_mul_f32_e32 v24, 0x3db504f3, v24
	v_mul_f32_e32 v24, 0x3fb8aa3b, v24
	v_exp_f32_e32 v39, v24
	v_sub_f32_e32 v24, v26, v79
	v_mul_f32_e32 v24, 0x3db504f3, v24
	v_sub_f32_e32 v21, v21, v79
	v_mul_f32_e32 v24, 0x3fb8aa3b, v24
	v_mul_f32_e32 v21, 0x3db504f3, v21
	v_exp_f32_e32 v38, v24
	v_sub_f32_e32 v24, v27, v79
	v_mul_f32_e32 v21, 0x3fb8aa3b, v21
	v_mul_f32_e32 v24, 0x3db504f3, v24
	v_sub_f32_e32 v20, v20, v79
	v_exp_f32_e32 v26, v21
	v_sub_f32_e32 v21, v22, v79
	v_mul_f32_e32 v24, 0x3fb8aa3b, v24
	v_mul_f32_e32 v20, 0x3db504f3, v20
	v_mul_f32_e32 v21, 0x3db504f3, v21
	v_sub_f32_e32 v17, v17, v79
	v_exp_f32_e32 v40, v24
	v_mul_f32_e32 v20, 0x3fb8aa3b, v20
	v_mul_f32_e32 v21, 0x3fb8aa3b, v21
	v_mul_f32_e32 v17, 0x3db504f3, v17
	v_exp_f32_e32 v24, v20
	v_exp_f32_e32 v25, v21
	v_sub_f32_e32 v21, v23, v79
	v_mul_f32_e32 v17, 0x3fb8aa3b, v17
	v_add_f32_e32 v20, v39, v28
	v_mul_f32_e32 v21, 0x3db504f3, v21
	v_sub_f32_e32 v16, v16, v79
	v_exp_f32_e32 v30, v17
	v_sub_f32_e32 v17, v18, v79
	v_add_f32_e32 v20, v38, v20
	v_mul_f32_e32 v21, 0x3fb8aa3b, v21
	v_mul_f32_e32 v16, 0x3db504f3, v16
	v_mul_f32_e32 v17, 0x3db504f3, v17
	v_add_f32_e32 v20, v40, v20
	v_exp_f32_e32 v28, v21
	v_mul_f32_e32 v16, 0x3fb8aa3b, v16
	v_mul_f32_e32 v17, 0x3fb8aa3b, v17
	v_add_f32_e32 v20, v24, v20
	v_exp_f32_e32 v27, v16
	v_exp_f32_e32 v29, v17
	v_sub_f32_e32 v17, v19, v79
	v_add_f32_e32 v16, v26, v20
	v_mul_f32_e32 v17, 0x3db504f3, v17
	v_sub_f32_e32 v12, v12, v79
	v_add_f32_e32 v16, v25, v16
	v_mul_f32_e32 v17, 0x3fb8aa3b, v17
	v_mul_f32_e32 v12, 0x3db504f3, v12
	v_add_f32_e32 v16, v28, v16
	v_exp_f32_e32 v32, v17
	v_mul_f32_e32 v12, 0x3fb8aa3b, v12
	v_add_f32_e32 v16, v27, v16
	v_exp_f32_e32 v12, v12
	v_add_f32_e32 v16, v30, v16
	v_sub_f32_e32 v13, v13, v79
	v_add_f32_e32 v16, v29, v16
	v_mul_f32_e32 v13, 0x3db504f3, v13
	v_add_f32_e32 v16, v32, v16
	v_mul_f32_e32 v13, 0x3fb8aa3b, v13
	v_sub_f32_e32 v9, v9, v79
	v_add_f32_e32 v17, v12, v16
	v_exp_f32_e32 v16, v13
	v_sub_f32_e32 v13, v14, v79
	v_mul_f32_e32 v9, 0x3db504f3, v9
	v_mul_f32_e32 v13, 0x3db504f3, v13
	v_sub_f32_e32 v14, v15, v79
	v_mul_f32_e32 v9, 0x3fb8aa3b, v9
	v_mul_f32_e32 v13, 0x3fb8aa3b, v13
	v_mul_f32_e32 v14, 0x3db504f3, v14
	v_sub_f32_e32 v8, v8, v79
	v_exp_f32_e32 v21, v9
	v_sub_f32_e32 v9, v10, v79
	v_exp_f32_e32 v13, v13
	v_mul_f32_e32 v14, 0x3fb8aa3b, v14
	v_mul_f32_e32 v8, 0x3db504f3, v8
	v_mul_f32_e32 v9, 0x3db504f3, v9
	v_exp_f32_e32 v19, v14
	v_mul_f32_e32 v8, 0x3fb8aa3b, v8
	v_mul_f32_e32 v9, 0x3fb8aa3b, v9
	v_exp_f32_e32 v18, v8
	v_exp_f32_e32 v20, v9
	v_sub_f32_e32 v9, v11, v79
	v_add_f32_e32 v8, v16, v17
	v_mul_f32_e32 v9, 0x3db504f3, v9
	v_sub_f32_e32 v4, v4, v79
	v_add_f32_e32 v8, v13, v8
	v_mul_f32_e32 v9, 0x3fb8aa3b, v9
	v_mul_f32_e32 v4, 0x3db504f3, v4
	v_add_f32_e32 v8, v19, v8
	v_exp_f32_e32 v23, v9
	v_mul_f32_e32 v4, 0x3fb8aa3b, v4
	v_add_f32_e32 v8, v18, v8
	v_exp_f32_e32 v4, v4
	v_add_f32_e32 v8, v21, v8
	v_sub_f32_e32 v5, v5, v79
	v_add_f32_e32 v8, v20, v8
	v_mul_f32_e32 v5, 0x3db504f3, v5
	v_add_f32_e32 v8, v23, v8
	v_mul_f32_e32 v5, 0x3fb8aa3b, v5
	v_add_f32_e32 v9, v4, v8
	v_exp_f32_e32 v8, v5
	v_sub_f32_e32 v5, v6, v79
	v_mul_f32_e32 v5, 0x3db504f3, v5
	v_sub_f32_e32 v6, v7, v79
	v_mul_f32_e32 v5, 0x3fb8aa3b, v5
	v_mul_f32_e32 v6, 0x3db504f3, v6
	v_sub_f32_e32 v0, v0, v79
	v_exp_f32_e32 v5, v5
	v_mul_f32_e32 v6, 0x3fb8aa3b, v6
	v_mul_f32_e32 v0, 0x3db504f3, v0
	v_exp_f32_e32 v6, v6
	v_mul_f32_e32 v0, 0x3fb8aa3b, v0
	v_exp_f32_e32 v0, v0
	v_add_f32_e32 v7, v8, v9
	v_add_f32_e32 v7, v5, v7
	v_add_f32_e32 v7, v6, v7
	v_bfe_u32 v9, v57, 16, 1
	v_bfe_u32 v52, v58, 16, 1
	v_add_f32_e32 v15, v0, v7
	v_sub_f32_e32 v1, v1, v79
	v_bfe_u32 v7, v59, 16, 1
	v_add3_u32 v17, v57, v9, s73
	v_bfe_u32 v9, v60, 16, 1
	v_add3_u32 v52, v58, v52, s73
	v_mul_f32_e32 v1, 0x3db504f3, v1
	v_sub_f32_e32 v2, v2, v79
	v_bfe_u32 v14, v61, 16, 1
	v_add3_u32 v7, v59, v7, s73
	v_bfe_u32 v31, v56, 16, 1
	v_add3_u32 v9, v60, v9, s73
	v_lshrrev_b32_e32 v57, 16, v52
	v_mul_f32_e32 v1, 0x3fb8aa3b, v1
	v_mul_f32_e32 v2, 0x3db504f3, v2
	v_add3_u32 v14, v61, v14, s73
	v_add3_u32 v31, v56, v31, s73
	v_lshrrev_b32_e32 v56, 16, v9
	v_and_or_b32 v59, v7, s74, v57
	v_cvt_pk_bf16_f32 v57, v62, v63
	v_sub_f32_e32 v11, v3, v79
	v_exp_f32_e32 v1, v1
	v_mul_f32_e32 v10, 0x3fb8aa3b, v2
	v_lshrrev_b32_e32 v31, 16, v31
	v_and_or_b32 v56, v14, s74, v56
	v_mul_f32_e32 v14, 0x3db504f3, v11
	v_mul_u32_u24_e32 v2, 0x210, v67
	v_and_or_b32 v58, v17, s74, v31
	v_exp_f32_e32 v22, v10
	v_mul_f32_e32 v17, 0x3fb8aa3b, v14
	v_add3_u32 v9, s68, v64, v2
	v_and_b32_e32 v2, 8, v67
	v_add_u32_e32 v9, v9, v2
	v_exp_f32_e32 v31, v17
	v_add_u32_e32 v2, 0x2010, v9
	v_add_u32_e32 v7, 0x4020, v9
	v_add_u32_e32 v10, 0x6030, v9
	v_add_u32_e32 v3, 0x8040, v9
	v_add_u32_e32 v11, 0xa050, v9
	v_add_u32_e32 v14, 0xc060, v9
	v_add_u32_e32 v67, 0xe070, v9
	ds_read2_b64 v[52:55], v9 offset1:4
	ds_read2_b64 v[60:63], v2 offset0:32 offset1:36
	ds_read2_b64 v[80:83], v7 offset0:64 offset1:68
	ds_read2_b64 v[84:87], v10 offset0:96 offset1:100
	ds_read2_b64 v[88:91], v3 offset0:128 offset1:132
	ds_read2_b64 v[92:95], v11 offset0:160 offset1:164
	ds_read2_b64 v[96:99], v14 offset0:192 offset1:196
	v_add_f32_e32 v15, v1, v15
	ds_read2_b64 v[100:103], v67 offset0:224 offset1:228
	v_add_f32_e32 v15, v22, v15
	v_add_f32_e32 v15, v31, v15
	ds_bpermute_b32 v17, v104, v15
	s_waitcnt lgkmcnt(8)
	v_mfma_f32_16x16x32_bf16 v[52:55], v[52:55], v[56:59], 0
	s_waitcnt lgkmcnt(0)
	v_add_f32_e32 v15, v15, v17
	v_mfma_f32_16x16x32_bf16 v[60:63], v[60:63], v[56:59], 0
	ds_bpermute_b32 v17, v105, v15
	v_mfma_f32_16x16x32_bf16 v[80:83], v[80:83], v[56:59], 0
	v_mfma_f32_16x16x32_bf16 v[84:87], v[84:87], v[56:59], 0
	v_mfma_f32_16x16x32_bf16 v[88:91], v[88:91], v[56:59], 0
	v_mfma_f32_16x16x32_bf16 v[92:95], v[92:95], v[56:59], 0
	v_mfma_f32_16x16x32_bf16 v[96:99], v[96:99], v[56:59], 0
	v_mfma_f32_16x16x32_bf16 v[56:59], v[100:103], v[56:59], 0
	v_bfe_u32 v100, v111, 16, 1
	v_bfe_u32 v101, v109, 16, 1
	v_bfe_u32 v102, v107, 16, 1
	v_add3_u32 v104, v107, v102, s73
	v_add3_u32 v105, v109, v101, s73
	v_add3_u32 v109, v111, v100, s73
	v_bfe_u32 v100, v106, 16, 1
	v_bfe_u32 v101, v108, 16, 1
	v_bfe_u32 v102, v110, 16, 1
	v_bfe_u32 v103, v112, 16, 1
	v_add3_u32 v107, v112, v103, s73
	v_add3_u32 v110, v110, v102, s73
	v_add3_u32 v108, v108, v101, s73
	v_add3_u32 v106, v106, v100, s73
	ds_read2_b64 v[100:103], v9 offset0:8 offset1:12
	v_bfe_u32 v79, v113, 16, 1
	v_add3_u32 v79, v113, v79, s73
	v_lshrrev_b32_e32 v111, 16, v106
	v_lshrrev_b32_e32 v108, 16, v108
	v_lshrrev_b32_e32 v106, 16, v110
	v_lshrrev_b32_e32 v107, 16, v107
	v_and_or_b32 v107, v79, s74, v107
	v_and_or_b32 v106, v109, s74, v106
	v_and_or_b32 v105, v105, s74, v108
	v_and_or_b32 v104, v104, s74, v111
	s_waitcnt lgkmcnt(0)
	s_nop 0
	v_mfma_f32_16x16x32_bf16 v[52:55], v[100:103], v[104:107], v[52:55]
	ds_read2_b64 v[100:103], v2 offset0:40 offset1:44
	s_waitcnt lgkmcnt(0)
	v_mfma_f32_16x16x32_bf16 v[60:63], v[100:103], v[104:107], v[60:63]
	ds_read2_b64 v[100:103], v7 offset0:72 offset1:76
	s_waitcnt lgkmcnt(0)
	v_mfma_f32_16x16x32_bf16 v[80:83], v[100:103], v[104:107], v[80:83]
	ds_read2_b64 v[100:103], v10 offset0:104 offset1:108
	s_waitcnt lgkmcnt(0)
	v_mfma_f32_16x16x32_bf16 v[84:87], v[100:103], v[104:107], v[84:87]
	ds_read2_b64 v[100:103], v3 offset0:136 offset1:140
	s_waitcnt lgkmcnt(0)
	v_mfma_f32_16x16x32_bf16 v[88:91], v[100:103], v[104:107], v[88:91]
	ds_read2_b64 v[100:103], v11 offset0:168 offset1:172
	s_waitcnt lgkmcnt(0)
	v_mfma_f32_16x16x32_bf16 v[92:95], v[100:103], v[104:107], v[92:95]
	ds_read2_b64 v[100:103], v14 offset0:200 offset1:204
	s_waitcnt lgkmcnt(0)
	v_mfma_f32_16x16x32_bf16 v[96:99], v[100:103], v[104:107], v[96:99]
	ds_read2_b64 v[100:103], v67 offset0:232 offset1:236
	s_waitcnt lgkmcnt(0)
	v_mfma_f32_16x16x32_bf16 v[56:59], v[100:103], v[104:107], v[56:59]
	v_bfe_u32 v100, v116, 16, 1
	v_bfe_u32 v101, v114, 16, 1
	v_bfe_u32 v102, v51, 16, 1
	v_add3_u32 v51, v51, v102, s73
	v_add3_u32 v104, v114, v101, s73
	v_add3_u32 v105, v116, v100, s73
	v_bfe_u32 v100, v49, 16, 1
	v_bfe_u32 v101, v50, 16, 1
	v_bfe_u32 v102, v115, 16, 1
	v_bfe_u32 v103, v117, 16, 1
	v_add3_u32 v106, v117, v103, s73
	v_add3_u32 v107, v115, v102, s73
	v_add3_u32 v50, v50, v101, s73
	v_add3_u32 v49, v49, v100, s73
	ds_read2_b64 v[100:103], v9 offset0:16 offset1:20
	v_bfe_u32 v79, v118, 16, 1
	v_add3_u32 v79, v118, v79, s73
	v_lshrrev_b32_e32 v49, 16, v49
	v_lshrrev_b32_e32 v50, 16, v50
	v_lshrrev_b32_e32 v108, 16, v107
	v_lshrrev_b32_e32 v106, 16, v106
	v_and_or_b32 v107, v79, s74, v106
	v_and_or_b32 v106, v105, s74, v108
	v_and_or_b32 v105, v104, s74, v50
	v_and_or_b32 v104, v51, s74, v49
	s_waitcnt lgkmcnt(0)
	s_nop 0
	v_mfma_f32_16x16x32_bf16 v[50:53], v[100:103], v[104:107], v[52:55]
	ds_read2_b64 v[100:103], v2 offset0:48 offset1:52
	s_waitcnt lgkmcnt(0)
	v_mfma_f32_16x16x32_bf16 v[60:63], v[100:103], v[104:107], v[60:63]
	ds_read2_b64 v[100:103], v7 offset0:80 offset1:84
	s_waitcnt lgkmcnt(0)
	v_mfma_f32_16x16x32_bf16 v[80:83], v[100:103], v[104:107], v[80:83]
	ds_read2_b64 v[100:103], v10 offset0:112 offset1:116
	s_waitcnt lgkmcnt(0)
	v_mfma_f32_16x16x32_bf16 v[84:87], v[100:103], v[104:107], v[84:87]
	ds_read2_b64 v[100:103], v3 offset0:144 offset1:148
	s_waitcnt lgkmcnt(0)
	v_mfma_f32_16x16x32_bf16 v[88:91], v[100:103], v[104:107], v[88:91]
	ds_read2_b64 v[100:103], v11 offset0:176 offset1:180
	s_waitcnt lgkmcnt(0)
	v_mfma_f32_16x16x32_bf16 v[92:95], v[100:103], v[104:107], v[92:95]
	ds_read2_b64 v[100:103], v14 offset0:208 offset1:212
	s_waitcnt lgkmcnt(0)
	v_mfma_f32_16x16x32_bf16 v[96:99], v[100:103], v[104:107], v[96:99]
	ds_read2_b64 v[100:103], v67 offset0:240 offset1:244
	s_waitcnt lgkmcnt(0)
	v_mfma_f32_16x16x32_bf16 v[54:57], v[100:103], v[104:107], v[56:59]
	v_bfe_u32 v49, v48, 16, 1
	s_nop 1
	v_bfe_u32 v58, v47, 16, 1
	v_bfe_u32 v59, v45, 16, 1
	v_bfe_u32 v79, v43, 16, 1
	v_add3_u32 v79, v43, v79, s73
	v_add3_u32 v59, v45, v59, s73
	v_add3_u32 v47, v47, v58, s73
	v_add3_u32 v48, v48, v49, s73
	v_bfe_u32 v43, v41, 16, 1
	v_bfe_u32 v45, v42, 16, 1
	v_bfe_u32 v49, v44, 16, 1
	v_bfe_u32 v58, v46, 16, 1
	v_add3_u32 v46, v46, v58, s73
	v_add3_u32 v49, v44, v49, s73
	v_add3_u32 v58, v42, v45, s73
	v_add3_u32 v41, v41, v43, s73
	ds_read2_b64 v[42:45], v9 offset0:24 offset1:28
	v_lshrrev_b32_e32 v41, 16, v41
	v_lshrrev_b32_e32 v58, 16, v58
	v_lshrrev_b32_e32 v100, 16, v49
	v_lshrrev_b32_e32 v46, 16, v46
	v_and_or_b32 v49, v48, s74, v46
	v_and_or_b32 v48, v47, s74, v100
	v_and_or_b32 v47, v59, s74, v58
	v_and_or_b32 v46, v79, s74, v41
	s_waitcnt lgkmcnt(0)
	s_nop 0
	v_mfma_f32_16x16x32_bf16 v[42:45], v[42:45], v[46:49], v[50:53]
	s_nop 2
	ds_read2_b64 v[50:53], v2 offset0:56 offset1:60
	s_waitcnt lgkmcnt(0)
	v_mfma_f32_16x16x32_bf16 v[50:53], v[50:53], v[46:49], v[60:63]
	s_nop 2
	ds_read2_b64 v[58:61], v7 offset0:88 offset1:92
	s_waitcnt lgkmcnt(0)
	v_mfma_f32_16x16x32_bf16 v[58:61], v[58:61], v[46:49], v[80:83]
	s_nop 2
	ds_read2_b64 v[80:83], v10 offset0:120 offset1:124
	s_waitcnt lgkmcnt(0)
	v_mfma_f32_16x16x32_bf16 v[80:83], v[80:83], v[46:49], v[84:87]
	s_nop 2
	ds_read2_b64 v[84:87], v3 offset0:152 offset1:156
	s_waitcnt lgkmcnt(0)
	v_mfma_f32_16x16x32_bf16 v[84:87], v[84:87], v[46:49], v[88:91]
	s_nop 2
	ds_read2_b64 v[88:91], v11 offset0:184 offset1:188
	s_waitcnt lgkmcnt(0)
	v_mfma_f32_16x16x32_bf16 v[88:91], v[88:91], v[46:49], v[92:95]
	s_nop 2
	ds_read2_b64 v[92:95], v14 offset0:216 offset1:220
	s_waitcnt lgkmcnt(0)
	v_mfma_f32_16x16x32_bf16 v[92:95], v[92:95], v[46:49], v[96:99]
	s_nop 2
	ds_read2_b64 v[96:99], v67 offset0:248 offset1:252
	s_waitcnt lgkmcnt(0)
	v_mfma_f32_16x16x32_bf16 v[46:49], v[96:99], v[46:49], v[54:57]
	v_bfe_u32 v41, v40, 16, 1
	s_nop 1
	v_bfe_u32 v54, v39, 16, 1
	v_bfe_u32 v55, v37, 16, 1
	v_bfe_u32 v56, v35, 16, 1
	v_add3_u32 v56, v35, v56, s73
	v_add3_u32 v55, v37, v55, s73
	v_add3_u32 v39, v39, v54, s73
	v_add3_u32 v40, v40, v41, s73
	v_bfe_u32 v35, v33, 16, 1
	v_bfe_u32 v37, v34, 16, 1
	v_bfe_u32 v41, v36, 16, 1
	v_bfe_u32 v54, v38, 16, 1
	v_add3_u32 v38, v38, v54, s73
	v_add3_u32 v41, v36, v41, s73
	v_add3_u32 v54, v34, v37, s73
	v_add3_u32 v33, v33, v35, s73
	ds_read2_b64 v[34:37], v9 offset0:32 offset1:36
	v_lshrrev_b32_e32 v33, 16, v33
	v_lshrrev_b32_e32 v54, 16, v54
	v_lshrrev_b32_e32 v57, 16, v41
	v_lshrrev_b32_e32 v38, 16, v38
	v_and_or_b32 v41, v40, s74, v38
	v_and_or_b32 v40, v39, s74, v57
	v_and_or_b32 v39, v55, s74, v54
	v_and_or_b32 v38, v56, s74, v33
	ds_read2_b64 v[54:57], v10 offset0:128 offset1:132
	v_add_u32_e32 v62, 0xe870, v9
	s_waitcnt lgkmcnt(1)
	v_mfma_f32_16x16x32_bf16 v[34:37], v[34:37], v[38:41], v[42:45]
	s_nop 2
	ds_read2_b64 v[42:45], v2 offset0:64 offset1:68
	s_waitcnt lgkmcnt(0)
	v_mfma_f32_16x16x32_bf16 v[42:45], v[42:45], v[38:41], v[50:53]
	s_nop 2
	ds_read2_b64 v[50:53], v7 offset0:96 offset1:100
	s_waitcnt lgkmcnt(0)
	v_mfma_f32_16x16x32_bf16 v[50:53], v[50:53], v[38:41], v[58:61]
	s_nop 2
	ds_read2_b64 v[58:61], v3 offset0:160 offset1:164
	v_mfma_f32_16x16x32_bf16 v[54:57], v[54:57], v[38:41], v[80:83]
	s_nop 2
	ds_read2_b64 v[80:83], v11 offset0:192 offset1:196
	s_waitcnt lgkmcnt(1)
	v_mfma_f32_16x16x32_bf16 v[58:61], v[58:61], v[38:41], v[84:87]
	s_nop 2
	ds_read2_b64 v[84:87], v14 offset0:224 offset1:228
	s_waitcnt lgkmcnt(1)
	v_mfma_f32_16x16x32_bf16 v[80:83], v[80:83], v[38:41], v[88:91]
	s_nop 2
	ds_read2_b64 v[88:91], v62 offset1:4
	s_waitcnt lgkmcnt(1)
	v_mfma_f32_16x16x32_bf16 v[84:87], v[84:87], v[38:41], v[92:95]
	s_waitcnt lgkmcnt(0)
	v_mfma_f32_16x16x32_bf16 v[38:41], v[88:91], v[38:41], v[46:49]
	v_bfe_u32 v33, v32, 16, 1
	s_nop 1
	v_bfe_u32 v46, v30, 16, 1
	v_bfe_u32 v47, v28, 16, 1
	v_bfe_u32 v48, v26, 16, 1
	v_add3_u32 v63, v26, v48, s73
	v_add3_u32 v28, v28, v47, s73
	v_add3_u32 v30, v30, v46, s73
	v_add3_u32 v32, v32, v33, s73
	v_bfe_u32 v26, v24, 16, 1
	v_bfe_u32 v33, v25, 16, 1
	v_bfe_u32 v46, v27, 16, 1
	v_bfe_u32 v47, v29, 16, 1
	v_add3_u32 v29, v29, v47, s73
	v_add3_u32 v46, v27, v46, s73
	v_add3_u32 v33, v25, v33, s73
	v_add3_u32 v47, v24, v26, s73
	ds_read2_b64 v[24:27], v9 offset0:40 offset1:44
	v_lshrrev_b32_e32 v67, 16, v47
	v_lshrrev_b32_e32 v33, 16, v33
	v_lshrrev_b32_e32 v46, 16, v46
	v_lshrrev_b32_e32 v29, 16, v29
	v_and_or_b32 v49, v32, s74, v29
	v_and_or_b32 v48, v30, s74, v46
	v_and_or_b32 v47, v28, s74, v33
	v_and_or_b32 v46, v63, s74, v67
	s_waitcnt lgkmcnt(0)
	s_nop 0
	v_mfma_f32_16x16x32_bf16 v[24:27], v[24:27], v[46:49], v[34:37]
	s_nop 2
	ds_read2_b64 v[32:35], v2 offset0:72 offset1:76
	s_waitcnt lgkmcnt(0)
	v_mfma_f32_16x16x32_bf16 v[32:35], v[32:35], v[46:49], v[42:45]
	s_nop 2
	ds_read2_b64 v[42:45], v7 offset0:104 offset1:108
	s_waitcnt lgkmcnt(0)
	v_mfma_f32_16x16x32_bf16 v[42:45], v[42:45], v[46:49], v[50:53]
	s_nop 2
	ds_read2_b64 v[50:53], v10 offset0:136 offset1:140
	s_waitcnt lgkmcnt(0)
	v_mfma_f32_16x16x32_bf16 v[50:53], v[50:53], v[46:49], v[54:57]
	s_nop 2
	ds_read2_b64 v[54:57], v3 offset0:168 offset1:172
	s_waitcnt lgkmcnt(0)
	v_mfma_f32_16x16x32_bf16 v[54:57], v[54:57], v[46:49], v[58:61]
	s_nop 2
	ds_read2_b64 v[58:61], v11 offset0:200 offset1:204
	s_waitcnt lgkmcnt(0)
	v_mfma_f32_16x16x32_bf16 v[58:61], v[58:61], v[46:49], v[80:83]
	s_nop 2
	ds_read2_b64 v[80:83], v14 offset0:232 offset1:236
	s_waitcnt lgkmcnt(0)
	v_mfma_f32_16x16x32_bf16 v[80:83], v[80:83], v[46:49], v[84:87]
	s_nop 2
	ds_read2_b64 v[84:87], v62 offset0:8 offset1:12
	s_waitcnt lgkmcnt(0)
	v_mfma_f32_16x16x32_bf16 v[36:39], v[84:87], v[46:49], v[38:41]
	v_bfe_u32 v28, v23, 16, 1
	v_bfe_u32 v29, v21, 16, 1
	v_bfe_u32 v30, v19, 16, 1
	v_bfe_u32 v40, v16, 16, 1
	v_add3_u32 v16, v16, v40, s73
	v_add3_u32 v30, v19, v30, s73
	v_add3_u32 v29, v21, v29, s73
	v_add3_u32 v23, v23, v28, s73
	v_bfe_u32 v19, v12, 16, 1
	v_bfe_u32 v21, v13, 16, 1
	v_bfe_u32 v28, v18, 16, 1
	v_bfe_u32 v40, v20, 16, 1
	v_add3_u32 v40, v20, v40, s73
	v_add3_u32 v28, v18, v28, s73
	v_add3_u32 v13, v13, v21, s73
	v_add3_u32 v12, v12, v19, s73
	ds_read2_b64 v[18:21], v9 offset0:48 offset1:52
	v_lshrrev_b32_e32 v12, 16, v12
	v_lshrrev_b32_e32 v13, 16, v13
	v_lshrrev_b32_e32 v28, 16, v28
	v_lshrrev_b32_e32 v40, 16, v40
	v_and_or_b32 v49, v23, s74, v40
	v_and_or_b32 v48, v29, s74, v28
	v_and_or_b32 v47, v30, s74, v13
	v_and_or_b32 v46, v16, s74, v12
	s_waitcnt lgkmcnt(0)
	s_nop 0
	v_mfma_f32_16x16x32_bf16 v[18:21], v[18:21], v[46:49], v[24:27]
	s_nop 2
	ds_read2_b64 v[24:27], v2 offset0:80 offset1:84
	s_waitcnt lgkmcnt(0)
	v_mfma_f32_16x16x32_bf16 v[24:27], v[24:27], v[46:49], v[32:35]
	s_nop 2
	ds_read2_b64 v[32:35], v7 offset0:112 offset1:116
	s_waitcnt lgkmcnt(0)
	v_mfma_f32_16x16x32_bf16 v[32:35], v[32:35], v[46:49], v[42:45]
	s_nop 2
	ds_read2_b64 v[40:43], v10 offset0:144 offset1:148
	s_waitcnt lgkmcnt(0)
	v_mfma_f32_16x16x32_bf16 v[40:43], v[40:43], v[46:49], v[50:53]
	s_nop 2
	ds_read2_b64 v[50:53], v3 offset0:176 offset1:180
	s_waitcnt lgkmcnt(0)
	v_mfma_f32_16x16x32_bf16 v[50:53], v[50:53], v[46:49], v[54:57]
	s_nop 2
	ds_read2_b64 v[54:57], v11 offset0:208 offset1:212
	s_waitcnt lgkmcnt(0)
	v_mfma_f32_16x16x32_bf16 v[54:57], v[54:57], v[46:49], v[58:61]
	s_nop 2
	ds_read2_b64 v[58:61], v14 offset0:240 offset1:244
	s_waitcnt lgkmcnt(0)
	v_mfma_f32_16x16x32_bf16 v[58:61], v[58:61], v[46:49], v[80:83]
	s_nop 2
	ds_read2_b64 v[80:83], v62 offset0:16 offset1:20
	s_waitcnt lgkmcnt(0)
	v_mfma_f32_16x16x32_bf16 v[36:39], v[80:83], v[46:49], v[36:39]
	v_bfe_u32 v12, v31, 16, 1
	v_bfe_u32 v28, v22, 16, 1
	v_add3_u32 v12, v31, v12, s73
	v_add3_u32 v22, v22, v28, s73
	ds_read2_b64 v[28:31], v9 offset0:56 offset1:60
	v_bfe_u32 v13, v1, 16, 1
	v_bfe_u32 v16, v6, 16, 1
	v_bfe_u32 v23, v8, 16, 1
	v_add3_u32 v8, v8, v23, s73
	v_add3_u32 v6, v6, v16, s73
	v_add3_u32 v1, v1, v13, s73
	v_bfe_u32 v13, v4, 16, 1
	v_bfe_u32 v16, v5, 16, 1
	v_bfe_u32 v23, v0, 16, 1
	v_add3_u32 v0, v0, v23, s73
	v_add3_u32 v5, v5, v16, s73
	v_add3_u32 v4, v4, v13, s73
	v_lshrrev_b32_e32 v4, 16, v4
	v_lshrrev_b32_e32 v5, 16, v5
	v_lshrrev_b32_e32 v0, 16, v0
	v_lshrrev_b32_e32 v9, 16, v22
	v_and_or_b32 v47, v12, s74, v9
	v_and_or_b32 v46, v1, s74, v0
	v_and_or_b32 v45, v6, s74, v5
	v_and_or_b32 v44, v8, s74, v4
	ds_read2_b64 v[4:7], v7 offset0:120 offset1:124
	s_waitcnt lgkmcnt(1)
	v_mfma_f32_16x16x32_bf16 v[18:21], v[28:31], v[44:47], v[18:21]
	ds_read2_b64 v[28:31], v2 offset0:88 offset1:92
	ds_read2_b64 v[0:3], v3 offset0:184 offset1:188
	s_waitcnt lgkmcnt(1)
	v_mfma_f32_16x16x32_bf16 v[22:25], v[28:31], v[44:47], v[24:27]
	s_nop 2
	ds_read2_b64 v[26:29], v10 offset0:152 offset1:156
	ds_read2_b64 v[8:11], v11 offset0:216 offset1:220
	v_mfma_f32_16x16x32_bf16 v[4:7], v[4:7], v[44:47], v[32:35]
	s_waitcnt lgkmcnt(1)
	v_mfma_f32_16x16x32_bf16 v[26:29], v[26:29], v[44:47], v[40:43]
	s_nop 0
	ds_read2_b64 v[30:33], v14 offset0:248 offset1:252
	s_nop 0
	ds_read2_b64 v[40:43], v62 offset0:24 offset1:28
	v_mfma_f32_16x16x32_bf16 v[0:3], v[0:3], v[44:47], v[50:53]
	s_waitcnt lgkmcnt(2)
	v_mfma_f32_16x16x32_bf16 v[8:11], v[8:11], v[44:47], v[54:57]
	s_waitcnt lgkmcnt(1)
	v_mfma_f32_16x16x32_bf16 v[30:33], v[30:33], v[44:47], v[58:61]
	s_waitcnt lgkmcnt(0)
	v_mfma_f32_16x16x32_bf16 v[34:37], v[40:43], v[44:47], v[36:39]
	v_add_f32_e32 v12, v15, v17
	v_div_scale_f32 v13, s[4:5], v12, v12, 1.0
	v_rcp_f32_e32 v14, v13
	v_div_scale_f32 v15, vcc, 1.0, v12, 1.0
	s_mov_b64 s[4:5], 0
	v_fma_f32 v16, -v13, v14, 1.0
	v_fmac_f32_e32 v14, v16, v14
	v_mul_f32_e32 v16, v15, v14
	v_fma_f32 v17, -v13, v16, v15
	v_fmac_f32_e32 v16, v17, v14
	v_fma_f32 v13, -v13, v16, v15
	v_div_fmas_f32 v13, v13, v14, v16
	v_div_fixup_f32 v12, v13, v12, 1.0
	v_mov_b32_e32 v16, v18
	v_mov_b32_e32 v17, v20
	v_pk_mul_f32 v[16:17], v[12:13], v[16:17] op_sel_hi:[0,1]
	v_mov_b32_e32 v20, v19
	v_pk_mul_f32 v[18:19], v[12:13], v[20:21] op_sel_hi:[0,1]
	v_and_b32_sdwa v13, v17, v75 dst_sel:DWORD dst_unused:UNUSED_PAD src0_sel:WORD_1 src1_sel:DWORD
	v_and_b32_sdwa v20, v16, v75 dst_sel:DWORD dst_unused:UNUSED_PAD src0_sel:WORD_1 src1_sel:DWORD
	v_add3_u32 v16, v16, v20, s73
	v_add3_u32 v13, v17, v13, s73
	v_and_b32_sdwa v17, v19, v75 dst_sel:DWORD dst_unused:UNUSED_PAD src0_sel:WORD_1 src1_sel:DWORD
	v_and_b32_sdwa v20, v18, v75 dst_sel:DWORD dst_unused:UNUSED_PAD src0_sel:WORD_1 src1_sel:DWORD
	v_add3_u32 v17, v19, v17, s73
	v_add3_u32 v18, v18, v20, s73
	v_and_b32_e32 v17, 0xffff0000, v17
	v_and_b32_e32 v18, 0xffff0000, v18
	v_lshl_add_u64 v[14:15], v[68:69], 0, v[64:65]
	v_or_b32_sdwa v17, v17, v13 dst_sel:DWORD dst_unused:UNUSED_PAD src0_sel:DWORD src1_sel:WORD_1
	v_or_b32_sdwa v16, v18, v16 dst_sel:DWORD dst_unused:UNUSED_PAD src0_sel:DWORD src1_sel:WORD_1
	global_store_dwordx2 v[14:15], v[16:17], off
	v_mov_b32_e32 v16, v22
	v_mov_b32_e32 v17, v24
	v_pk_mul_f32 v[16:17], v[12:13], v[16:17] op_sel_hi:[0,1]
	v_mov_b32_e32 v24, v23
	v_pk_mul_f32 v[18:19], v[12:13], v[24:25] op_sel_hi:[0,1]
	v_and_b32_sdwa v13, v17, v75 dst_sel:DWORD dst_unused:UNUSED_PAD src0_sel:WORD_1 src1_sel:DWORD
	v_and_b32_sdwa v20, v16, v75 dst_sel:DWORD dst_unused:UNUSED_PAD src0_sel:WORD_1 src1_sel:DWORD
	v_add3_u32 v16, v16, v20, s73
	v_add3_u32 v13, v17, v13, s73
	v_and_b32_sdwa v17, v19, v75 dst_sel:DWORD dst_unused:UNUSED_PAD src0_sel:WORD_1 src1_sel:DWORD
	v_and_b32_sdwa v20, v18, v75 dst_sel:DWORD dst_unused:UNUSED_PAD src0_sel:WORD_1 src1_sel:DWORD
	v_add3_u32 v17, v19, v17, s73
	v_add3_u32 v18, v18, v20, s73
	v_and_b32_e32 v17, 0xffff0000, v17
	v_and_b32_e32 v18, 0xffff0000, v18
	v_or_b32_sdwa v17, v17, v13 dst_sel:DWORD dst_unused:UNUSED_PAD src0_sel:DWORD src1_sel:WORD_1
	v_or_b32_sdwa v16, v18, v16 dst_sel:DWORD dst_unused:UNUSED_PAD src0_sel:DWORD src1_sel:WORD_1
	global_store_dwordx2 v[14:15], v[16:17], off offset:32
	v_mov_b32_e32 v16, v4
	v_mov_b32_e32 v17, v6
	v_pk_mul_f32 v[16:17], v[12:13], v[16:17] op_sel_hi:[0,1]
	v_mov_b32_e32 v6, v5
	v_pk_mul_f32 v[4:5], v[12:13], v[6:7] op_sel_hi:[0,1]
	v_and_b32_sdwa v7, v16, v75 dst_sel:DWORD dst_unused:UNUSED_PAD src0_sel:WORD_1 src1_sel:DWORD
	v_add3_u32 v7, v16, v7, s73
	v_and_b32_sdwa v13, v5, v75 dst_sel:DWORD dst_unused:UNUSED_PAD src0_sel:WORD_1 src1_sel:DWORD
	v_and_b32_sdwa v16, v4, v75 dst_sel:DWORD dst_unused:UNUSED_PAD src0_sel:WORD_1 src1_sel:DWORD
	v_and_b32_sdwa v6, v17, v75 dst_sel:DWORD dst_unused:UNUSED_PAD src0_sel:WORD_1 src1_sel:DWORD
	v_add3_u32 v5, v5, v13, s73
	v_add3_u32 v4, v4, v16, s73
	v_add3_u32 v6, v17, v6, s73
	v_and_b32_e32 v5, 0xffff0000, v5
	v_and_b32_e32 v4, 0xffff0000, v4
	v_or_b32_sdwa v5, v5, v6 dst_sel:DWORD dst_unused:UNUSED_PAD src0_sel:DWORD src1_sel:WORD_1
	v_or_b32_sdwa v4, v4, v7 dst_sel:DWORD dst_unused:UNUSED_PAD src0_sel:DWORD src1_sel:WORD_1
	global_store_dwordx2 v[14:15], v[4:5], off offset:64
	v_mov_b32_e32 v4, v26
	v_mov_b32_e32 v5, v28
	v_pk_mul_f32 v[4:5], v[12:13], v[4:5] op_sel_hi:[0,1]
	v_mov_b32_e32 v28, v27
	v_pk_mul_f32 v[6:7], v[12:13], v[28:29] op_sel_hi:[0,1]
	v_and_b32_sdwa v13, v5, v75 dst_sel:DWORD dst_unused:UNUSED_PAD src0_sel:WORD_1 src1_sel:DWORD
	v_and_b32_sdwa v16, v4, v75 dst_sel:DWORD dst_unused:UNUSED_PAD src0_sel:WORD_1 src1_sel:DWORD
	v_add3_u32 v4, v4, v16, s73
	v_add3_u32 v5, v5, v13, s73
	v_and_b32_sdwa v13, v7, v75 dst_sel:DWORD dst_unused:UNUSED_PAD src0_sel:WORD_1 src1_sel:DWORD
	v_and_b32_sdwa v16, v6, v75 dst_sel:DWORD dst_unused:UNUSED_PAD src0_sel:WORD_1 src1_sel:DWORD
	v_add3_u32 v7, v7, v13, s73
	v_add3_u32 v6, v6, v16, s73
	v_and_b32_e32 v7, 0xffff0000, v7
	v_and_b32_e32 v6, 0xffff0000, v6
	v_or_b32_sdwa v5, v7, v5 dst_sel:DWORD dst_unused:UNUSED_PAD src0_sel:DWORD src1_sel:WORD_1
	v_or_b32_sdwa v4, v6, v4 dst_sel:DWORD dst_unused:UNUSED_PAD src0_sel:DWORD src1_sel:WORD_1
	global_store_dwordx2 v[14:15], v[4:5], off offset:96
	v_mov_b32_e32 v4, v0
	v_mov_b32_e32 v5, v2
	v_pk_mul_f32 v[4:5], v[12:13], v[4:5] op_sel_hi:[0,1]
	v_mov_b32_e32 v2, v1
	v_pk_mul_f32 v[0:1], v[12:13], v[2:3] op_sel_hi:[0,1]
	v_and_b32_sdwa v2, v5, v75 dst_sel:DWORD dst_unused:UNUSED_PAD src0_sel:WORD_1 src1_sel:DWORD
	v_and_b32_sdwa v3, v4, v75 dst_sel:DWORD dst_unused:UNUSED_PAD src0_sel:WORD_1 src1_sel:DWORD
	v_add3_u32 v3, v4, v3, s73
	v_add3_u32 v2, v5, v2, s73
	v_and_b32_sdwa v4, v1, v75 dst_sel:DWORD dst_unused:UNUSED_PAD src0_sel:WORD_1 src1_sel:DWORD
	v_and_b32_sdwa v5, v0, v75 dst_sel:DWORD dst_unused:UNUSED_PAD src0_sel:WORD_1 src1_sel:DWORD
	v_add3_u32 v1, v1, v4, s73
	v_add3_u32 v0, v0, v5, s73
	v_and_b32_e32 v1, 0xffff0000, v1
	v_and_b32_e32 v0, 0xffff0000, v0
	v_or_b32_sdwa v1, v1, v2 dst_sel:DWORD dst_unused:UNUSED_PAD src0_sel:DWORD src1_sel:WORD_1
	v_or_b32_sdwa v0, v0, v3 dst_sel:DWORD dst_unused:UNUSED_PAD src0_sel:DWORD src1_sel:WORD_1
	global_store_dwordx2 v[14:15], v[0:1], off offset:128
	v_mov_b32_e32 v0, v8
	v_mov_b32_e32 v1, v10
	v_pk_mul_f32 v[0:1], v[12:13], v[0:1] op_sel_hi:[0,1]
	v_mov_b32_e32 v10, v9
	v_pk_mul_f32 v[2:3], v[12:13], v[10:11] op_sel_hi:[0,1]
	v_and_b32_sdwa v4, v1, v75 dst_sel:DWORD dst_unused:UNUSED_PAD src0_sel:WORD_1 src1_sel:DWORD
	v_and_b32_sdwa v5, v0, v75 dst_sel:DWORD dst_unused:UNUSED_PAD src0_sel:WORD_1 src1_sel:DWORD
	v_add3_u32 v0, v0, v5, s73
	v_add3_u32 v1, v1, v4, s73
	v_and_b32_sdwa v4, v3, v75 dst_sel:DWORD dst_unused:UNUSED_PAD src0_sel:WORD_1 src1_sel:DWORD
	v_and_b32_sdwa v5, v2, v75 dst_sel:DWORD dst_unused:UNUSED_PAD src0_sel:WORD_1 src1_sel:DWORD
	v_add3_u32 v3, v3, v4, s73
	v_add3_u32 v2, v2, v5, s73
	v_and_b32_e32 v3, 0xffff0000, v3
	v_and_b32_e32 v2, 0xffff0000, v2
	v_or_b32_sdwa v1, v3, v1 dst_sel:DWORD dst_unused:UNUSED_PAD src0_sel:DWORD src1_sel:WORD_1
	v_or_b32_sdwa v0, v2, v0 dst_sel:DWORD dst_unused:UNUSED_PAD src0_sel:DWORD src1_sel:WORD_1
	global_store_dwordx2 v[14:15], v[0:1], off offset:160
	v_mov_b32_e32 v0, v30
	v_mov_b32_e32 v1, v32
	v_pk_mul_f32 v[0:1], v[12:13], v[0:1] op_sel_hi:[0,1]
	v_mov_b32_e32 v32, v31
	v_pk_mul_f32 v[2:3], v[12:13], v[32:33] op_sel_hi:[0,1]
	v_and_b32_sdwa v4, v1, v75 dst_sel:DWORD dst_unused:UNUSED_PAD src0_sel:WORD_1 src1_sel:DWORD
	v_and_b32_sdwa v5, v0, v75 dst_sel:DWORD dst_unused:UNUSED_PAD src0_sel:WORD_1 src1_sel:DWORD
	v_add3_u32 v0, v0, v5, s73
	v_add3_u32 v1, v1, v4, s73
	v_and_b32_sdwa v4, v3, v75 dst_sel:DWORD dst_unused:UNUSED_PAD src0_sel:WORD_1 src1_sel:DWORD
	v_and_b32_sdwa v5, v2, v75 dst_sel:DWORD dst_unused:UNUSED_PAD src0_sel:WORD_1 src1_sel:DWORD
	v_add3_u32 v3, v3, v4, s73
	v_add3_u32 v2, v2, v5, s73
	v_and_b32_e32 v3, 0xffff0000, v3
	v_and_b32_e32 v2, 0xffff0000, v2
	v_or_b32_sdwa v1, v3, v1 dst_sel:DWORD dst_unused:UNUSED_PAD src0_sel:DWORD src1_sel:WORD_1
	v_or_b32_sdwa v0, v2, v0 dst_sel:DWORD dst_unused:UNUSED_PAD src0_sel:DWORD src1_sel:WORD_1
	global_store_dwordx2 v[14:15], v[0:1], off offset:192
	v_mov_b32_e32 v0, v34
	v_mov_b32_e32 v1, v36
	v_pk_mul_f32 v[0:1], v[12:13], v[0:1] op_sel_hi:[0,1]
	v_mov_b32_e32 v36, v35
	v_pk_mul_f32 v[2:3], v[12:13], v[36:37] op_sel_hi:[0,1]
	v_and_b32_sdwa v4, v1, v75 dst_sel:DWORD dst_unused:UNUSED_PAD src0_sel:WORD_1 src1_sel:DWORD
	v_and_b32_sdwa v5, v0, v75 dst_sel:DWORD dst_unused:UNUSED_PAD src0_sel:WORD_1 src1_sel:DWORD
	v_add3_u32 v0, v0, v5, s73
	v_add3_u32 v1, v1, v4, s73
	v_and_b32_sdwa v4, v3, v75 dst_sel:DWORD dst_unused:UNUSED_PAD src0_sel:WORD_1 src1_sel:DWORD
	v_and_b32_sdwa v5, v2, v75 dst_sel:DWORD dst_unused:UNUSED_PAD src0_sel:WORD_1 src1_sel:DWORD
	v_add3_u32 v3, v3, v4, s73
	v_add3_u32 v2, v2, v5, s73
	v_and_b32_e32 v3, 0xffff0000, v3
	v_and_b32_e32 v2, 0xffff0000, v2
	v_or_b32_sdwa v1, v3, v1 dst_sel:DWORD dst_unused:UNUSED_PAD src0_sel:DWORD src1_sel:WORD_1
	v_or_b32_sdwa v0, v2, v0 dst_sel:DWORD dst_unused:UNUSED_PAD src0_sel:DWORD src1_sel:WORD_1
	global_store_dwordx2 v[14:15], v[0:1], off offset:224
	s_barrier
.LBB0_652:
	s_andn2_b64 vcc, exec, s[4:5]
	s_cbranch_vccnz .LBB0_657
	s_load_dwordx4 s[16:19], s[28:29], 0x18
	v_mov_b32_e32 v68, v156
	s_and_b32 s48, s64, 0x7f00
	v_ashrrev_i32_e32 v8, 4, v68
	s_add_i32 s4, s33, 0x10000
	v_lshlrev_b32_e32 v0, 3, v68
	v_ashrrev_i32_e32 v9, 31, v8
	s_and_b32 s7, s4, 0x180
	s_waitcnt vmcnt(1)
	v_and_b32_e32 v7, 0x78, v0
	v_lshl_add_u64 v[0:1], v[8:9], 0, s[48:49]
	v_lshlrev_b32_e32 v64, 2, v7
	v_lshlrev_b64 v[4:5], 11, v[0:1]
	s_lshl_b32 s4, s7, 2
	s_waitcnt lgkmcnt(0)
	v_lshl_add_u64 v[2:3], s[16:17], 0, v[64:65]
	v_or_b32_e32 v4, s4, v4
	v_lshl_add_u64 v[0:1], v[2:3], 0, v[4:5]
	global_load_dwordx4 v[12:15], v[0:1], off nt
	global_load_dwordx4 v[16:19], v[0:1], off offset:16 nt
	v_lshl_add_u64 v[0:1], s[18:19], 0, v[64:65]
	v_lshl_add_u64 v[4:5], v[0:1], 0, v[4:5]
	global_load_dwordx4 v[20:23], v[4:5], off nt
	global_load_dwordx4 v[24:27], v[4:5], off offset:16 nt
	v_add_u32_e32 v4, 0x200, v68
	v_ashrrev_i32_e32 v10, 4, v4
	v_ashrrev_i32_e32 v11, 31, v10
	v_lshl_add_u64 v[4:5], v[10:11], 0, s[48:49]
	v_lshlrev_b64 v[36:37], 11, v[4:5]
	v_or_b32_e32 v36, s4, v36
	v_lshl_add_u64 v[4:5], v[2:3], 0, v[36:37]
	global_load_dwordx4 v[28:31], v[4:5], off nt
	global_load_dwordx4 v[32:35], v[4:5], off offset:16 nt
	v_lshl_add_u64 v[40:41], v[0:1], 0, v[36:37]
	global_load_dwordx4 v[36:39], v[40:41], off offset:16 nt
	s_nop 0
	global_load_dwordx4 v[40:43], v[40:41], off nt
	v_add_u32_e32 v6, 0x400, v68
	v_mov_b32_e32 v9, s68
	v_ashrrev_i32_e32 v6, 4, v6
	v_lshl_add_u32 v4, v7, 1, 0
	v_mad_u32_u24 v5, v7, s69, v9
	v_add_u32_e32 v5, v5, v7
	v_ashrrev_i32_e32 v7, 31, v6
	v_mad_u64_u32 v[52:53], s[8:9], v8, s70, v[4:5]
	v_lshl_add_u32 v11, v8, 1, v5
	v_lshl_add_u64 v[8:9], v[6:7], 0, s[48:49]
	v_lshlrev_b64 v[8:9], 11, v[8:9]
	v_or_b32_e32 v8, s4, v8
	v_lshl_add_u64 v[48:49], v[2:3], 0, v[8:9]
	global_load_dwordx4 v[44:47], v[48:49], off offset:16 nt
	s_nop 0
	global_load_dwordx4 v[48:51], v[48:49], off nt
	v_lshl_add_u64 v[8:9], v[0:1], 0, v[8:9]
	v_cmp_gt_u32_e32 vcc, 64, v68
	s_waitcnt vmcnt(9)
	v_bfe_u32 v7, v12, 16, 1
	v_bfe_u32 v53, v13, 16, 1
	v_bfe_u32 v54, v14, 16, 1
	v_bfe_u32 v55, v15, 16, 1
	s_waitcnt vmcnt(8)
	v_bfe_u32 v56, v16, 16, 1
	v_bfe_u32 v57, v17, 16, 1
	v_bfe_u32 v58, v18, 16, 1
	v_bfe_u32 v59, v19, 16, 1
	v_add3_u32 v7, v12, v7, s73
	v_add3_u32 v12, v13, v53, s73
	v_add3_u32 v13, v14, v54, s73
	v_add3_u32 v14, v15, v55, s73
	v_add3_u32 v15, v16, v56, s73
	v_add3_u32 v16, v17, v57, s73
	v_add3_u32 v17, v18, v58, s73
	v_add3_u32 v18, v19, v59, s73
	v_lshrrev_b32_e32 v7, 16, v7
	v_lshrrev_b32_e32 v13, 16, v13
	v_lshrrev_b32_e32 v15, 16, v15
	v_lshrrev_b32_e32 v17, 16, v17
	s_waitcnt vmcnt(7)
	v_bfe_u32 v60, v20, 16, 1
	v_bfe_u32 v61, v21, 16, 1
	v_bfe_u32 v62, v22, 16, 1
	v_bfe_u32 v63, v23, 16, 1
	s_waitcnt vmcnt(6)
	v_bfe_u32 v64, v24, 16, 1
	v_bfe_u32 v67, v25, 16, 1
	v_bfe_u32 v69, v26, 16, 1
	v_bfe_u32 v79, v27, 16, 1
	v_and_or_b32 v12, v12, s74, v7
	v_and_or_b32 v13, v14, s74, v13
	v_and_or_b32 v14, v16, s74, v15
	v_and_or_b32 v15, v18, s74, v17
	v_add3_u32 v19, v20, v60, s73
	v_add3_u32 v20, v21, v61, s73
	v_add3_u32 v21, v22, v62, s73
	v_add3_u32 v22, v23, v63, s73
	v_add3_u32 v23, v24, v64, s73
	v_add3_u32 v24, v25, v67, s73
	v_add3_u32 v25, v26, v69, s73
	v_add3_u32 v26, v27, v79, s73
	ds_write_b128 v52, v[12:15]
	ds_write_b16_d16_hi v11, v19
	ds_write_b16_d16_hi v11, v20 offset:528
	ds_write_b16_d16_hi v11, v21 offset:1056
	ds_write_b16_d16_hi v11, v22 offset:1584
	ds_write_b16_d16_hi v11, v23 offset:2112
	ds_write_b16_d16_hi v11, v24 offset:2640
	ds_write_b16_d16_hi v11, v25 offset:3168
	ds_write_b16_d16_hi v11, v26 offset:3696
	global_load_dwordx4 v[16:19], v[8:9], off offset:16 nt
	global_load_dwordx4 v[20:23], v[8:9], off nt
	s_waitcnt vmcnt(7)
	v_cvt_pk_bf16_f32 v12, v28, v29
	v_cvt_pk_bf16_f32 v13, v30, v31
	s_waitcnt vmcnt(6)
	v_cvt_pk_bf16_f32 v14, v32, v33
	v_cvt_pk_bf16_f32 v15, v34, v35
	s_waitcnt vmcnt(4)
	v_bfe_u32 v8, v41, 16, 1
	v_bfe_u32 v7, v40, 16, 1
	v_add3_u32 v11, v41, v8, s73
	v_bfe_u32 v8, v42, 16, 1
	v_add3_u32 v7, v40, v7, s73
	v_add3_u32 v40, v42, v8, s73
	v_bfe_u32 v8, v43, 16, 1
	v_add3_u32 v41, v43, v8, s73
	v_bfe_u32 v8, v36, 16, 1
	v_add3_u32 v36, v36, v8, s73
	v_bfe_u32 v8, v37, 16, 1
	v_add3_u32 v37, v37, v8, s73
	v_add_u32_e32 v8, 0x600, v68
	v_ashrrev_i32_e32 v8, 4, v8
	v_ashrrev_i32_e32 v9, 31, v8
	v_lshl_add_u64 v[24:25], v[8:9], 0, s[48:49]
	v_lshlrev_b64 v[32:33], 11, v[24:25]
	v_or_b32_e32 v32, s4, v32
	v_lshl_add_u64 v[28:29], v[2:3], 0, v[32:33]
	global_load_dwordx4 v[24:27], v[28:29], off offset:16 nt
	s_nop 0
	global_load_dwordx4 v[28:31], v[28:29], off nt
	v_bfe_u32 v34, v38, 16, 1
	v_add3_u32 v9, v38, v34, s73
	v_bfe_u32 v34, v39, 16, 1
	v_add3_u32 v38, v39, v34, s73
	v_mad_u64_u32 v[34:35], s[8:9], v10, s70, v[4:5]
	v_lshl_add_u32 v10, v10, 1, v5
	ds_write_b128 v34, v[12:15]
	ds_write_b16_d16_hi v10, v7
	ds_write_b16_d16_hi v10, v11 offset:528
	ds_write_b16_d16_hi v10, v40 offset:1056
	ds_write_b16_d16_hi v10, v41 offset:1584
	ds_write_b16_d16_hi v10, v36 offset:2112
	ds_write_b16_d16_hi v10, v37 offset:2640
	ds_write_b16_d16_hi v10, v9 offset:3168
	ds_write_b16_d16_hi v10, v38 offset:3696
	v_lshl_add_u64 v[10:11], v[0:1], 0, v[32:33]
	global_load_dwordx4 v[32:35], v[10:11], off offset:16 nt
	global_load_dwordx4 v[36:39], v[10:11], off nt
	s_waitcnt vmcnt(6)
	v_cvt_pk_bf16_f32 v12, v48, v49
	v_cvt_pk_bf16_f32 v13, v50, v51
	v_cvt_pk_bf16_f32 v14, v44, v45
	v_cvt_pk_bf16_f32 v15, v46, v47
	s_waitcnt vmcnt(4)
	v_bfe_u32 v10, v22, 16, 1
	v_add3_u32 v44, v22, v10, s73
	v_bfe_u32 v10, v23, 16, 1
	v_add3_u32 v45, v23, v10, s73
	v_bfe_u32 v10, v16, 16, 1
	v_add3_u32 v46, v16, v10, s73
	v_bfe_u32 v10, v17, 16, 1
	v_add3_u32 v47, v17, v10, s73
	v_add_u32_e32 v10, 0x800, v68
	v_ashrrev_i32_e32 v10, 4, v10
	v_ashrrev_i32_e32 v11, 31, v10
	v_lshl_add_u64 v[16:17], v[10:11], 0, s[48:49]
	v_lshlrev_b64 v[16:17], 11, v[16:17]
	v_or_b32_e32 v16, s4, v16
	v_bfe_u32 v7, v20, 16, 1
	v_bfe_u32 v9, v21, 16, 1
	v_lshl_add_u64 v[40:41], v[2:3], 0, v[16:17]
	v_add3_u32 v7, v20, v7, s73
	v_add3_u32 v9, v21, v9, s73
	global_load_dwordx4 v[20:23], v[40:41], off offset:16 nt
	s_nop 0
	global_load_dwordx4 v[40:43], v[40:41], off nt
	v_bfe_u32 v48, v18, 16, 1
	v_add3_u32 v11, v18, v48, s73
	v_bfe_u32 v18, v19, 16, 1
	v_add3_u32 v48, v19, v18, s73
	v_mad_u64_u32 v[18:19], s[8:9], v6, s70, v[4:5]
	v_lshl_add_u32 v6, v6, 1, v5
	ds_write_b128 v18, v[12:15]
	ds_write_b16_d16_hi v6, v7
	ds_write_b16_d16_hi v6, v9 offset:528
	ds_write_b16_d16_hi v6, v44 offset:1056
	ds_write_b16_d16_hi v6, v45 offset:1584
	ds_write_b16_d16_hi v6, v46 offset:2112
	ds_write_b16_d16_hi v6, v47 offset:2640
	ds_write_b16_d16_hi v6, v11 offset:3168
	ds_write_b16_d16_hi v6, v48 offset:3696
	s_waitcnt vmcnt(4)
	v_cvt_pk_bf16_f32 v12, v28, v29
	v_bfe_u32 v6, v30, 16, 1
	v_add3_u32 v6, v30, v6, s73
	v_lshrrev_b32_e32 v9, 16, v6
	v_lshl_add_u64 v[6:7], v[0:1], 0, v[16:17]
	global_load_dwordx4 v[16:19], v[6:7], off offset:16 nt
	global_load_dwordx4 v[44:47], v[6:7], off nt
	v_bfe_u32 v6, v31, 16, 1
	v_add3_u32 v6, v31, v6, s73
	v_and_or_b32 v13, v6, s74, v9
	v_cvt_pk_bf16_f32 v14, v24, v25
	v_cvt_pk_bf16_f32 v15, v26, v27
	s_waitcnt vmcnt(4)
	v_bfe_u32 v6, v36, 16, 1
	v_add3_u32 v9, v36, v6, s73
	v_bfe_u32 v6, v37, 16, 1
	v_add3_u32 v11, v37, v6, s73
	v_bfe_u32 v6, v38, 16, 1
	v_add3_u32 v36, v38, v6, s73
	v_bfe_u32 v6, v39, 16, 1
	v_add3_u32 v37, v39, v6, s73
	v_bfe_u32 v6, v32, 16, 1
	v_add3_u32 v38, v32, v6, s73
	v_bfe_u32 v6, v33, 16, 1
	v_add3_u32 v39, v33, v6, s73
	v_add_u32_e32 v6, 0xa00, v68
	v_ashrrev_i32_e32 v6, 4, v6
	v_ashrrev_i32_e32 v7, 31, v6
	v_lshl_add_u64 v[24:25], v[6:7], 0, s[48:49]
	v_lshlrev_b64 v[32:33], 11, v[24:25]
	v_or_b32_e32 v32, s4, v32
	v_lshl_add_u64 v[28:29], v[2:3], 0, v[32:33]
	global_load_dwordx4 v[24:27], v[28:29], off offset:16 nt
	s_nop 0
	global_load_dwordx4 v[28:31], v[28:29], off nt
	v_bfe_u32 v48, v34, 16, 1
	v_add3_u32 v7, v34, v48, s73
	v_bfe_u32 v34, v35, 16, 1
	v_add3_u32 v48, v35, v34, s73
	v_mad_u64_u32 v[34:35], s[8:9], v8, s70, v[4:5]
	v_lshl_add_u32 v8, v8, 1, v5
	ds_write_b128 v34, v[12:15]
	ds_write_b16_d16_hi v8, v9
	ds_write_b16_d16_hi v8, v11 offset:528
	ds_write_b16_d16_hi v8, v36 offset:1056
	ds_write_b16_d16_hi v8, v37 offset:1584
	ds_write_b16_d16_hi v8, v38 offset:2112
	ds_write_b16_d16_hi v8, v39 offset:2640
	ds_write_b16_d16_hi v8, v7 offset:3168
	ds_write_b16_d16_hi v8, v48 offset:3696
	s_waitcnt vmcnt(4)
	v_cvt_pk_bf16_f32 v12, v40, v41
	v_lshl_add_u64 v[8:9], v[0:1], 0, v[32:33]
	global_load_dwordx4 v[32:35], v[8:9], off offset:16 nt
	global_load_dwordx4 v[36:39], v[8:9], off nt
	v_cvt_pk_bf16_f32 v13, v42, v43
	v_cvt_pk_bf16_f32 v14, v20, v21
	v_cvt_pk_bf16_f32 v15, v22, v23
	s_waitcnt vmcnt(4)
	v_bfe_u32 v8, v45, 16, 1
	v_add3_u32 v11, v45, v8, s73
	v_bfe_u32 v8, v46, 16, 1
	v_add3_u32 v42, v46, v8, s73
	v_bfe_u32 v8, v47, 16, 1
	v_add3_u32 v43, v47, v8, s73
	v_bfe_u32 v8, v16, 16, 1
	v_add3_u32 v46, v16, v8, s73
	v_bfe_u32 v8, v17, 16, 1
	v_add3_u32 v47, v17, v8, s73
	v_bfe_u32 v8, v18, 16, 1
	v_add3_u32 v48, v18, v8, s73
	v_bfe_u32 v8, v19, 16, 1
	v_bfe_u32 v7, v44, 16, 1
	v_add3_u32 v49, v19, v8, s73
	v_add_u32_e32 v8, 0xc00, v68
	v_add3_u32 v7, v44, v7, s73
	v_ashrrev_i32_e32 v44, 4, v8
	v_ashrrev_i32_e32 v45, 31, v44
	v_lshl_add_u64 v[8:9], v[44:45], 0, s[48:49]
	v_lshlrev_b64 v[40:41], 11, v[8:9]
	v_or_b32_e32 v40, s4, v40
	v_lshl_add_u64 v[8:9], v[2:3], 0, v[40:41]
	global_load_dwordx4 v[16:19], v[8:9], off offset:16 nt
	global_load_dwordx4 v[20:23], v[8:9], off nt
	v_mad_u64_u32 v[8:9], s[8:9], v10, s70, v[4:5]
	ds_write_b128 v8, v[12:15]
	v_lshl_add_u32 v8, v10, 1, v5
	ds_write_b16_d16_hi v8, v7
	ds_write_b16_d16_hi v8, v11 offset:528
	ds_write_b16_d16_hi v8, v42 offset:1056
	ds_write_b16_d16_hi v8, v43 offset:1584
	ds_write_b16_d16_hi v8, v46 offset:2112
	ds_write_b16_d16_hi v8, v47 offset:2640
	ds_write_b16_d16_hi v8, v48 offset:3168
	ds_write_b16_d16_hi v8, v49 offset:3696
	v_lshl_add_u64 v[10:11], v[0:1], 0, v[40:41]
	global_load_dwordx4 v[12:15], v[10:11], off offset:16 nt
	global_load_dwordx4 v[40:43], v[10:11], off nt
	s_waitcnt vmcnt(7)
	v_bfe_u32 v10, v25, 16, 1
	s_waitcnt vmcnt(6)
	v_cvt_pk_bf16_f32 v8, v28, v29
	v_cvt_pk_bf16_f32 v9, v30, v31
	v_bfe_u32 v7, v24, 16, 1
	v_add3_u32 v7, v24, v7, s73
	v_lshrrev_b32_e32 v7, 16, v7
	v_add3_u32 v10, v25, v10, s73
	v_and_or_b32 v10, v10, s74, v7
	s_waitcnt vmcnt(4)
	v_bfe_u32 v24, v37, 16, 1
	v_cvt_pk_bf16_f32 v11, v26, v27
	v_bfe_u32 v7, v36, 16, 1
	v_add3_u32 v45, v37, v24, s73
	v_add_u32_e32 v24, 0xe00, v68
	v_add3_u32 v7, v36, v7, s73
	v_ashrrev_i32_e32 v36, 4, v24
	v_ashrrev_i32_e32 v37, 31, v36
	v_lshl_add_u64 v[24:25], v[36:37], 0, s[48:49]
	v_lshlrev_b64 v[46:47], 11, v[24:25]
	v_or_b32_e32 v46, s4, v46
	v_lshl_add_u64 v[2:3], v[2:3], 0, v[46:47]
	global_load_dwordx4 v[24:27], v[2:3], off offset:16 nt
	global_load_dwordx4 v[28:31], v[2:3], off nt
	v_bfe_u32 v2, v38, 16, 1
	v_add3_u32 v37, v38, v2, s73
	v_bfe_u32 v2, v39, 16, 1
	v_add3_u32 v38, v39, v2, s73
	v_bfe_u32 v2, v32, 16, 1
	v_add3_u32 v32, v32, v2, s73
	v_bfe_u32 v2, v33, 16, 1
	v_add3_u32 v33, v33, v2, s73
	v_bfe_u32 v2, v34, 16, 1
	v_add3_u32 v34, v34, v2, s73
	v_bfe_u32 v2, v35, 16, 1
	v_add3_u32 v35, v35, v2, s73
	v_mad_u64_u32 v[2:3], s[4:5], v6, s70, v[4:5]
	ds_write_b128 v2, v[8:11]
	v_lshl_add_u32 v10, v6, 1, v5
	ds_write_b16_d16_hi v10, v7
	ds_write_b16_d16_hi v10, v45 offset:528
	ds_write_b16_d16_hi v10, v37 offset:1056
	ds_write_b16_d16_hi v10, v38 offset:1584
	ds_write_b16_d16_hi v10, v32 offset:2112
	v_lshl_add_u64 v[6:7], v[0:1], 0, v[46:47]
	global_load_dwordx4 v[0:3], v[6:7], off offset:16 nt
	s_nop 0
	global_load_dwordx4 v[6:9], v[6:7], off nt
	ds_write_b16_d16_hi v10, v33 offset:2640
	ds_write_b16_d16_hi v10, v34 offset:3168
	ds_write_b16_d16_hi v10, v35 offset:3696
	s_waitcnt vmcnt(6)
	v_cvt_pk_bf16_f32 v20, v20, v21
	v_cvt_pk_bf16_f32 v21, v22, v23
	v_cvt_pk_bf16_f32 v22, v16, v17
	v_cvt_pk_bf16_f32 v23, v18, v19
	s_waitcnt vmcnt(4)
	v_bfe_u32 v10, v40, 16, 1
	v_add3_u32 v16, v40, v10, s73
	v_bfe_u32 v10, v41, 16, 1
	v_add3_u32 v17, v41, v10, s73
	v_bfe_u32 v10, v42, 16, 1
	v_add3_u32 v18, v42, v10, s73
	v_bfe_u32 v10, v43, 16, 1
	v_add3_u32 v19, v43, v10, s73
	v_bfe_u32 v10, v12, 16, 1
	v_add3_u32 v12, v12, v10, s73
	v_bfe_u32 v10, v13, 16, 1
	v_add3_u32 v13, v13, v10, s73
	v_bfe_u32 v10, v14, 16, 1
	v_add3_u32 v14, v14, v10, s73
	v_bfe_u32 v10, v15, 16, 1
	v_add3_u32 v15, v15, v10, s73
	v_mad_u64_u32 v[10:11], s[4:5], v44, s70, v[4:5]
	ds_write_b128 v10, v[20:23]
	v_lshl_add_u32 v10, v44, 1, v5
	ds_write_b16_d16_hi v10, v16
	ds_write_b16_d16_hi v10, v17 offset:528
	ds_write_b16_d16_hi v10, v18 offset:1056
	ds_write_b16_d16_hi v10, v19 offset:1584
	ds_write_b16_d16_hi v10, v12 offset:2112
	ds_write_b16_d16_hi v10, v13 offset:2640
	ds_write_b16_d16_hi v10, v14 offset:3168
	ds_write_b16_d16_hi v10, v15 offset:3696
	s_waitcnt vmcnt(3)
	v_bfe_u32 v13, v25, 16, 1
	s_waitcnt vmcnt(2)
	v_cvt_pk_bf16_f32 v10, v28, v29
	v_cvt_pk_bf16_f32 v11, v30, v31
	v_bfe_u32 v12, v24, 16, 1
	v_add3_u32 v12, v24, v12, s73
	v_lshrrev_b32_e32 v12, 16, v12
	v_add3_u32 v13, v25, v13, s73
	v_and_or_b32 v12, v13, s74, v12
	v_cvt_pk_bf16_f32 v13, v26, v27
	s_waitcnt vmcnt(0)
	v_bfe_u32 v14, v6, 16, 1
	v_add3_u32 v6, v6, v14, s73
	v_bfe_u32 v14, v7, 16, 1
	v_add3_u32 v7, v7, v14, s73
	v_bfe_u32 v14, v8, 16, 1
	v_add3_u32 v8, v8, v14, s73
	v_bfe_u32 v14, v9, 16, 1
	v_add3_u32 v9, v9, v14, s73
	v_bfe_u32 v14, v0, 16, 1
	v_add3_u32 v14, v0, v14, s73
	v_bfe_u32 v0, v1, 16, 1
	v_add3_u32 v15, v1, v0, s73
	v_bfe_u32 v0, v2, 16, 1
	v_add3_u32 v2, v2, v0, s73
	v_bfe_u32 v0, v3, 16, 1
	v_add3_u32 v3, v3, v0, s73
	v_mad_u64_u32 v[0:1], s[4:5], v36, s70, v[4:5]
	ds_write_b128 v0, v[10:13]
	v_lshl_add_u32 v0, v36, 1, v5
	ds_write_b16_d16_hi v0, v6
	ds_write_b16_d16_hi v0, v7 offset:528
	ds_write_b16_d16_hi v0, v8 offset:1056
	ds_write_b16_d16_hi v0, v9 offset:1584
	ds_write_b16_d16_hi v0, v14 offset:2112
	ds_write_b16_d16_hi v0, v15 offset:2640
	ds_write_b16_d16_hi v0, v2 offset:3168
	ds_write_b16_d16_hi v0, v3 offset:3696
	s_waitcnt lgkmcnt(0)
	s_barrier
	s_and_saveexec_b64 s[4:5], vcc
	s_cbranch_execz .LBB0_656
	s_and_b32 s6, s6, 0x1fc
	s_bitset1_b32 s6, 14
	v_and_or_b32 v0, v68, 3, s6
	v_mul_u32_u24_e32 v0, 0x1e00, v0
	v_lshlrev_b32_e32 v64, 1, v0
	v_lshl_add_u64 v[0:1], s[30:31], 0, v[64:65]
	s_lshl_b32 s48, s7, 1
	v_lshl_add_u64 v[0:1], v[0:1], 0, s[48:49]
	v_and_b32_e32 v64, -16, v68
	v_lshl_add_u64 v[4:5], v[0:1], 0, v[64:65]
	v_add_co_u32_e32 v0, vcc, s76, v4
	s_mov_b64 s[8:9], 0x2000
	s_nop 0
	v_addc_co_u32_e32 v1, vcc, 0, v5, vcc
	global_load_dwordx4 v[0:3], v[0:1], off
	v_lshl_add_u64 v[4:5], v[4:5], 0, s[8:9]
	global_load_dwordx4 v[80:83], v[4:5], off offset:64
	global_load_dwordx4 v[84:87], v[4:5], off offset:128
	global_load_dwordx4 v[88:91], v[4:5], off offset:192
	v_and_b32_e32 v4, 48, v68
	v_and_b32_e32 v64, 15, v68
	v_add_u32_e32 v100, 0, v4
	v_mad_u32_u24 v101, v64, s70, v100
	ds_read_b128 v[4:7], v101
	ds_read_b128 v[8:11], v101 offset:64
	ds_read_b128 v[12:15], v101 offset:128
	v_lshrrev_b32_e32 v67, 4, v68
	s_waitcnt vmcnt(3) lgkmcnt(2)
	v_mfma_f32_16x16x32_bf16 v[4:7], v[4:7], v[0:3], 0
	s_waitcnt vmcnt(2) lgkmcnt(1)
	v_mfma_f32_16x16x32_bf16 v[4:7], v[8:11], v[80:83], v[4:7]
	ds_read_b128 v[8:11], v101 offset:192
	s_waitcnt vmcnt(1) lgkmcnt(1)
	v_mfma_f32_16x16x32_bf16 v[4:7], v[12:15], v[84:87], v[4:7]
	s_waitcnt vmcnt(0) lgkmcnt(0)
	v_mfma_f32_16x16x32_bf16 v[60:63], v[8:11], v[88:91], v[4:7]
	s_nop 5
	ds_read_b128 v[4:7], v101 offset:4352
	ds_read_b128 v[8:11], v101 offset:4416
	ds_read_b128 v[12:15], v101 offset:4480
	s_waitcnt lgkmcnt(2)
	v_mfma_f32_16x16x32_bf16 v[4:7], v[4:7], v[0:3], 0
	s_waitcnt lgkmcnt(1)
	v_mfma_f32_16x16x32_bf16 v[4:7], v[8:11], v[80:83], v[4:7]
	ds_read_b128 v[8:11], v101 offset:4544
	s_waitcnt lgkmcnt(1)
	v_mfma_f32_16x16x32_bf16 v[4:7], v[12:15], v[84:87], v[4:7]
	s_waitcnt lgkmcnt(0)
	v_mfma_f32_16x16x32_bf16 v[56:59], v[8:11], v[88:91], v[4:7]
	s_nop 5
	ds_read_b128 v[4:7], v101 offset:8704
	ds_read_b128 v[8:11], v101 offset:8768
	ds_read_b128 v[12:15], v101 offset:8832
	s_waitcnt lgkmcnt(2)
	v_mfma_f32_16x16x32_bf16 v[4:7], v[4:7], v[0:3], 0
	s_waitcnt lgkmcnt(1)
	v_mfma_f32_16x16x32_bf16 v[4:7], v[8:11], v[80:83], v[4:7]
	ds_read_b128 v[8:11], v101 offset:8896
	s_waitcnt lgkmcnt(1)
	v_mfma_f32_16x16x32_bf16 v[4:7], v[12:15], v[84:87], v[4:7]
	s_waitcnt lgkmcnt(0)
	v_mfma_f32_16x16x32_bf16 v[52:55], v[8:11], v[88:91], v[4:7]
	v_or_b32_e32 v69, 48, v68
	v_mad_u64_u32 v[16:17], s[8:9], v69, s70, v[100:101]
	s_nop 3
	ds_read_b128 v[4:7], v16
	ds_read_b128 v[8:11], v16 offset:64
	ds_read_b128 v[12:15], v16 offset:128
	s_waitcnt lgkmcnt(2)
	v_mfma_f32_16x16x32_bf16 v[4:7], v[4:7], v[0:3], 0
	s_waitcnt lgkmcnt(1)
	v_mfma_f32_16x16x32_bf16 v[4:7], v[8:11], v[80:83], v[4:7]
	ds_read_b128 v[8:11], v16 offset:192
	s_waitcnt lgkmcnt(1)
	v_mfma_f32_16x16x32_bf16 v[4:7], v[12:15], v[84:87], v[4:7]
	s_waitcnt lgkmcnt(0)
	v_mfma_f32_16x16x32_bf16 v[48:51], v[8:11], v[88:91], v[4:7]
	s_nop 5
	ds_read_b128 v[4:7], v101 offset:17408
	ds_read_b128 v[8:11], v101 offset:17472
	ds_read_b128 v[12:15], v101 offset:17536
	s_waitcnt lgkmcnt(2)
	v_mfma_f32_16x16x32_bf16 v[4:7], v[4:7], v[0:3], 0
	s_waitcnt lgkmcnt(1)
	v_mfma_f32_16x16x32_bf16 v[4:7], v[8:11], v[80:83], v[4:7]
	ds_read_b128 v[8:11], v101 offset:17600
	s_waitcnt lgkmcnt(1)
	v_mfma_f32_16x16x32_bf16 v[4:7], v[12:15], v[84:87], v[4:7]
	s_waitcnt lgkmcnt(0)
	v_mfma_f32_16x16x32_bf16 v[44:47], v[8:11], v[88:91], v[4:7]
	s_nop 5
	ds_read_b128 v[4:7], v101 offset:21760
	ds_read_b128 v[8:11], v101 offset:21824
	ds_read_b128 v[12:15], v101 offset:21888
	s_waitcnt lgkmcnt(2)
	v_mfma_f32_16x16x32_bf16 v[4:7], v[4:7], v[0:3], 0
	s_waitcnt lgkmcnt(1)
	v_mfma_f32_16x16x32_bf16 v[4:7], v[8:11], v[80:83], v[4:7]
	ds_read_b128 v[8:11], v101 offset:21952
	s_waitcnt lgkmcnt(1)
	v_mfma_f32_16x16x32_bf16 v[4:7], v[12:15], v[84:87], v[4:7]
	s_waitcnt lgkmcnt(0)
	v_mfma_f32_16x16x32_bf16 v[40:43], v[8:11], v[88:91], v[4:7]
	s_nop 5
	ds_read_b128 v[4:7], v101 offset:26112
	ds_read_b128 v[8:11], v101 offset:26176
	ds_read_b128 v[12:15], v101 offset:26240
	s_waitcnt lgkmcnt(2)
	v_mfma_f32_16x16x32_bf16 v[4:7], v[4:7], v[0:3], 0
	s_waitcnt lgkmcnt(1)
	v_mfma_f32_16x16x32_bf16 v[4:7], v[8:11], v[80:83], v[4:7]
	ds_read_b128 v[8:11], v101 offset:26304
	s_waitcnt lgkmcnt(1)
	v_mfma_f32_16x16x32_bf16 v[4:7], v[12:15], v[84:87], v[4:7]
	s_waitcnt lgkmcnt(0)
	v_mfma_f32_16x16x32_bf16 v[36:39], v[8:11], v[88:91], v[4:7]
	v_or_b32_e32 v79, 0x70, v68
	v_mad_u64_u32 v[16:17], s[8:9], v79, s70, v[100:101]
	s_nop 3
	ds_read_b128 v[4:7], v16
	ds_read_b128 v[8:11], v16 offset:64
	ds_read_b128 v[12:15], v16 offset:128
	s_waitcnt lgkmcnt(2)
	v_mfma_f32_16x16x32_bf16 v[4:7], v[4:7], v[0:3], 0
	s_waitcnt lgkmcnt(1)
	v_mfma_f32_16x16x32_bf16 v[4:7], v[8:11], v[80:83], v[4:7]
	ds_read_b128 v[8:11], v16 offset:192
	s_waitcnt lgkmcnt(1)
	v_mfma_f32_16x16x32_bf16 v[4:7], v[12:15], v[84:87], v[4:7]
	s_waitcnt lgkmcnt(0)
	v_mfma_f32_16x16x32_bf16 v[32:35], v[8:11], v[88:91], v[4:7]
	s_nop 5
	ds_read_b128 v[4:7], v101 offset:34816
	ds_read_b128 v[8:11], v101 offset:34880
	ds_read_b128 v[12:15], v101 offset:34944
	s_waitcnt lgkmcnt(2)
	v_mfma_f32_16x16x32_bf16 v[4:7], v[4:7], v[0:3], 0
	s_waitcnt lgkmcnt(1)
	v_mfma_f32_16x16x32_bf16 v[4:7], v[8:11], v[80:83], v[4:7]
	ds_read_b128 v[8:11], v101 offset:35008
	s_waitcnt lgkmcnt(1)
	v_mfma_f32_16x16x32_bf16 v[4:7], v[12:15], v[84:87], v[4:7]
	s_waitcnt lgkmcnt(0)
	v_mfma_f32_16x16x32_bf16 v[28:31], v[8:11], v[88:91], v[4:7]
	s_nop 5
	ds_read_b128 v[4:7], v101 offset:39168
	ds_read_b128 v[8:11], v101 offset:39232
	ds_read_b128 v[12:15], v101 offset:39296
	s_waitcnt lgkmcnt(2)
	v_mfma_f32_16x16x32_bf16 v[4:7], v[4:7], v[0:3], 0
	s_waitcnt lgkmcnt(1)
	v_mfma_f32_16x16x32_bf16 v[4:7], v[8:11], v[80:83], v[4:7]
	ds_read_b128 v[8:11], v101 offset:39360
	s_waitcnt lgkmcnt(1)
	v_mfma_f32_16x16x32_bf16 v[4:7], v[12:15], v[84:87], v[4:7]
	s_waitcnt lgkmcnt(0)
	v_mfma_f32_16x16x32_bf16 v[24:27], v[8:11], v[88:91], v[4:7]
	s_nop 5
	ds_read_b128 v[4:7], v101 offset:43520
	ds_read_b128 v[8:11], v101 offset:43584
	ds_read_b128 v[12:15], v101 offset:43648
	s_waitcnt lgkmcnt(2)
	v_mfma_f32_16x16x32_bf16 v[4:7], v[4:7], v[0:3], 0
	s_waitcnt lgkmcnt(1)
	v_mfma_f32_16x16x32_bf16 v[4:7], v[8:11], v[80:83], v[4:7]
	ds_read_b128 v[8:11], v101 offset:43712
	s_waitcnt lgkmcnt(1)
	v_mfma_f32_16x16x32_bf16 v[4:7], v[12:15], v[84:87], v[4:7]
	s_waitcnt lgkmcnt(0)
	v_mfma_f32_16x16x32_bf16 v[20:23], v[8:11], v[88:91], v[4:7]
	s_nop 5
	v_or_b32_e32 v4, 0xb0, v68
	v_mad_u64_u32 v[16:17], s[8:9], v4, s70, v[100:101]
	ds_read_b128 v[4:7], v16
	ds_read_b128 v[8:11], v16 offset:64
	ds_read_b128 v[12:15], v16 offset:128
	s_waitcnt lgkmcnt(2)
	v_mfma_f32_16x16x32_bf16 v[4:7], v[4:7], v[0:3], 0
	s_waitcnt lgkmcnt(1)
	v_mfma_f32_16x16x32_bf16 v[4:7], v[8:11], v[80:83], v[4:7]
	ds_read_b128 v[8:11], v16 offset:192
	s_waitcnt lgkmcnt(1)
	v_mfma_f32_16x16x32_bf16 v[4:7], v[12:15], v[84:87], v[4:7]
	s_waitcnt lgkmcnt(0)
	v_mfma_f32_16x16x32_bf16 v[16:19], v[8:11], v[88:91], v[4:7]
	s_nop 5
	ds_read_b128 v[4:7], v101 offset:52224
	ds_read_b128 v[8:11], v101 offset:52288
	ds_read_b128 v[12:15], v101 offset:52352
	s_waitcnt lgkmcnt(2)
	v_mfma_f32_16x16x32_bf16 v[4:7], v[4:7], v[0:3], 0
	s_waitcnt lgkmcnt(1)
	v_mfma_f32_16x16x32_bf16 v[4:7], v[8:11], v[80:83], v[4:7]
	ds_read_b128 v[8:11], v101 offset:52416
	s_waitcnt lgkmcnt(1)
	v_mfma_f32_16x16x32_bf16 v[4:7], v[12:15], v[84:87], v[4:7]
	s_waitcnt lgkmcnt(0)
	v_mfma_f32_16x16x32_bf16 v[12:15], v[8:11], v[88:91], v[4:7]
	s_nop 5
	ds_read_b128 v[4:7], v101 offset:56576
	ds_read_b128 v[8:11], v101 offset:56640
	ds_read_b128 v[92:95], v101 offset:56704
	s_waitcnt lgkmcnt(2)
	v_mfma_f32_16x16x32_bf16 v[4:7], v[4:7], v[0:3], 0
	s_waitcnt lgkmcnt(1)
	v_mfma_f32_16x16x32_bf16 v[4:7], v[8:11], v[80:83], v[4:7]
	ds_read_b128 v[8:11], v101 offset:56768
	s_waitcnt lgkmcnt(1)
	v_mfma_f32_16x16x32_bf16 v[4:7], v[92:95], v[84:87], v[4:7]
	s_waitcnt lgkmcnt(0)
	v_mfma_f32_16x16x32_bf16 v[8:11], v[8:11], v[88:91], v[4:7]
	s_nop 5
	ds_read_b128 v[4:7], v101 offset:60928
	ds_read_b128 v[92:95], v101 offset:60992
	ds_read_b128 v[96:99], v101 offset:61056
	s_waitcnt lgkmcnt(2)
	v_mfma_f32_16x16x32_bf16 v[4:7], v[4:7], v[0:3], 0
	s_waitcnt lgkmcnt(1)
	v_mfma_f32_16x16x32_bf16 v[4:7], v[92:95], v[80:83], v[4:7]
	ds_read_b128 v[92:95], v101 offset:61120
	s_waitcnt lgkmcnt(1)
	v_mfma_f32_16x16x32_bf16 v[4:7], v[96:99], v[84:87], v[4:7]
	s_waitcnt lgkmcnt(0)
	v_mfma_f32_16x16x32_bf16 v[4:7], v[92:95], v[88:91], v[4:7]
	v_or_b32_e32 v68, 0xf0, v68
	v_mad_u64_u32 v[100:101], s[8:9], v68, s70, v[100:101]
	ds_read_b128 v[92:95], v100
	ds_read_b128 v[96:99], v100 offset:64
	s_waitcnt lgkmcnt(1)
	v_mfma_f32_16x16x32_bf16 v[0:3], v[92:95], v[0:3], 0
	ds_read_b128 v[92:95], v100 offset:128
	s_waitcnt lgkmcnt(1)
	v_mfma_f32_16x16x32_bf16 v[0:3], v[96:99], v[80:83], v[0:3]
	ds_read_b128 v[80:83], v100 offset:192
	s_waitcnt lgkmcnt(1)
	v_mfma_f32_16x16x32_bf16 v[0:3], v[92:95], v[84:87], v[0:3]
	s_waitcnt lgkmcnt(0)
	v_mfma_f32_16x16x32_bf16 v[0:3], v[80:83], v[88:91], v[0:3]
	v_max_f32_e32 v68, v63, v63
	v_max_f32_e32 v80, v62, v62
	v_max_f32_e32 v68, v80, v68
	v_max_f32_e32 v80, v59, v59
	v_max_f32_e32 v81, v58, v58
	v_max_f32_e32 v80, v81, v80
	v_max3_f32 v68, v60, v61, v68
	v_max3_f32 v80, v56, v57, v80
	s_mov_b32 s7, 0xf149f2ca
	v_max3_f32 v68, v68, s7, v80
	v_max_f32_e32 v80, v55, v55
	v_max_f32_e32 v81, v54, v54
	v_max_f32_e32 v80, v81, v80
	v_max_f32_e32 v81, v51, v51
	v_max_f32_e32 v82, v50, v50
	v_max_f32_e32 v81, v82, v81
	v_max3_f32 v80, v52, v53, v80
	v_max3_f32 v81, v48, v49, v81
	v_max3_f32 v68, v68, v80, v81
	v_max_f32_e32 v80, v47, v47
	v_max_f32_e32 v81, v46, v46
	v_max_f32_e32 v80, v81, v80
	v_max_f32_e32 v81, v43, v43
	v_max_f32_e32 v82, v42, v42
	v_max_f32_e32 v81, v82, v81
	v_max3_f32 v80, v44, v45, v80
	v_max3_f32 v81, v40, v41, v81
	v_max3_f32 v68, v68, v80, v81
	v_max_f32_e32 v80, v39, v39
	v_max_f32_e32 v81, v38, v38
	v_max_f32_e32 v80, v81, v80
	v_max_f32_e32 v81, v35, v35
	v_max_f32_e32 v82, v34, v34
	v_max_f32_e32 v81, v82, v81
	v_max3_f32 v80, v36, v37, v80
	v_max3_f32 v81, v32, v33, v81
	v_max3_f32 v68, v68, v80, v81
	v_max_f32_e32 v80, v31, v31
	v_max_f32_e32 v81, v30, v30
	v_max_f32_e32 v80, v81, v80
	v_max_f32_e32 v81, v27, v27
	v_max_f32_e32 v82, v26, v26
	v_max_f32_e32 v81, v82, v81
	v_max3_f32 v80, v28, v29, v80
	v_max3_f32 v81, v24, v25, v81
	v_max3_f32 v68, v68, v80, v81
	v_max_f32_e32 v80, v23, v23
	v_max_f32_e32 v81, v22, v22
	v_max_f32_e32 v80, v81, v80
	v_max_f32_e32 v81, v19, v19
	v_max_f32_e32 v82, v18, v18
	v_max_f32_e32 v81, v82, v81
	v_max3_f32 v80, v20, v21, v80
	v_max3_f32 v81, v16, v17, v81
	v_max3_f32 v68, v68, v80, v81
	v_max_f32_e32 v80, v15, v15
	v_max_f32_e32 v81, v14, v14
	v_max_f32_e32 v80, v81, v80
	v_max_f32_e32 v81, v11, v11
	v_max_f32_e32 v82, v10, v10
	v_max_f32_e32 v81, v82, v81
	v_max3_f32 v80, v12, v13, v80
	v_max3_f32 v81, v8, v9, v81
	v_max3_f32 v68, v68, v80, v81
	v_max_f32_e32 v80, v7, v7
	v_max_f32_e32 v81, v6, v6
	v_max_f32_e32 v80, v81, v80
	v_max_f32_e32 v81, v3, v3
	v_max_f32_e32 v82, v2, v2
	v_max_f32_e32 v81, v82, v81
	v_max3_f32 v80, v4, v5, v80
	v_max3_f32 v81, v0, v1, v81
	v_cmp_lt_i32_e32 vcc, v72, v73
	v_max3_f32 v68, v68, v80, v81
	s_nop 0
	v_cndmask_b32_e32 v80, v71, v72, vcc
	v_lshlrev_b32_e32 v108, 2, v80
	ds_bpermute_b32 v80, v108, v68
	v_cmp_lt_i32_e32 vcc, v74, v73
	s_waitcnt lgkmcnt(0)
	v_max_f32_e32 v80, v80, v80
	v_max_f32_e32 v68, v68, v80
	v_cndmask_b32_e32 v80, v71, v74, vcc
	v_lshlrev_b32_e32 v109, 2, v80
	ds_bpermute_b32 v80, v109, v68
	s_waitcnt lgkmcnt(0)
	v_max_f32_e32 v80, v80, v80
	v_max_f32_e32 v68, v68, v80
	v_sub_f32_e32 v60, v60, v68
	v_sub_f32_e32 v62, v62, v68
	v_mul_f32_e32 v60, 0x3db504f3, v60
	v_sub_f32_e32 v61, v61, v68
	v_mul_f32_e32 v62, 0x3db504f3, v62
	v_mul_f32_e32 v60, 0x3fb8aa3b, v60
	v_mul_f32_e32 v61, 0x3db504f3, v61
	v_mul_f32_e32 v62, 0x3fb8aa3b, v62
	v_exp_f32_e32 v60, v60
	v_mul_f32_e32 v61, 0x3fb8aa3b, v61
	v_exp_f32_e32 v81, v62
	v_sub_f32_e32 v62, v63, v68
	v_exp_f32_e32 v61, v61
	v_mul_f32_e32 v62, 0x3db504f3, v62
	v_sub_f32_e32 v56, v56, v68
	v_mul_f32_e32 v62, 0x3fb8aa3b, v62
	v_mul_f32_e32 v56, 0x3db504f3, v56
	v_sub_f32_e32 v57, v57, v68
	v_sub_f32_e32 v53, v53, v68
	v_exp_f32_e32 v63, v62
	v_mul_f32_e32 v56, 0x3fb8aa3b, v56
	v_mul_f32_e32 v57, 0x3db504f3, v57
	v_sub_f32_e32 v58, v58, v68
	v_mul_f32_e32 v53, 0x3db504f3, v53
	v_add_f32_e32 v80, 0, v60
	v_exp_f32_e32 v56, v56
	v_mul_f32_e32 v57, 0x3fb8aa3b, v57
	v_mul_f32_e32 v58, 0x3db504f3, v58
	v_sub_f32_e32 v59, v59, v68
	v_mul_f32_e32 v53, 0x3fb8aa3b, v53
	v_add_f32_e32 v62, v61, v80
	v_exp_f32_e32 v57, v57
	v_mul_f32_e32 v58, 0x3fb8aa3b, v58
	v_mul_f32_e32 v59, 0x3db504f3, v59
	v_sub_f32_e32 v52, v52, v68
	v_exp_f32_e32 v111, v53
	v_sub_f32_e32 v53, v54, v68
	v_add_f32_e32 v62, v81, v62
	v_exp_f32_e32 v58, v58
	v_mul_f32_e32 v59, 0x3fb8aa3b, v59
	v_mul_f32_e32 v52, 0x3db504f3, v52
	v_mul_f32_e32 v53, 0x3db504f3, v53
	v_sub_f32_e32 v49, v49, v68
	v_add_f32_e32 v62, v63, v62
	v_exp_f32_e32 v59, v59
	v_mul_f32_e32 v52, 0x3fb8aa3b, v52
	v_mul_f32_e32 v53, 0x3fb8aa3b, v53
	v_mul_f32_e32 v49, 0x3db504f3, v49
	v_add_f32_e32 v62, v56, v62
	v_exp_f32_e32 v110, v52
	v_exp_f32_e32 v112, v53
	v_sub_f32_e32 v53, v55, v68
	v_mul_f32_e32 v49, 0x3fb8aa3b, v49
	v_add_f32_e32 v52, v57, v62
	v_mul_f32_e32 v53, 0x3db504f3, v53
	v_sub_f32_e32 v48, v48, v68
	v_exp_f32_e32 v115, v49
	v_sub_f32_e32 v49, v50, v68
	v_add_f32_e32 v52, v58, v52
	v_mul_f32_e32 v53, 0x3fb8aa3b, v53
	v_mul_f32_e32 v48, 0x3db504f3, v48
	v_mul_f32_e32 v49, 0x3db504f3, v49
	v_sub_f32_e32 v45, v45, v68
	v_add_f32_e32 v52, v59, v52
	v_exp_f32_e32 v113, v53
	v_mul_f32_e32 v48, 0x3fb8aa3b, v48
	v_mul_f32_e32 v49, 0x3fb8aa3b, v49
	v_mul_f32_e32 v45, 0x3db504f3, v45
	v_add_f32_e32 v52, v110, v52
	v_exp_f32_e32 v114, v48
	v_exp_f32_e32 v116, v49
	v_sub_f32_e32 v49, v51, v68
	v_mul_f32_e32 v45, 0x3fb8aa3b, v45
	v_add_f32_e32 v48, v111, v52
	v_mul_f32_e32 v49, 0x3db504f3, v49
	v_sub_f32_e32 v44, v44, v68
	v_exp_f32_e32 v53, v45
	v_sub_f32_e32 v45, v46, v68
	v_add_f32_e32 v48, v112, v48
	v_mul_f32_e32 v49, 0x3fb8aa3b, v49
	v_mul_f32_e32 v44, 0x3db504f3, v44
	v_mul_f32_e32 v45, 0x3db504f3, v45
	v_sub_f32_e32 v41, v41, v68
	v_add_f32_e32 v48, v113, v48
	v_exp_f32_e32 v117, v49
	v_mul_f32_e32 v44, 0x3fb8aa3b, v44
	v_mul_f32_e32 v45, 0x3fb8aa3b, v45
	v_mul_f32_e32 v41, 0x3db504f3, v41
	v_add_f32_e32 v48, v114, v48
	v_exp_f32_e32 v51, v44
	v_exp_f32_e32 v52, v45
	v_sub_f32_e32 v45, v47, v68
	v_mul_f32_e32 v41, 0x3fb8aa3b, v41
	v_add_f32_e32 v44, v115, v48
	v_mul_f32_e32 v45, 0x3db504f3, v45
	v_sub_f32_e32 v40, v40, v68
	v_exp_f32_e32 v120, v41
	v_sub_f32_e32 v41, v42, v68
	v_add_f32_e32 v44, v116, v44
	v_mul_f32_e32 v45, 0x3fb8aa3b, v45
	v_mul_f32_e32 v40, 0x3db504f3, v40
	v_mul_f32_e32 v41, 0x3db504f3, v41
	v_sub_f32_e32 v37, v37, v68
	v_add_f32_e32 v44, v117, v44
	v_exp_f32_e32 v118, v45
	v_mul_f32_e32 v40, 0x3fb8aa3b, v40
	v_mul_f32_e32 v41, 0x3fb8aa3b, v41
	v_mul_f32_e32 v37, 0x3db504f3, v37
	v_add_f32_e32 v44, v51, v44
	v_exp_f32_e32 v119, v40
	v_exp_f32_e32 v121, v41
	v_sub_f32_e32 v41, v43, v68
	v_mul_f32_e32 v37, 0x3fb8aa3b, v37
	v_add_f32_e32 v40, v53, v44
	v_mul_f32_e32 v41, 0x3db504f3, v41
	v_sub_f32_e32 v36, v36, v68
	v_exp_f32_e32 v45, v37
	v_sub_f32_e32 v37, v38, v68
	v_add_f32_e32 v40, v52, v40
	v_mul_f32_e32 v41, 0x3fb8aa3b, v41
	v_mul_f32_e32 v36, 0x3db504f3, v36
	v_mul_f32_e32 v37, 0x3db504f3, v37
	v_sub_f32_e32 v33, v33, v68
	v_add_f32_e32 v40, v118, v40
	v_exp_f32_e32 v122, v41
	v_mul_f32_e32 v36, 0x3fb8aa3b, v36
	v_mul_f32_e32 v37, 0x3fb8aa3b, v37
	v_mul_f32_e32 v33, 0x3db504f3, v33
	v_add_f32_e32 v40, v119, v40
	v_exp_f32_e32 v43, v36
	v_exp_f32_e32 v44, v37
	v_sub_f32_e32 v37, v39, v68
	v_mul_f32_e32 v33, 0x3fb8aa3b, v33
	v_add_f32_e32 v36, v120, v40
	v_mul_f32_e32 v37, 0x3db504f3, v37
	v_sub_f32_e32 v32, v32, v68
	v_exp_f32_e32 v49, v33
	v_sub_f32_e32 v33, v34, v68
	v_add_f32_e32 v36, v121, v36
	v_mul_f32_e32 v37, 0x3fb8aa3b, v37
	v_mul_f32_e32 v32, 0x3db504f3, v32
	v_mul_f32_e32 v33, 0x3db504f3, v33
	v_sub_f32_e32 v29, v29, v68
	v_add_f32_e32 v36, v122, v36
	v_exp_f32_e32 v47, v37
	v_mul_f32_e32 v32, 0x3fb8aa3b, v32
	v_mul_f32_e32 v33, 0x3fb8aa3b, v33
	v_mul_f32_e32 v29, 0x3db504f3, v29
	v_add_f32_e32 v36, v43, v36
	v_exp_f32_e32 v46, v32
	v_exp_f32_e32 v48, v33
	v_sub_f32_e32 v33, v35, v68
	v_mul_f32_e32 v29, 0x3fb8aa3b, v29
	v_add_f32_e32 v32, v45, v36
	v_mul_f32_e32 v33, 0x3db504f3, v33
	v_sub_f32_e32 v28, v28, v68
	v_exp_f32_e32 v38, v29
	v_sub_f32_e32 v29, v30, v68
	v_add_f32_e32 v32, v44, v32
	v_mul_f32_e32 v33, 0x3fb8aa3b, v33
	v_mul_f32_e32 v28, 0x3db504f3, v28
	v_mul_f32_e32 v29, 0x3db504f3, v29
	v_add_f32_e32 v32, v47, v32
	v_exp_f32_e32 v50, v33
	v_mul_f32_e32 v28, 0x3fb8aa3b, v28
	v_mul_f32_e32 v29, 0x3fb8aa3b, v29
	v_add_f32_e32 v32, v46, v32
	v_exp_f32_e32 v36, v28
	v_exp_f32_e32 v37, v29
	v_sub_f32_e32 v29, v31, v68
	v_add_f32_e32 v28, v49, v32
	v_mul_f32_e32 v29, 0x3db504f3, v29
	v_sub_f32_e32 v24, v24, v68
	v_add_f32_e32 v28, v48, v28
	v_mul_f32_e32 v29, 0x3fb8aa3b, v29
	v_mul_f32_e32 v24, 0x3db504f3, v24
	v_add_f32_e32 v28, v50, v28
	v_exp_f32_e32 v39, v29
	v_mul_f32_e32 v24, 0x3fb8aa3b, v24
	v_add_f32_e32 v28, v36, v28
	v_exp_f32_e32 v31, v24
	v_add_f32_e32 v24, v38, v28
	v_add_f32_e32 v24, v37, v24
	v_add_f32_e32 v24, v39, v24
	v_add_f32_e32 v28, v31, v24
	v_sub_f32_e32 v24, v25, v68
	v_mul_f32_e32 v24, 0x3db504f3, v24
	v_mul_f32_e32 v24, 0x3fb8aa3b, v24
	v_exp_f32_e32 v41, v24
	v_sub_f32_e32 v24, v26, v68
	v_mul_f32_e32 v24, 0x3db504f3, v24
	v_sub_f32_e32 v21, v21, v68
	v_mul_f32_e32 v24, 0x3fb8aa3b, v24
	v_mul_f32_e32 v21, 0x3db504f3, v21
	v_exp_f32_e32 v40, v24
	v_sub_f32_e32 v24, v27, v68
	v_mul_f32_e32 v21, 0x3fb8aa3b, v21
	v_mul_f32_e32 v24, 0x3db504f3, v24
	v_sub_f32_e32 v20, v20, v68
	v_exp_f32_e32 v25, v21
	v_sub_f32_e32 v21, v22, v68
	v_mul_f32_e32 v24, 0x3fb8aa3b, v24
	v_mul_f32_e32 v20, 0x3db504f3, v20
	v_mul_f32_e32 v21, 0x3db504f3, v21
	v_sub_f32_e32 v17, v17, v68
	v_exp_f32_e32 v42, v24
	v_mul_f32_e32 v20, 0x3fb8aa3b, v20
	v_mul_f32_e32 v21, 0x3fb8aa3b, v21
	v_mul_f32_e32 v17, 0x3db504f3, v17
	v_exp_f32_e32 v24, v20
	v_exp_f32_e32 v22, v21
	v_sub_f32_e32 v21, v23, v68
	v_mul_f32_e32 v17, 0x3fb8aa3b, v17
	v_add_f32_e32 v20, v41, v28
	v_mul_f32_e32 v21, 0x3db504f3, v21
	v_sub_f32_e32 v16, v16, v68
	v_exp_f32_e32 v29, v17
	v_sub_f32_e32 v17, v18, v68
	v_add_f32_e32 v20, v40, v20
	v_mul_f32_e32 v21, 0x3fb8aa3b, v21
	v_mul_f32_e32 v16, 0x3db504f3, v16
	v_mul_f32_e32 v17, 0x3db504f3, v17
	v_add_f32_e32 v20, v42, v20
	v_exp_f32_e32 v26, v21
	v_mul_f32_e32 v16, 0x3fb8aa3b, v16
	v_mul_f32_e32 v17, 0x3fb8aa3b, v17
	v_add_f32_e32 v20, v24, v20
	v_exp_f32_e32 v23, v16
	v_exp_f32_e32 v28, v17
	v_sub_f32_e32 v17, v19, v68
	v_add_f32_e32 v16, v25, v20
	v_mul_f32_e32 v17, 0x3db504f3, v17
	v_sub_f32_e32 v12, v12, v68
	v_add_f32_e32 v16, v22, v16
	v_mul_f32_e32 v17, 0x3fb8aa3b, v17
	v_mul_f32_e32 v12, 0x3db504f3, v12
	v_sub_f32_e32 v13, v13, v68
	v_add_f32_e32 v16, v26, v16
	v_exp_f32_e32 v30, v17
	v_mul_f32_e32 v12, 0x3fb8aa3b, v12
	v_mul_f32_e32 v13, 0x3db504f3, v13
	v_add_f32_e32 v16, v23, v16
	v_exp_f32_e32 v12, v12
	v_mul_f32_e32 v13, 0x3fb8aa3b, v13
	v_add_f32_e32 v16, v29, v16
	v_exp_f32_e32 v17, v13
	v_sub_f32_e32 v13, v14, v68
	v_add_f32_e32 v16, v28, v16
	v_mul_f32_e32 v13, 0x3db504f3, v13
	v_sub_f32_e32 v9, v9, v68
	v_add_f32_e32 v16, v30, v16
	v_mul_f32_e32 v13, 0x3fb8aa3b, v13
	v_mul_f32_e32 v9, 0x3db504f3, v9
	v_add_f32_e32 v19, v12, v16
	v_exp_f32_e32 v16, v13
	v_sub_f32_e32 v13, v15, v68
	v_mul_f32_e32 v9, 0x3fb8aa3b, v9
	v_mul_f32_e32 v13, 0x3db504f3, v13
	v_sub_f32_e32 v8, v8, v68
	v_exp_f32_e32 v20, v9
	v_sub_f32_e32 v9, v10, v68
	v_mul_f32_e32 v13, 0x3fb8aa3b, v13
	v_mul_f32_e32 v8, 0x3db504f3, v8
	v_mul_f32_e32 v9, 0x3db504f3, v9
	v_exp_f32_e32 v18, v13
	v_mul_f32_e32 v8, 0x3fb8aa3b, v8
	v_mul_f32_e32 v9, 0x3fb8aa3b, v9
	v_exp_f32_e32 v15, v8
	v_add_f32_e32 v8, v17, v19
	v_exp_f32_e32 v19, v9
	v_sub_f32_e32 v9, v11, v68
	v_mul_f32_e32 v9, 0x3db504f3, v9
	v_sub_f32_e32 v4, v4, v68
	v_add_f32_e32 v8, v16, v8
	v_mul_f32_e32 v9, 0x3fb8aa3b, v9
	v_mul_f32_e32 v4, 0x3db504f3, v4
	v_add_f32_e32 v8, v18, v8
	v_exp_f32_e32 v21, v9
	v_mul_f32_e32 v4, 0x3fb8aa3b, v4
	v_add_f32_e32 v8, v15, v8
	v_exp_f32_e32 v4, v4
	v_add_f32_e32 v8, v20, v8
	v_sub_f32_e32 v5, v5, v68
	v_add_f32_e32 v8, v19, v8
	v_mul_f32_e32 v5, 0x3db504f3, v5
	v_add_f32_e32 v8, v21, v8
	v_mul_f32_e32 v5, 0x3fb8aa3b, v5
	v_add_f32_e32 v9, v4, v8
	v_exp_f32_e32 v8, v5
	v_sub_f32_e32 v5, v6, v68
	v_mul_f32_e32 v5, 0x3db504f3, v5
	v_sub_f32_e32 v6, v7, v68
	v_mul_f32_e32 v5, 0x3fb8aa3b, v5
	v_mul_f32_e32 v6, 0x3db504f3, v6
	v_sub_f32_e32 v0, v0, v68
	v_exp_f32_e32 v5, v5
	v_mul_f32_e32 v6, 0x3fb8aa3b, v6
	v_mul_f32_e32 v0, 0x3db504f3, v0
	v_exp_f32_e32 v7, v6
	v_mul_f32_e32 v0, 0x3fb8aa3b, v0
	v_exp_f32_e32 v6, v0
	v_add_f32_e32 v0, v8, v9
	v_add_f32_e32 v0, v5, v0
	v_add_f32_e32 v0, v7, v0
	v_add_f32_e32 v104, v6, v0
	v_sub_f32_e32 v0, v1, v68
	v_mul_f32_e32 v0, 0x3db504f3, v0
	v_mul_f32_e32 v0, 0x3fb8aa3b, v0
	v_exp_f32_e32 v10, v0
	v_sub_f32_e32 v0, v2, v68
	v_mul_f32_e32 v0, 0x3db504f3, v0
	v_mul_f32_e32 v0, 0x3fb8aa3b, v0
	v_exp_f32_e32 v9, v0
	v_sub_f32_e32 v27, v3, v68
	v_bfe_u32 v0, v59, 16, 1
	v_bfe_u32 v1, v57, 16, 1
	v_bfe_u32 v2, v63, 16, 1
	v_bfe_u32 v3, v61, 16, 1
	v_lshl_add_u32 v62, v67, 3, s68
	v_add3_u32 v13, v61, v3, s73
	v_add3_u32 v54, v63, v2, s73
	v_add3_u32 v11, v57, v1, s73
	v_add3_u32 v32, v59, v0, s73
	v_bfe_u32 v0, v60, 16, 1
	v_bfe_u32 v1, v81, 16, 1
	v_bfe_u32 v2, v56, 16, 1
	v_bfe_u32 v3, v58, 16, 1
	v_add3_u32 v3, v58, v3, s73
	v_add3_u32 v2, v56, v2, s73
	v_add3_u32 v1, v81, v1, s73
	v_add3_u32 v0, v60, v0, s73
	v_mad_u32_u24 v14, v64, s69, v62
	v_and_b32_e32 v140, 8, v64
	v_add_u32_e32 v14, v14, v140
	v_lshrrev_b32_e32 v58, 16, v0
	v_lshrrev_b32_e32 v55, 16, v1
	v_lshrrev_b32_e32 v33, 16, v2
	v_lshrrev_b32_e32 v34, 16, v3
	ds_read2_b64 v[0:3], v14 offset1:4
	v_and_or_b32 v56, v11, s74, v33
	v_add_u32_e32 v11, 0x2010, v14
	v_and_or_b32 v57, v32, s74, v34
	ds_read2_b64 v[32:35], v11 offset0:32 offset1:36
	v_and_or_b32 v55, v54, s74, v55
	v_and_or_b32 v54, v13, s74, v58
	v_add_u32_e32 v13, 0x4020, v14
	ds_read2_b64 v[58:61], v13 offset0:64 offset1:68
	s_waitcnt lgkmcnt(2)
	v_mfma_f32_16x16x32_bf16 v[80:83], v[0:3], v[54:57], 0
	v_mul_f32_e32 v2, 0x3db504f3, v27
	v_mul_f32_e32 v2, 0x3fb8aa3b, v2
	v_exp_f32_e32 v27, v2
	v_add_f32_e32 v2, v10, v104
	v_add_f32_e32 v2, v9, v2
	s_waitcnt lgkmcnt(1)
	v_mfma_f32_16x16x32_bf16 v[88:91], v[32:35], v[54:57], 0
	v_add_f32_e32 v32, v27, v2
	v_mad_u64_u32 v[2:3], s[8:9], v79, s69, v[62:63]
	v_mad_u64_u32 v[0:1], s[8:9], v69, s69, v[62:63]
	v_and_b32_e32 v140, 0x78, v79
	v_and_b32_e32 v141, 0x78, v69
	v_add_u32_e32 v2, v2, v140
	v_add_u32_e32 v0, v0, v141
	ds_bpermute_b32 v3, v108, v32
	v_add_u32_e32 v1, 0x8040, v14
	v_add_u32_e32 v34, 0xa050, v14
	v_add_u32_e32 v35, 0xc060, v14
	ds_read2_b64 v[84:87], v0 offset1:4
	ds_read2_b64 v[92:95], v1 offset0:128 offset1:132
	ds_read2_b64 v[96:99], v34 offset0:160 offset1:164
	ds_read2_b64 v[100:103], v35 offset0:192 offset1:196
	ds_read2_b64 v[104:107], v2 offset1:4
	s_waitcnt lgkmcnt(5)
	v_add_f32_e32 v32, v32, v3
	ds_bpermute_b32 v33, v109, v32
	v_mfma_f32_16x16x32_bf16 v[58:61], v[58:61], v[54:57], 0
	s_waitcnt lgkmcnt(5)
	v_mfma_f32_16x16x32_bf16 v[84:87], v[84:87], v[54:57], 0
	s_waitcnt lgkmcnt(4)
	v_mfma_f32_16x16x32_bf16 v[92:95], v[92:95], v[54:57], 0
	s_waitcnt lgkmcnt(3)
	v_mfma_f32_16x16x32_bf16 v[96:99], v[96:99], v[54:57], 0
	s_waitcnt lgkmcnt(2)
	v_mfma_f32_16x16x32_bf16 v[100:103], v[100:103], v[54:57], 0
	s_waitcnt lgkmcnt(1)
	v_mfma_f32_16x16x32_bf16 v[54:57], v[104:107], v[54:57], 0
	v_bfe_u32 v104, v114, 16, 1
	v_bfe_u32 v105, v116, 16, 1
	v_add3_u32 v108, v116, v105, s73
	v_add3_u32 v109, v114, v104, s73
	ds_read2_b64 v[104:107], v14 offset0:8 offset1:12
	v_bfe_u32 v69, v110, 16, 1
	v_bfe_u32 v3, v117, 16, 1
	v_bfe_u32 v62, v115, 16, 1
	v_bfe_u32 v68, v111, 16, 1
	v_add3_u32 v69, v110, v69, s73
	v_add3_u32 v68, v111, v68, s73
	v_add3_u32 v62, v115, v62, s73
	v_add3_u32 v3, v117, v3, s73
	v_lshrrev_b32_e32 v69, 16, v69
	v_lshrrev_b32_e32 v109, 16, v109
	v_lshrrev_b32_e32 v108, 16, v108
	v_and_or_b32 v111, v3, s74, v108
	v_and_or_b32 v110, v62, s74, v109
	v_cvt_pk_bf16_f32 v109, v112, v113
	v_and_or_b32 v108, v68, s74, v69
	s_waitcnt lgkmcnt(0)
	s_nop 0
	v_mfma_f32_16x16x32_bf16 v[80:83], v[104:107], v[108:111], v[80:83]
	ds_read2_b64 v[104:107], v11 offset0:40 offset1:44
	s_waitcnt lgkmcnt(0)
	v_mfma_f32_16x16x32_bf16 v[88:91], v[104:107], v[108:111], v[88:91]
	ds_read2_b64 v[104:107], v13 offset0:72 offset1:76
	s_waitcnt lgkmcnt(0)
	v_mfma_f32_16x16x32_bf16 v[58:61], v[104:107], v[108:111], v[58:61]
	ds_read2_b64 v[104:107], v0 offset0:8 offset1:12
	s_waitcnt lgkmcnt(0)
	v_mfma_f32_16x16x32_bf16 v[84:87], v[104:107], v[108:111], v[84:87]
	ds_read2_b64 v[104:107], v1 offset0:136 offset1:140
	s_waitcnt lgkmcnt(0)
	v_mfma_f32_16x16x32_bf16 v[92:95], v[104:107], v[108:111], v[92:95]
	ds_read2_b64 v[104:107], v34 offset0:168 offset1:172
	s_waitcnt lgkmcnt(0)
	v_mfma_f32_16x16x32_bf16 v[96:99], v[104:107], v[108:111], v[96:99]
	ds_read2_b64 v[104:107], v35 offset0:200 offset1:204
	s_waitcnt lgkmcnt(0)
	v_mfma_f32_16x16x32_bf16 v[100:103], v[104:107], v[108:111], v[100:103]
	ds_read2_b64 v[104:107], v2 offset0:8 offset1:12
	s_waitcnt lgkmcnt(0)
	v_mfma_f32_16x16x32_bf16 v[54:57], v[104:107], v[108:111], v[54:57]
	v_bfe_u32 v104, v121, 16, 1
	v_add3_u32 v108, v121, v104, s73
	ds_read2_b64 v[104:107], v14 offset0:16 offset1:20
	v_bfe_u32 v68, v53, 16, 1
	v_add3_u32 v53, v53, v68, s73
	v_bfe_u32 v68, v51, 16, 1
	v_bfe_u32 v69, v52, 16, 1
	v_bfe_u32 v79, v119, 16, 1
	v_bfe_u32 v3, v122, 16, 1
	v_bfe_u32 v62, v120, 16, 1
	v_bfe_u32 v63, v118, 16, 1
	v_add3_u32 v79, v119, v79, s73
	v_add3_u32 v52, v52, v69, s73
	v_add3_u32 v51, v51, v68, s73
	v_add3_u32 v63, v118, v63, s73
	v_add3_u32 v62, v120, v62, s73
	v_add3_u32 v3, v122, v3, s73
	v_lshrrev_b32_e32 v51, 16, v51
	v_lshrrev_b32_e32 v52, 16, v52
	v_lshrrev_b32_e32 v68, 16, v79
	v_lshrrev_b32_e32 v69, 16, v108
	v_and_or_b32 v111, v3, s74, v69
	v_and_or_b32 v110, v62, s74, v68
	v_and_or_b32 v109, v63, s74, v52
	v_and_or_b32 v108, v53, s74, v51
	s_waitcnt lgkmcnt(0)
	s_nop 0
	v_mfma_f32_16x16x32_bf16 v[80:83], v[104:107], v[108:111], v[80:83]
	ds_read2_b64 v[104:107], v11 offset0:48 offset1:52
	s_waitcnt lgkmcnt(0)
	v_mfma_f32_16x16x32_bf16 v[88:91], v[104:107], v[108:111], v[88:91]
	ds_read2_b64 v[104:107], v13 offset0:80 offset1:84
	s_waitcnt lgkmcnt(0)
	v_mfma_f32_16x16x32_bf16 v[58:61], v[104:107], v[108:111], v[58:61]
	ds_read2_b64 v[104:107], v0 offset0:16 offset1:20
	s_waitcnt lgkmcnt(0)
	v_mfma_f32_16x16x32_bf16 v[84:87], v[104:107], v[108:111], v[84:87]
	ds_read2_b64 v[104:107], v1 offset0:144 offset1:148
	s_waitcnt lgkmcnt(0)
	v_mfma_f32_16x16x32_bf16 v[92:95], v[104:107], v[108:111], v[92:95]
	ds_read2_b64 v[104:107], v34 offset0:176 offset1:180
	s_waitcnt lgkmcnt(0)
	v_mfma_f32_16x16x32_bf16 v[96:99], v[104:107], v[108:111], v[96:99]
	ds_read2_b64 v[104:107], v35 offset0:208 offset1:212
	s_waitcnt lgkmcnt(0)
	v_mfma_f32_16x16x32_bf16 v[100:103], v[104:107], v[108:111], v[100:103]
	ds_read2_b64 v[104:107], v2 offset0:16 offset1:20
	s_waitcnt lgkmcnt(0)
	v_mfma_f32_16x16x32_bf16 v[52:55], v[104:107], v[108:111], v[54:57]
	v_bfe_u32 v3, v50, 16, 1
	v_bfe_u32 v51, v49, 16, 1
	s_nop 0
	v_bfe_u32 v56, v47, 16, 1
	v_bfe_u32 v57, v45, 16, 1
	v_add3_u32 v57, v45, v57, s73
	v_add3_u32 v56, v47, v56, s73
	v_add3_u32 v49, v49, v51, s73
	v_add3_u32 v3, v50, v3, s73
	v_bfe_u32 v45, v43, 16, 1
	v_bfe_u32 v47, v44, 16, 1
	v_bfe_u32 v50, v46, 16, 1
	v_bfe_u32 v51, v48, 16, 1
	v_add3_u32 v48, v48, v51, s73
	v_add3_u32 v50, v46, v50, s73
	v_add3_u32 v51, v44, v47, s73
	v_add3_u32 v43, v43, v45, s73
	ds_read2_b64 v[44:47], v14 offset0:24 offset1:28
	v_lshrrev_b32_e32 v43, 16, v43
	v_lshrrev_b32_e32 v62, 16, v51
	v_lshrrev_b32_e32 v50, 16, v50
	v_lshrrev_b32_e32 v48, 16, v48
	v_and_or_b32 v51, v3, s74, v48
	v_and_or_b32 v50, v49, s74, v50
	v_and_or_b32 v49, v56, s74, v62
	v_and_or_b32 v48, v57, s74, v43
	s_waitcnt lgkmcnt(0)
	s_nop 0
	v_mfma_f32_16x16x32_bf16 v[44:47], v[44:47], v[48:51], v[80:83]
	s_nop 2
	ds_read2_b64 v[80:83], v11 offset0:56 offset1:60
	s_waitcnt lgkmcnt(0)
	v_mfma_f32_16x16x32_bf16 v[80:83], v[80:83], v[48:51], v[88:91]
	s_nop 2
	ds_read2_b64 v[88:91], v13 offset0:88 offset1:92
	s_waitcnt lgkmcnt(0)
	v_mfma_f32_16x16x32_bf16 v[56:59], v[88:91], v[48:51], v[58:61]
	s_nop 2
	ds_read2_b64 v[60:63], v0 offset0:24 offset1:28
	ds_read2_b64 v[88:91], v34 offset0:184 offset1:188
	s_waitcnt lgkmcnt(1)
	v_mfma_f32_16x16x32_bf16 v[60:63], v[60:63], v[48:51], v[84:87]
	s_nop 2
	ds_read2_b64 v[84:87], v1 offset0:152 offset1:156
	s_waitcnt lgkmcnt(0)
	v_mfma_f32_16x16x32_bf16 v[84:87], v[84:87], v[48:51], v[92:95]
	s_nop 2
	ds_read2_b64 v[92:95], v35 offset0:216 offset1:220
	v_mfma_f32_16x16x32_bf16 v[88:91], v[88:91], v[48:51], v[96:99]
	s_nop 2
	ds_read2_b64 v[96:99], v2 offset0:24 offset1:28
	s_waitcnt lgkmcnt(1)
	v_mfma_f32_16x16x32_bf16 v[92:95], v[92:95], v[48:51], v[100:103]
	s_waitcnt lgkmcnt(0)
	v_mfma_f32_16x16x32_bf16 v[48:51], v[96:99], v[48:51], v[52:55]
	v_bfe_u32 v3, v42, 16, 1
	v_bfe_u32 v43, v41, 16, 1
	s_nop 0
	v_bfe_u32 v52, v39, 16, 1
	v_bfe_u32 v53, v38, 16, 1
	v_add3_u32 v53, v38, v53, s73
	v_add3_u32 v52, v39, v52, s73
	v_add3_u32 v41, v41, v43, s73
	v_add3_u32 v3, v42, v3, s73
	v_bfe_u32 v38, v36, 16, 1
	v_bfe_u32 v39, v37, 16, 1
	v_bfe_u32 v42, v31, 16, 1
	v_bfe_u32 v43, v40, 16, 1
	v_add3_u32 v40, v40, v43, s73
	v_add3_u32 v31, v31, v42, s73
	v_add3_u32 v42, v37, v39, s73
	v_add3_u32 v43, v36, v38, s73
	v_lshrrev_b32_e32 v54, 16, v43
	v_lshrrev_b32_e32 v55, 16, v42
	v_lshrrev_b32_e32 v31, 16, v31
	v_lshrrev_b32_e32 v40, 16, v40
	ds_read2_b64 v[36:39], v14 offset0:32 offset1:36
	v_and_or_b32 v43, v3, s74, v40
	v_and_or_b32 v42, v41, s74, v31
	v_and_or_b32 v41, v52, s74, v55
	v_and_or_b32 v40, v53, s74, v54
	ds_read2_b64 v[52:55], v13 offset0:96 offset1:100
	s_waitcnt lgkmcnt(1)
	v_mfma_f32_16x16x32_bf16 v[36:39], v[36:39], v[40:43], v[44:47]
	s_nop 2
	ds_read2_b64 v[44:47], v11 offset0:64 offset1:68
	s_waitcnt lgkmcnt(1)
	v_mfma_f32_16x16x32_bf16 v[52:55], v[52:55], v[40:43], v[56:59]
	s_nop 2
	ds_read2_b64 v[56:59], v0 offset0:32 offset1:36
	s_waitcnt lgkmcnt(1)
	v_mfma_f32_16x16x32_bf16 v[44:47], v[44:47], v[40:43], v[80:83]
	s_nop 2
	ds_read2_b64 v[80:83], v34 offset0:192 offset1:196
	s_waitcnt lgkmcnt(1)
	v_mfma_f32_16x16x32_bf16 v[56:59], v[56:59], v[40:43], v[60:63]
	s_nop 2
	ds_read2_b64 v[60:63], v1 offset0:160 offset1:164
	s_waitcnt lgkmcnt(0)
	v_mfma_f32_16x16x32_bf16 v[60:63], v[60:63], v[40:43], v[84:87]
	s_nop 2
	ds_read2_b64 v[84:87], v35 offset0:224 offset1:228
	v_mfma_f32_16x16x32_bf16 v[80:83], v[80:83], v[40:43], v[88:91]
	s_nop 2
	ds_read2_b64 v[88:91], v2 offset0:32 offset1:36
	s_waitcnt lgkmcnt(1)
	v_mfma_f32_16x16x32_bf16 v[84:87], v[84:87], v[40:43], v[92:95]
	s_waitcnt lgkmcnt(0)
	v_mfma_f32_16x16x32_bf16 v[40:43], v[88:91], v[40:43], v[48:51]
	v_bfe_u32 v3, v30, 16, 1
	v_bfe_u32 v31, v29, 16, 1
	s_nop 0
	v_bfe_u32 v48, v26, 16, 1
	v_bfe_u32 v49, v25, 16, 1
	v_add3_u32 v49, v25, v49, s73
	v_add3_u32 v26, v26, v48, s73
	v_add3_u32 v29, v29, v31, s73
	v_add3_u32 v3, v30, v3, s73
	v_bfe_u32 v25, v24, 16, 1
	v_bfe_u32 v30, v22, 16, 1
	v_bfe_u32 v31, v23, 16, 1
	v_bfe_u32 v48, v28, 16, 1
	v_add3_u32 v28, v28, v48, s73
	v_add3_u32 v31, v23, v31, s73
	v_add3_u32 v30, v22, v30, s73
	v_add3_u32 v48, v24, v25, s73
	ds_read2_b64 v[22:25], v14 offset0:40 offset1:44
	v_lshrrev_b32_e32 v48, 16, v48
	v_lshrrev_b32_e32 v50, 16, v30
	v_lshrrev_b32_e32 v30, 16, v31
	v_lshrrev_b32_e32 v28, 16, v28
	v_and_or_b32 v31, v3, s74, v28
	v_and_or_b32 v30, v29, s74, v30
	v_and_or_b32 v29, v26, s74, v50
	v_and_or_b32 v28, v49, s74, v48
	ds_read2_b64 v[48:51], v0 offset0:40 offset1:44
	s_waitcnt lgkmcnt(1)
	v_mfma_f32_16x16x32_bf16 v[22:25], v[22:25], v[28:31], v[36:39]
	s_nop 2
	ds_read2_b64 v[36:39], v11 offset0:72 offset1:76
	s_waitcnt lgkmcnt(0)
	v_mfma_f32_16x16x32_bf16 v[36:39], v[36:39], v[28:31], v[44:47]
	s_nop 2
	ds_read2_b64 v[44:47], v13 offset0:104 offset1:108
	s_waitcnt lgkmcnt(0)
	v_mfma_f32_16x16x32_bf16 v[44:47], v[44:47], v[28:31], v[52:55]
	s_nop 2
	ds_read2_b64 v[52:55], v1 offset0:168 offset1:172
	v_mfma_f32_16x16x32_bf16 v[48:51], v[48:51], v[28:31], v[56:59]
	s_nop 2
	ds_read2_b64 v[56:59], v34 offset0:200 offset1:204
	s_waitcnt lgkmcnt(1)
	v_mfma_f32_16x16x32_bf16 v[52:55], v[52:55], v[28:31], v[60:63]
	s_nop 2
	ds_read2_b64 v[60:63], v35 offset0:232 offset1:236
	s_waitcnt lgkmcnt(1)
	v_mfma_f32_16x16x32_bf16 v[56:59], v[56:59], v[28:31], v[80:83]
	s_nop 2
	ds_read2_b64 v[80:83], v2 offset0:40 offset1:44
	s_waitcnt lgkmcnt(1)
	v_mfma_f32_16x16x32_bf16 v[60:63], v[60:63], v[28:31], v[84:87]
	s_waitcnt lgkmcnt(0)
	v_mfma_f32_16x16x32_bf16 v[28:31], v[80:83], v[28:31], v[40:43]
	v_bfe_u32 v3, v21, 16, 1
	v_bfe_u32 v26, v20, 16, 1
	s_nop 0
	v_bfe_u32 v40, v18, 16, 1
	v_bfe_u32 v41, v17, 16, 1
	v_add3_u32 v68, v17, v41, s73
	v_add3_u32 v40, v18, v40, s73
	v_add3_u32 v20, v20, v26, s73
	v_add3_u32 v3, v21, v3, s73
	v_bfe_u32 v17, v12, 16, 1
	v_bfe_u32 v18, v16, 16, 1
	v_bfe_u32 v21, v15, 16, 1
	v_bfe_u32 v26, v19, 16, 1
	v_add3_u32 v26, v19, v26, s73
	v_add3_u32 v15, v15, v21, s73
	v_add3_u32 v21, v16, v18, s73
	v_add3_u32 v12, v12, v17, s73
	ds_read2_b64 v[16:19], v14 offset0:48 offset1:52
	v_lshrrev_b32_e32 v12, 16, v12
	v_lshrrev_b32_e32 v21, 16, v21
	v_lshrrev_b32_e32 v15, 16, v15
	v_lshrrev_b32_e32 v26, 16, v26
	v_and_or_b32 v43, v3, s74, v26
	v_and_or_b32 v42, v20, s74, v15
	v_and_or_b32 v41, v40, s74, v21
	v_and_or_b32 v40, v68, s74, v12
	s_waitcnt lgkmcnt(0)
	s_nop 0
	v_mfma_f32_16x16x32_bf16 v[16:19], v[16:19], v[40:43], v[22:25]
	s_nop 2
	ds_read2_b64 v[20:23], v11 offset0:80 offset1:84
	s_waitcnt lgkmcnt(0)
	v_mfma_f32_16x16x32_bf16 v[20:23], v[20:23], v[40:43], v[36:39]
	s_nop 2
	ds_read2_b64 v[36:39], v13 offset0:112 offset1:116
	s_waitcnt lgkmcnt(0)
	v_mfma_f32_16x16x32_bf16 v[36:39], v[36:39], v[40:43], v[44:47]
	s_nop 2
	ds_read2_b64 v[44:47], v0 offset0:48 offset1:52
	s_waitcnt lgkmcnt(0)
	v_mfma_f32_16x16x32_bf16 v[44:47], v[44:47], v[40:43], v[48:51]
	s_nop 2
	ds_read2_b64 v[48:51], v1 offset0:176 offset1:180
	s_waitcnt lgkmcnt(0)
	v_mfma_f32_16x16x32_bf16 v[48:51], v[48:51], v[40:43], v[52:55]
	s_nop 2
	ds_read2_b64 v[52:55], v34 offset0:208 offset1:212
	s_waitcnt lgkmcnt(0)
	v_mfma_f32_16x16x32_bf16 v[52:55], v[52:55], v[40:43], v[56:59]
	s_nop 2
	ds_read2_b64 v[56:59], v35 offset0:240 offset1:244
	s_waitcnt lgkmcnt(0)
	v_mfma_f32_16x16x32_bf16 v[56:59], v[56:59], v[40:43], v[60:63]
	s_nop 2
	ds_read2_b64 v[60:63], v2 offset0:48 offset1:52
	s_waitcnt lgkmcnt(0)
	v_mfma_f32_16x16x32_bf16 v[40:43], v[60:63], v[40:43], v[28:31]
	v_bfe_u32 v12, v10, 16, 1
	v_bfe_u32 v15, v7, 16, 1
	v_bfe_u32 v24, v8, 16, 1
	v_add3_u32 v8, v8, v24, s73
	v_add3_u32 v15, v7, v15, s73
	v_add3_u32 v10, v10, v12, s73
	v_bfe_u32 v7, v4, 16, 1
	v_bfe_u32 v12, v5, 16, 1
	v_bfe_u32 v24, v6, 16, 1
	v_bfe_u32 v25, v9, 16, 1
	v_add3_u32 v9, v9, v25, s73
	v_add3_u32 v24, v6, v24, s73
	v_add3_u32 v12, v5, v12, s73
	v_add3_u32 v25, v4, v7, s73
	ds_read2_b64 v[4:7], v14 offset0:56 offset1:60
	v_bfe_u32 v3, v27, 16, 1
	v_add3_u32 v3, v27, v3, s73
	v_lshrrev_b32_e32 v14, 16, v25
	v_lshrrev_b32_e32 v12, 16, v12
	v_lshrrev_b32_e32 v24, 16, v24
	v_lshrrev_b32_e32 v9, 16, v9
	v_and_or_b32 v63, v3, s74, v9
	v_and_or_b32 v62, v10, s74, v24
	v_and_or_b32 v61, v15, s74, v12
	v_and_or_b32 v60, v8, s74, v14
	s_waitcnt lgkmcnt(0)
	s_nop 0
	v_mfma_f32_16x16x32_bf16 v[28:31], v[4:7], v[60:63], v[16:19]
	ds_read2_b64 v[4:7], v11 offset0:88 offset1:92
	s_waitcnt lgkmcnt(0)
	v_mfma_f32_16x16x32_bf16 v[24:27], v[4:7], v[60:63], v[20:23]
	ds_read2_b64 v[4:7], v13 offset0:120 offset1:124
	s_waitcnt lgkmcnt(0)
	v_mfma_f32_16x16x32_bf16 v[20:23], v[4:7], v[60:63], v[36:39]
	ds_read2_b64 v[4:7], v0 offset0:56 offset1:60
	s_waitcnt lgkmcnt(0)
	v_mfma_f32_16x16x32_bf16 v[16:19], v[4:7], v[60:63], v[44:47]
	ds_read2_b64 v[4:7], v1 offset0:184 offset1:188
	ds_read2_b64 v[0:3], v2 offset0:56 offset1:60
	s_waitcnt lgkmcnt(1)
	v_mfma_f32_16x16x32_bf16 v[12:15], v[4:7], v[60:63], v[48:51]
	ds_read2_b64 v[4:7], v34 offset0:216 offset1:220
	s_waitcnt lgkmcnt(0)
	v_mfma_f32_16x16x32_bf16 v[8:11], v[4:7], v[60:63], v[52:55]
	ds_read2_b64 v[4:7], v35 offset0:248 offset1:252
	s_waitcnt lgkmcnt(0)
	v_mfma_f32_16x16x32_bf16 v[4:7], v[4:7], v[60:63], v[56:59]
	v_mfma_f32_16x16x32_bf16 v[0:3], v[0:3], v[60:63], v[40:43]
	v_cmp_gt_u32_e32 vcc, 4, v64
	s_and_b64 exec, exec, vcc
	s_cbranch_execz .LBB0_656
	v_add_f32_e32 v32, v32, v33
	v_div_scale_f32 v33, s[8:9], v32, v32, 1.0
	v_rcp_f32_e32 v34, v33
	v_div_scale_f32 v35, vcc, 1.0, v32, 1.0
	v_mov_b32_e32 v38, v28
	v_fma_f32 v36, -v33, v34, 1.0
	v_fmac_f32_e32 v34, v36, v34
	v_mul_f32_e32 v36, v35, v34
	v_fma_f32 v37, -v33, v36, v35
	v_fmac_f32_e32 v36, v37, v34
	v_fma_f32 v33, -v33, v36, v35
	v_div_fmas_f32 v33, v33, v34, v36
	v_div_fixup_f32 v32, v33, v32, 1.0
	v_or_b32_e32 v33, s6, v64
	v_mul_u32_u24_e32 v33, 0x1e00, v33
	v_mov_b32_e32 v39, v30
	v_mov_b32_e32 v30, v29
	v_lshlrev_b32_e32 v64, 1, v33
	v_pk_mul_f32 v[38:39], v[32:33], v[38:39] op_sel_hi:[0,1]
	v_pk_mul_f32 v[28:29], v[32:33], v[30:31] op_sel_hi:[0,1]
	v_lshl_add_u64 v[34:35], s[30:31], 0, v[64:65]
	v_and_b32_sdwa v31, v38, v75 dst_sel:DWORD dst_unused:UNUSED_PAD src0_sel:WORD_1 src1_sel:DWORD
	v_and_b32_sdwa v33, v29, v75 dst_sel:DWORD dst_unused:UNUSED_PAD src0_sel:WORD_1 src1_sel:DWORD
	v_lshl_add_u64 v[34:35], v[34:35], 0, s[48:49]
	v_lshlrev_b32_e32 v64, 3, v67
	v_and_b32_sdwa v30, v39, v75 dst_sel:DWORD dst_unused:UNUSED_PAD src0_sel:WORD_1 src1_sel:DWORD
	v_add3_u32 v31, v38, v31, s73
	v_and_b32_sdwa v38, v28, v75 dst_sel:DWORD dst_unused:UNUSED_PAD src0_sel:WORD_1 src1_sel:DWORD
	v_add3_u32 v29, v29, v33, s73
	v_lshl_add_u64 v[34:35], v[34:35], 0, v[64:65]
	v_add3_u32 v30, v39, v30, s73
	v_add3_u32 v28, v28, v38, s73
	v_and_b32_e32 v29, 0xffff0000, v29
	v_and_b32_e32 v28, 0xffff0000, v28
	v_or_b32_sdwa v29, v29, v30 dst_sel:DWORD dst_unused:UNUSED_PAD src0_sel:DWORD src1_sel:WORD_1
	v_add_co_u32_e32 v30, vcc, s76, v34
	v_or_b32_sdwa v28, v28, v31 dst_sel:DWORD dst_unused:UNUSED_PAD src0_sel:DWORD src1_sel:WORD_1
	s_nop 0
	v_addc_co_u32_e32 v31, vcc, 0, v35, vcc
	global_store_dwordx2 v[30:31], v[28:29], off
	v_mov_b32_e32 v28, v24
	v_mov_b32_e32 v29, v26
	v_pk_mul_f32 v[28:29], v[32:33], v[28:29] op_sel_hi:[0,1]
	v_mov_b32_e32 v26, v25
	v_pk_mul_f32 v[24:25], v[32:33], v[26:27] op_sel_hi:[0,1]
	v_and_b32_sdwa v26, v29, v75 dst_sel:DWORD dst_unused:UNUSED_PAD src0_sel:WORD_1 src1_sel:DWORD
	v_and_b32_sdwa v27, v28, v75 dst_sel:DWORD dst_unused:UNUSED_PAD src0_sel:WORD_1 src1_sel:DWORD
	v_add3_u32 v27, v28, v27, s73
	v_add3_u32 v26, v29, v26, s73
	v_and_b32_sdwa v28, v25, v75 dst_sel:DWORD dst_unused:UNUSED_PAD src0_sel:WORD_1 src1_sel:DWORD
	v_and_b32_sdwa v29, v24, v75 dst_sel:DWORD dst_unused:UNUSED_PAD src0_sel:WORD_1 src1_sel:DWORD
	v_add3_u32 v25, v25, v28, s73
	v_add3_u32 v24, v24, v29, s73
	s_mov_b64 s[6:7], 0x2000
	v_and_b32_e32 v25, 0xffff0000, v25
	v_and_b32_e32 v24, 0xffff0000, v24
	v_lshl_add_u64 v[36:37], v[34:35], 0, s[6:7]
	v_or_b32_sdwa v25, v25, v26 dst_sel:DWORD dst_unused:UNUSED_PAD src0_sel:DWORD src1_sel:WORD_1
	v_or_b32_sdwa v24, v24, v27 dst_sel:DWORD dst_unused:UNUSED_PAD src0_sel:DWORD src1_sel:WORD_1
	global_store_dwordx2 v[36:37], v[24:25], off offset:32
	v_mov_b32_e32 v24, v20
	v_mov_b32_e32 v25, v22
	v_pk_mul_f32 v[24:25], v[32:33], v[24:25] op_sel_hi:[0,1]
	v_mov_b32_e32 v22, v21
	v_pk_mul_f32 v[20:21], v[32:33], v[22:23] op_sel_hi:[0,1]
	v_and_b32_sdwa v22, v25, v75 dst_sel:DWORD dst_unused:UNUSED_PAD src0_sel:WORD_1 src1_sel:DWORD
	v_and_b32_sdwa v23, v24, v75 dst_sel:DWORD dst_unused:UNUSED_PAD src0_sel:WORD_1 src1_sel:DWORD
	v_add3_u32 v23, v24, v23, s73
	v_add3_u32 v22, v25, v22, s73
	v_and_b32_sdwa v24, v21, v75 dst_sel:DWORD dst_unused:UNUSED_PAD src0_sel:WORD_1 src1_sel:DWORD
	v_and_b32_sdwa v25, v20, v75 dst_sel:DWORD dst_unused:UNUSED_PAD src0_sel:WORD_1 src1_sel:DWORD
	v_add3_u32 v21, v21, v24, s73
	v_add3_u32 v20, v20, v25, s73
	v_and_b32_e32 v21, 0xffff0000, v21
	v_and_b32_e32 v20, 0xffff0000, v20
	v_or_b32_sdwa v21, v21, v22 dst_sel:DWORD dst_unused:UNUSED_PAD src0_sel:DWORD src1_sel:WORD_1
	v_or_b32_sdwa v20, v20, v23 dst_sel:DWORD dst_unused:UNUSED_PAD src0_sel:DWORD src1_sel:WORD_1
	global_store_dwordx2 v[36:37], v[20:21], off offset:64
	v_mov_b32_e32 v20, v16
	v_mov_b32_e32 v21, v18
	v_pk_mul_f32 v[20:21], v[32:33], v[20:21] op_sel_hi:[0,1]
	v_mov_b32_e32 v18, v17
	v_pk_mul_f32 v[16:17], v[32:33], v[18:19] op_sel_hi:[0,1]
	v_and_b32_sdwa v18, v21, v75 dst_sel:DWORD dst_unused:UNUSED_PAD src0_sel:WORD_1 src1_sel:DWORD
	v_and_b32_sdwa v19, v20, v75 dst_sel:DWORD dst_unused:UNUSED_PAD src0_sel:WORD_1 src1_sel:DWORD
	v_add3_u32 v19, v20, v19, s73
	v_add3_u32 v18, v21, v18, s73
	v_and_b32_sdwa v20, v17, v75 dst_sel:DWORD dst_unused:UNUSED_PAD src0_sel:WORD_1 src1_sel:DWORD
	v_and_b32_sdwa v21, v16, v75 dst_sel:DWORD dst_unused:UNUSED_PAD src0_sel:WORD_1 src1_sel:DWORD
	v_add3_u32 v17, v17, v20, s73
	v_add3_u32 v16, v16, v21, s73
	v_and_b32_e32 v17, 0xffff0000, v17
	v_and_b32_e32 v16, 0xffff0000, v16
	v_or_b32_sdwa v17, v17, v18 dst_sel:DWORD dst_unused:UNUSED_PAD src0_sel:DWORD src1_sel:WORD_1
	v_or_b32_sdwa v16, v16, v19 dst_sel:DWORD dst_unused:UNUSED_PAD src0_sel:DWORD src1_sel:WORD_1
	global_store_dwordx2 v[36:37], v[16:17], off offset:96
	v_mov_b32_e32 v16, v12
	v_mov_b32_e32 v17, v14
	v_pk_mul_f32 v[16:17], v[32:33], v[16:17] op_sel_hi:[0,1]
	v_mov_b32_e32 v14, v13
	v_pk_mul_f32 v[12:13], v[32:33], v[14:15] op_sel_hi:[0,1]
	v_and_b32_sdwa v14, v17, v75 dst_sel:DWORD dst_unused:UNUSED_PAD src0_sel:WORD_1 src1_sel:DWORD
	v_and_b32_sdwa v15, v16, v75 dst_sel:DWORD dst_unused:UNUSED_PAD src0_sel:WORD_1 src1_sel:DWORD
	v_add3_u32 v15, v16, v15, s73
	v_add3_u32 v14, v17, v14, s73
	v_and_b32_sdwa v16, v13, v75 dst_sel:DWORD dst_unused:UNUSED_PAD src0_sel:WORD_1 src1_sel:DWORD
	v_and_b32_sdwa v17, v12, v75 dst_sel:DWORD dst_unused:UNUSED_PAD src0_sel:WORD_1 src1_sel:DWORD
	v_add3_u32 v13, v13, v16, s73
	v_add3_u32 v12, v12, v17, s73
	v_and_b32_e32 v13, 0xffff0000, v13
	v_and_b32_e32 v12, 0xffff0000, v12
	v_or_b32_sdwa v13, v13, v14 dst_sel:DWORD dst_unused:UNUSED_PAD src0_sel:DWORD src1_sel:WORD_1
	v_or_b32_sdwa v12, v12, v15 dst_sel:DWORD dst_unused:UNUSED_PAD src0_sel:DWORD src1_sel:WORD_1
	global_store_dwordx2 v[36:37], v[12:13], off offset:128
	v_mov_b32_e32 v12, v8
	v_mov_b32_e32 v13, v10
	v_pk_mul_f32 v[12:13], v[32:33], v[12:13] op_sel_hi:[0,1]
	v_mov_b32_e32 v10, v9
	v_pk_mul_f32 v[8:9], v[32:33], v[10:11] op_sel_hi:[0,1]
	v_and_b32_sdwa v10, v13, v75 dst_sel:DWORD dst_unused:UNUSED_PAD src0_sel:WORD_1 src1_sel:DWORD
	v_and_b32_sdwa v11, v12, v75 dst_sel:DWORD dst_unused:UNUSED_PAD src0_sel:WORD_1 src1_sel:DWORD
	v_add3_u32 v11, v12, v11, s73
	v_add3_u32 v10, v13, v10, s73
	v_and_b32_sdwa v12, v9, v75 dst_sel:DWORD dst_unused:UNUSED_PAD src0_sel:WORD_1 src1_sel:DWORD
	v_and_b32_sdwa v13, v8, v75 dst_sel:DWORD dst_unused:UNUSED_PAD src0_sel:WORD_1 src1_sel:DWORD
	v_add3_u32 v9, v9, v12, s73
	v_add3_u32 v8, v8, v13, s73
	v_and_b32_e32 v9, 0xffff0000, v9
	v_and_b32_e32 v8, 0xffff0000, v8
	v_or_b32_sdwa v9, v9, v10 dst_sel:DWORD dst_unused:UNUSED_PAD src0_sel:DWORD src1_sel:WORD_1
	v_or_b32_sdwa v8, v8, v11 dst_sel:DWORD dst_unused:UNUSED_PAD src0_sel:DWORD src1_sel:WORD_1
	global_store_dwordx2 v[36:37], v[8:9], off offset:160
	v_mov_b32_e32 v8, v4
	v_mov_b32_e32 v9, v6
	v_pk_mul_f32 v[8:9], v[32:33], v[8:9] op_sel_hi:[0,1]
	v_mov_b32_e32 v6, v5
	v_pk_mul_f32 v[4:5], v[32:33], v[6:7] op_sel_hi:[0,1]
	v_and_b32_sdwa v6, v9, v75 dst_sel:DWORD dst_unused:UNUSED_PAD src0_sel:WORD_1 src1_sel:DWORD
	v_and_b32_sdwa v7, v8, v75 dst_sel:DWORD dst_unused:UNUSED_PAD src0_sel:WORD_1 src1_sel:DWORD
	v_add3_u32 v7, v8, v7, s73
	v_add3_u32 v6, v9, v6, s73
	v_and_b32_sdwa v8, v5, v75 dst_sel:DWORD dst_unused:UNUSED_PAD src0_sel:WORD_1 src1_sel:DWORD
	v_and_b32_sdwa v9, v4, v75 dst_sel:DWORD dst_unused:UNUSED_PAD src0_sel:WORD_1 src1_sel:DWORD
	v_add3_u32 v5, v5, v8, s73
	v_add3_u32 v4, v4, v9, s73
	v_and_b32_e32 v5, 0xffff0000, v5
	v_and_b32_e32 v4, 0xffff0000, v4
	v_or_b32_sdwa v5, v5, v6 dst_sel:DWORD dst_unused:UNUSED_PAD src0_sel:DWORD src1_sel:WORD_1
	v_or_b32_sdwa v4, v4, v7 dst_sel:DWORD dst_unused:UNUSED_PAD src0_sel:DWORD src1_sel:WORD_1
	global_store_dwordx2 v[36:37], v[4:5], off offset:192
	v_mov_b32_e32 v4, v0
	v_mov_b32_e32 v5, v2
	v_pk_mul_f32 v[4:5], v[32:33], v[4:5] op_sel_hi:[0,1]
	v_mov_b32_e32 v2, v1
	v_pk_mul_f32 v[0:1], v[32:33], v[2:3] op_sel_hi:[0,1]
	v_and_b32_sdwa v2, v5, v75 dst_sel:DWORD dst_unused:UNUSED_PAD src0_sel:WORD_1 src1_sel:DWORD
	v_and_b32_sdwa v3, v4, v75 dst_sel:DWORD dst_unused:UNUSED_PAD src0_sel:WORD_1 src1_sel:DWORD
	v_add3_u32 v3, v4, v3, s73
	v_add3_u32 v2, v5, v2, s73
	v_and_b32_sdwa v4, v1, v75 dst_sel:DWORD dst_unused:UNUSED_PAD src0_sel:WORD_1 src1_sel:DWORD
	v_and_b32_sdwa v5, v0, v75 dst_sel:DWORD dst_unused:UNUSED_PAD src0_sel:WORD_1 src1_sel:DWORD
	v_add3_u32 v1, v1, v4, s73
	v_add3_u32 v0, v0, v5, s73
	v_and_b32_e32 v1, 0xffff0000, v1
	v_and_b32_e32 v0, 0xffff0000, v0
	v_or_b32_sdwa v1, v1, v2 dst_sel:DWORD dst_unused:UNUSED_PAD src0_sel:DWORD src1_sel:WORD_1
	v_or_b32_sdwa v0, v0, v3 dst_sel:DWORD dst_unused:UNUSED_PAD src0_sel:DWORD src1_sel:WORD_1
	global_store_dwordx2 v[36:37], v[0:1], off offset:224

.LBB0_797:
	s_or_b64 exec, exec, s[4:5]
	v_or_b32_e32 v16, s30, v32
	v_mov_b64_e32 v[28:29], s[24:25]
	v_mad_u64_u32 v[34:35], s[4:5], v16, s2, v[28:29]
	s_lshl_b32 s4, s74, 2
	v_or_b32_e32 v38, v26, v18
	s_add_u32 s4, s26, s4
	s_mul_i32 s6, s31, 0x3c00
	s_addc_u32 s5, s27, 0
	v_ashrrev_i32_e32 v39, 31, v38
	v_add_u32_e32 v35, s6, v35
	s_waitcnt lgkmcnt(0)
	v_lshl_add_u64 v[18:19], v[38:39], 2, s[4:5]
	s_barrier
	s_waitcnt vmcnt(54)
	v_mov_b32_e32 v26, v208
	v_mov_b32_e32 v27, v209
	v_mov_b32_e32 v28, v210
	v_mov_b32_e32 v29, v211
	v_lshl_add_u64 v[34:35], v[34:35], 0, s[28:29]
	v_lshl_add_u64 v[40:41], v[38:39], 1, v[34:35]
	v_mov_b32_e32 v34, v212
	v_mov_b32_e32 v35, v213
	v_mov_b32_e32 v36, v214
	v_mov_b32_e32 v37, v215
	v_mov_b32_e32 v42, v224
	v_mov_b32_e32 v43, v225
	v_mov_b32_e32 v44, v226
	v_mov_b32_e32 v45, v227
	v_lshl_add_u32 v16, v32, 3, 0
	v_mov_b32_e32 v46, v12
	v_add_u32_e32 v12, 0x1a600, v16
	ds_read_b64 v[32:33], v12
	v_mov_b32_e32 v12, v8
	v_lshl_add_u32 v58, v38, 1, v31
	v_mov_b32_e32 v47, v14
	v_mov_b32_e32 v14, v13
	s_waitcnt lgkmcnt(0)
	v_add_f32_e32 v8, v32, v33
	v_mov_b32_e32 v30, v216
	v_mov_b32_e32 v31, v217
	v_mov_b32_e32 v32, v218
	v_mov_b32_e32 v33, v219
	v_mov_b32_e32 v38, v228
	v_mov_b32_e32 v39, v229
	s_nop 0
	v_mov_b32_e32 v40, v230
	v_mov_b32_e32 v41, v231
	v_fmamk_f32 v8, v8, 0x3c000000, v20
	v_mov_b32_e32 v13, v10
	v_mul_f32_e32 v10, 0x4b800000, v8
	v_cmp_gt_f32_e32 vcc, s3, v8
	s_add_u32 s4, s24, s28
	s_addc_u32 s5, s25, 0
	v_cndmask_b32_e32 v8, v8, v10, vcc
	v_rsq_f32_e32 v8, v8
	s_add_i32 s14, s14, s22
	s_cmpk_lt_i32 s14, 0x400
	v_mul_f32_e32 v10, 0x45800000, v8
	v_cndmask_b32_e32 v16, v8, v10, vcc
	v_pk_mul_f32 v[14:15], v[14:15], v[16:17] op_sel_hi:[1,0]
	v_pk_mul_f32 v[46:47], v[46:47], v[16:17] op_sel_hi:[1,0]
	v_pk_mul_f32 v[12:13], v[12:13], v[16:17] op_sel_hi:[1,0]
	v_mov_b32_e32 v49, v28
	v_mov_b32_e32 v28, v27
	v_lshlrev_b32_e32 v51, 16, v43
	v_lshlrev_b32_e32 v50, 16, v42
	v_and_b32_e32 v43, 0xffff0000, v43
	v_and_b32_e32 v42, 0xffff0000, v42
	v_mov_b32_e32 v48, v26
	v_mov_b32_e32 v26, v34
	v_pk_mul_f32 v[14:15], v[28:29], v[14:15]
	v_lshlrev_b32_e32 v29, 16, v45
	v_mul_f32_e32 v10, 0xbfb8aa3b, v42
	v_mul_f32_e32 v34, 0xbfb8aa3b, v43
	v_lshlrev_b32_e32 v28, 16, v44
	v_and_b32_e32 v44, 0xffff0000, v44
	v_mul_f32_e32 v8, 0xbfb8aa3b, v50
	v_mul_f32_e32 v27, 0xbfb8aa3b, v51
	v_mul_f32_e32 v52, 0xbfb8aa3b, v29
	v_exp_f32_e32 v10, v10
	v_exp_f32_e32 v34, v34
	v_pk_mul_f32 v[46:47], v[48:49], v[46:47]
	v_mul_f32_e32 v48, 0xbfb8aa3b, v28
	v_mul_f32_e32 v49, 0xbfb8aa3b, v44
	v_exp_f32_e32 v8, v8
	v_exp_f32_e32 v27, v27
	v_exp_f32_e32 v52, v52
	v_exp_f32_e32 v48, v48
	v_exp_f32_e32 v49, v49
	v_add_f32_e32 v10, 1.0, v10
	v_add_f32_e32 v34, 1.0, v34
	v_add_f32_e32 v8, 1.0, v8
	v_add_f32_e32 v27, 1.0, v27
	v_add_f32_e32 v57, 1.0, v52
	v_rcp_f32_e32 v52, v10
	v_rcp_f32_e32 v53, v34
	v_add_f32_e32 v54, 1.0, v48
	v_add_f32_e32 v55, 1.0, v49
	v_rcp_f32_e32 v48, v8
	v_rcp_f32_e32 v49, v27
	v_pk_mul_f32 v[42:43], v[52:53], v[42:43]
	v_and_b32_e32 v45, 0xffff0000, v45
	v_pk_mul_f32 v[14:15], v[42:43], v[14:15]
	v_pk_mul_f32 v[48:49], v[48:49], v[50:51]
	v_and_b32_sdwa v27, v15, v24 dst_sel:DWORD dst_unused:UNUSED_PAD src0_sel:WORD_1 src1_sel:DWORD
	v_pk_mul_f32 v[46:47], v[48:49], v[46:47]
	v_add3_u32 v15, v15, v27, s64
	v_and_b32_sdwa v8, v47, v24 dst_sel:DWORD dst_unused:UNUSED_PAD src0_sel:WORD_1 src1_sel:DWORD
	v_add3_u32 v8, v47, v8, s64
	v_and_b32_e32 v15, 0xffff0000, v15
	v_or_b32_sdwa v15, v15, v8 dst_sel:DWORD dst_unused:UNUSED_PAD src0_sel:DWORD src1_sel:WORD_1
	v_mul_f32_e32 v8, 0xbfb8aa3b, v45
	v_rcp_f32_e32 v54, v54
	v_rcp_f32_e32 v56, v55
	v_rcp_f32_e32 v55, v57
	v_exp_f32_e32 v8, v8
	v_and_b32_sdwa v34, v14, v24 dst_sel:DWORD dst_unused:UNUSED_PAD src0_sel:WORD_1 src1_sel:DWORD
	v_and_b32_sdwa v10, v46, v24 dst_sel:DWORD dst_unused:UNUSED_PAD src0_sel:WORD_1 src1_sel:DWORD
	v_add3_u32 v14, v14, v34, s64
	v_add3_u32 v10, v46, v10, s64
	v_and_b32_e32 v14, 0xffff0000, v14
	v_mov_b32_e32 v27, v36
	v_or_b32_sdwa v14, v14, v10 dst_sel:DWORD dst_unused:UNUSED_PAD src0_sel:DWORD src1_sel:WORD_1
	v_pk_mul_f32 v[12:13], v[26:27], v[12:13]
	v_pk_mul_f32 v[26:27], v[54:55], v[28:29]
	v_mov_b32_e32 v10, v9
	v_add_f32_e32 v8, 1.0, v8
	v_pk_mul_f32 v[12:13], v[12:13], v[26:27]
	v_pk_mul_f32 v[26:27], v[10:11], v[16:17] op_sel_hi:[1,0]
	v_rcp_f32_e32 v57, v8
	v_mov_b32_e32 v8, v220
	v_mov_b32_e32 v9, v221
	v_mov_b32_e32 v10, v222
	v_mov_b32_e32 v11, v223
	v_mov_b32_e32 v36, v35
	v_pk_mul_f32 v[18:19], v[36:37], v[26:27]
	v_pk_mul_f32 v[26:27], v[56:57], v[44:45]
	v_mov_b32_e32 v28, v4
	v_pk_mul_f32 v[18:19], v[18:19], v[26:27]
	v_cvt_pk_bf16_f32 v13, v13, v19
	v_cvt_pk_bf16_f32 v12, v12, v18
	ds_write2_b64 v58, v[14:15], v[12:13] offset1:4
	v_lshlrev_b32_e32 v12, 16, v38
	v_mul_f32_e32 v14, 0xbfb8aa3b, v12
	v_lshlrev_b32_e32 v13, 16, v39
	v_exp_f32_e32 v15, v14
	v_and_b32_e32 v14, 0xffff0000, v38
	v_mul_f32_e32 v18, 0xbfb8aa3b, v14
	v_mul_f32_e32 v4, 0xbfb8aa3b, v13
	v_exp_f32_e32 v19, v18
	v_exp_f32_e32 v4, v4
	v_add_f32_e32 v15, 1.0, v15
	v_rcp_f32_e32 v18, v15
	v_and_b32_e32 v15, 0xffff0000, v39
	v_add_f32_e32 v19, 1.0, v19
	v_add_f32_e32 v4, 1.0, v4
	v_rcp_f32_e32 v26, v19
	v_rcp_f32_e32 v19, v4
	v_mul_f32_e32 v4, 0xbfb8aa3b, v15
	v_exp_f32_e32 v4, v4
	v_mov_b32_e32 v29, v6
	v_pk_mul_f32 v[28:29], v[28:29], v[16:17] op_sel_hi:[1,0]
	v_mov_b32_e32 v34, v30
	v_add_f32_e32 v4, 1.0, v4
	v_rcp_f32_e32 v27, v4
	v_mov_b32_e32 v35, v32
	v_mov_b32_e32 v6, v5
	v_pk_mul_f32 v[28:29], v[28:29], v[34:35]
	v_pk_mul_f32 v[12:13], v[18:19], v[12:13]
	v_pk_mul_f32 v[4:5], v[6:7], v[16:17] op_sel_hi:[1,0]
	v_mov_b32_e32 v32, v31
	v_pk_mul_f32 v[12:13], v[28:29], v[12:13]
	v_pk_mul_f32 v[4:5], v[4:5], v[32:33]
	v_pk_mul_f32 v[6:7], v[26:27], v[14:15]
	v_mov_b32_e32 v26, v0
	v_pk_mul_f32 v[4:5], v[4:5], v[6:7]
	v_and_b32_sdwa v7, v12, v24 dst_sel:DWORD dst_unused:UNUSED_PAD src0_sel:WORD_1 src1_sel:DWORD
	v_add3_u32 v7, v12, v7, s64
	v_and_b32_sdwa v12, v5, v24 dst_sel:DWORD dst_unused:UNUSED_PAD src0_sel:WORD_1 src1_sel:DWORD
	v_and_b32_sdwa v6, v13, v24 dst_sel:DWORD dst_unused:UNUSED_PAD src0_sel:WORD_1 src1_sel:DWORD
	v_add3_u32 v5, v5, v12, s64
	v_add3_u32 v6, v13, v6, s64
	v_and_b32_sdwa v13, v4, v24 dst_sel:DWORD dst_unused:UNUSED_PAD src0_sel:WORD_1 src1_sel:DWORD
	v_and_b32_e32 v5, 0xffff0000, v5
	v_add3_u32 v4, v4, v13, s64
	v_or_b32_sdwa v5, v5, v6 dst_sel:DWORD dst_unused:UNUSED_PAD src0_sel:DWORD src1_sel:WORD_1
	v_lshlrev_b32_e32 v6, 16, v40
	v_and_b32_e32 v4, 0xffff0000, v4
	v_mul_f32_e32 v12, 0xbfb8aa3b, v6
	v_or_b32_sdwa v4, v4, v7 dst_sel:DWORD dst_unused:UNUSED_PAD src0_sel:DWORD src1_sel:WORD_1
	v_lshlrev_b32_e32 v7, 16, v41
	v_exp_f32_e32 v13, v12
	v_and_b32_e32 v12, 0xffff0000, v40
	v_mul_f32_e32 v14, 0xbfb8aa3b, v12
	v_mul_f32_e32 v0, 0xbfb8aa3b, v7
	v_exp_f32_e32 v15, v14
	v_exp_f32_e32 v0, v0
	v_add_f32_e32 v13, 1.0, v13
	v_rcp_f32_e32 v14, v13
	v_and_b32_e32 v13, 0xffff0000, v41
	v_add_f32_e32 v15, 1.0, v15
	v_add_f32_e32 v0, 1.0, v0
	v_rcp_f32_e32 v18, v15
	v_rcp_f32_e32 v15, v0
	v_mul_f32_e32 v0, 0xbfb8aa3b, v13
	v_exp_f32_e32 v0, v0
	v_mov_b32_e32 v27, v2
	v_pk_mul_f32 v[26:27], v[26:27], v[16:17] op_sel_hi:[1,0]
	v_mov_b32_e32 v28, v8
	v_add_f32_e32 v0, 1.0, v0
	v_rcp_f32_e32 v19, v0
	v_mov_b32_e32 v29, v10
	v_mov_b32_e32 v2, v1
	v_pk_mul_f32 v[26:27], v[26:27], v[28:29]
	v_pk_mul_f32 v[6:7], v[14:15], v[6:7]
	v_pk_mul_f32 v[0:1], v[2:3], v[16:17] op_sel_hi:[1,0]
	v_mov_b32_e32 v10, v9
	v_pk_mul_f32 v[6:7], v[26:27], v[6:7]
	v_pk_mul_f32 v[0:1], v[0:1], v[10:11]
	v_pk_mul_f32 v[2:3], v[18:19], v[12:13]
	s_nop 0
	v_pk_mul_f32 v[0:1], v[0:1], v[2:3]
	v_and_b32_sdwa v2, v7, v24 dst_sel:DWORD dst_unused:UNUSED_PAD src0_sel:WORD_1 src1_sel:DWORD
	v_and_b32_sdwa v3, v6, v24 dst_sel:DWORD dst_unused:UNUSED_PAD src0_sel:WORD_1 src1_sel:DWORD
	v_add3_u32 v3, v6, v3, s64
	v_add3_u32 v2, v7, v2, s64
	v_and_b32_sdwa v6, v1, v24 dst_sel:DWORD dst_unused:UNUSED_PAD src0_sel:WORD_1 src1_sel:DWORD
	v_and_b32_sdwa v7, v0, v24 dst_sel:DWORD dst_unused:UNUSED_PAD src0_sel:WORD_1 src1_sel:DWORD
	v_add3_u32 v1, v1, v6, s64
	v_add3_u32 v0, v0, v7, s64
	v_and_b32_e32 v1, 0xffff0000, v1
	v_and_b32_e32 v0, 0xffff0000, v0
	v_or_b32_sdwa v1, v1, v2 dst_sel:DWORD dst_unused:UNUSED_PAD src0_sel:DWORD src1_sel:WORD_1
	v_or_b32_sdwa v0, v0, v3 dst_sel:DWORD dst_unused:UNUSED_PAD src0_sel:DWORD src1_sel:WORD_1
	ds_write2_b64 v58, v[4:5], v[0:1] offset0:8 offset1:12
	v_lshlrev_b32_e32 v0, 4, v25
	v_and_b32_e32 v16, 0xf0, v0
	v_add_u32_e32 v4, 0, v16
	v_ashrrev_i32_e32 v6, 4, v25
	v_lshl_add_u64 v[8:9], s[4:5], 0, v[16:17]
	v_mad_u64_u32 v[0:1], s[4:5], v6, s70, v[4:5]
	v_ashrrev_i32_e32 v7, 31, v6
	s_waitcnt lgkmcnt(0)
	s_barrier
	ds_read_b128 v[0:3], v0
	v_lshl_add_u64 v[6:7], s[30:31], 0, v[6:7]
	v_mad_u64_u32 v[10:11], s[4:5], v6, s2, v[8:9]
	v_mov_b32_e32 v6, v11
	v_add_u32_e32 v5, 0x200, v25
	v_mad_u64_u32 v[6:7], s[4:5], v7, s2, v[6:7]
	v_ashrrev_i32_e32 v12, 4, v5
	v_mov_b32_e32 v11, v6
	v_mad_u64_u32 v[4:5], s[4:5], v12, s70, v[4:5]
	v_ashrrev_i32_e32 v13, 31, v12
	ds_read_b128 v[4:7], v4
	s_waitcnt lgkmcnt(1)
	global_store_dwordx4 v[10:11], v[0:3], off
	s_nop 1
	v_lshl_add_u64 v[0:1], s[30:31], 0, v[12:13]
	v_mad_u64_u32 v[2:3], s[4:5], v0, s2, v[8:9]
	v_mov_b32_e32 v0, v3
	v_mad_u64_u32 v[0:1], s[4:5], v1, s2, v[0:1]
	v_mov_b32_e32 v3, v0
	s_waitcnt lgkmcnt(0)
	global_store_dwordx4 v[2:3], v[4:7], off
	s_barrier
	s_cbranch_scc0 .LBB0_815

.LBB0_1115:
	ds_read2_b32 v[12:13], v17 offset1:65
	s_ashr_i32 s20, s2, 31
	s_lshr_b32 s20, s20, 28
	s_add_i32 s2, s2, s20
	s_ashr_i32 s2, s2, 4
	s_waitcnt lgkmcnt(0)
	v_bfe_u32 v14, v12, 16, 1
	v_add3_u32 v12, v12, v14, s17
	ds_read2_b32 v[14:15], v17 offset0:130 offset1:195
	v_bfe_u32 v34, v13, 16, 1
	v_lshrrev_b32_e32 v12, 16, v12
	v_add3_u32 v13, v13, v34, s17
	v_and_or_b32 v12, v13, s18, v12
	s_waitcnt lgkmcnt(0)
	v_bfe_u32 v13, v14, 16, 1
	v_add3_u32 v13, v14, v13, s17
	v_add_u32_e32 v14, 0x400, v17
	ds_read2_b32 v[34:35], v14 offset0:4 offset1:69
	v_bfe_u32 v36, v15, 16, 1
	v_lshrrev_b32_e32 v13, 16, v13
	v_add3_u32 v15, v15, v36, s17
	ds_read2_b32 v[36:37], v14 offset0:134 offset1:199
	v_and_or_b32 v13, v15, s18, v13
	s_waitcnt lgkmcnt(1)
	v_cvt_pk_bf16_f32 v14, v34, v35
	s_waitcnt lgkmcnt(0)
	v_cvt_pk_bf16_f32 v15, v36, v37
	v_lshl_add_u32 v34, s2, 6, v16
	s_lshl_b32 s20, s2, 10
	v_ashrrev_i32_e32 v35, 31, v34
	s_sub_i32 s20, s10, s20
	v_lshlrev_b64 v[34:35], 11, v[34:35]
	v_lshl_add_u64 v[34:35], s[8:9], 0, v[34:35]
	s_ashr_i32 s21, s20, 31
	v_lshl_add_u64 v[34:35], s[20:21], 1, v[34:35]
	v_lshl_add_u64 v[34:35], v[34:35], 0, v[8:9]
	s_add_i32 s10, s10, s11
	s_andn2_b64 vcc, exec, s[14:15]
	s_mov_b32 s2, s19
	global_store_dwordx4 v[34:35], v[12:15], off
	s_barrier
	s_cbranch_vccz .LBB0_1133

.LBB0_1322:
	ds_read2_b32 v[30:31], v5 offset1:65
	s_mul_hi_i32 s10, s10, 0x2e8ba2e9
	s_lshr_b32 s23, s10, 31
	s_ashr_i32 s10, s10, 3
	s_add_i32 s10, s10, s23
	s_waitcnt lgkmcnt(0)
	v_bfe_u32 v32, v30, 16, 1
	v_add3_u32 v30, v30, v32, s19
	ds_read2_b32 v[32:33], v5 offset0:130 offset1:195
	v_bfe_u32 v34, v31, 16, 1
	v_lshrrev_b32_e32 v30, 16, v30
	v_add3_u32 v31, v31, v34, s19
	v_and_or_b32 v30, v31, s20, v30
	s_waitcnt lgkmcnt(0)
	v_bfe_u32 v31, v32, 16, 1
	v_add3_u32 v31, v32, v31, s19
	v_add_u32_e32 v32, 0x400, v5
	ds_read2_b32 v[34:35], v32 offset0:4 offset1:69
	v_bfe_u32 v36, v33, 16, 1
	v_lshrrev_b32_e32 v31, 16, v31
	v_add3_u32 v33, v33, v36, s19
	ds_read2_b32 v[36:37], v32 offset0:134 offset1:199
	v_and_or_b32 v31, v33, s20, v31
	s_waitcnt lgkmcnt(1)
	v_cvt_pk_bf16_f32 v32, v34, v35
	s_waitcnt lgkmcnt(0)
	s_mul_i32 s23, s10, 0xfffff500
	s_add_i32 s24, s11, s23
	v_cvt_pk_bf16_f32 v33, v36, v37
	v_lshl_add_u32 v36, s10, 6, v4
	v_mov_b64_e32 v[34:35], s[14:15]
	v_mad_i64_i32 v[34:35], s[26:27], v36, s21, v[34:35]
	s_ashr_i32 s25, s24, 31
	v_lshl_add_u64 v[34:35], s[24:25], 1, v[34:35]
	v_lshl_add_u64 v[34:35], v[34:35], 0, v[0:1]
	s_add_i32 s11, s11, s18
	s_and_b64 vcc, exec, s[16:17]
	s_mov_b32 s10, s22
	global_store_dwordx4 v[34:35], v[30:33], off
	s_barrier
	s_cbranch_vccnz .LBB0_1325

.LBB0_1330:
	ds_read2_b32 v[30:31], v5 offset1:65
	s_mul_hi_i32 s2, s2, 0x2e8ba2e9
	s_lshr_b32 s15, s2, 31
	s_ashr_i32 s2, s2, 3
	s_add_i32 s2, s2, s15
	s_waitcnt lgkmcnt(0)
	v_bfe_u32 v32, v30, 16, 1
	v_add3_u32 v30, v30, v32, s11
	ds_read2_b32 v[32:33], v5 offset0:130 offset1:195
	v_bfe_u32 v34, v31, 16, 1
	v_lshrrev_b32_e32 v30, 16, v30
	v_add3_u32 v31, v31, v34, s11
	v_and_or_b32 v30, v31, s12, v30
	s_waitcnt lgkmcnt(0)
	v_bfe_u32 v31, v32, 16, 1
	v_add3_u32 v31, v32, v31, s11
	v_add_u32_e32 v32, 0x400, v5
	ds_read2_b32 v[34:35], v32 offset0:4 offset1:69
	v_bfe_u32 v36, v33, 16, 1
	v_lshrrev_b32_e32 v31, 16, v31
	v_add3_u32 v33, v33, v36, s11
	ds_read2_b32 v[36:37], v32 offset0:134 offset1:199
	v_and_or_b32 v31, v33, s12, v31
	s_waitcnt lgkmcnt(1)
	v_cvt_pk_bf16_f32 v32, v34, v35
	s_waitcnt lgkmcnt(0)
	s_mul_i32 s15, s2, 0xfffff500
	s_add_i32 s16, s3, s15
	v_cvt_pk_bf16_f32 v33, v36, v37
	v_lshl_add_u32 v36, s2, 6, v4
	v_mov_b64_e32 v[34:35], s[4:5]
	v_mad_i64_i32 v[34:35], s[18:19], v36, s13, v[34:35]
	s_ashr_i32 s17, s16, 31
	v_lshl_add_u64 v[34:35], s[16:17], 1, v[34:35]
	v_lshl_add_u64 v[34:35], v[34:35], 0, v[0:1]
	s_add_i32 s3, s3, s10
	s_and_b64 vcc, exec, s[8:9]
	s_mov_b32 s2, s14
	global_store_dwordx4 v[34:35], v[30:33], off
	s_barrier
	s_cbranch_vccnz .LBB0_1333
